# phase-3 gate-logit epilogue: nontemporal (nt) stores
# baseline (speedup 1.0000x reference)
.LBB0_242:
	s_add_u32 s23, s0, 0xfffc0080
	s_addc_u32 s24, s1, -1
	s_add_i32 s25, 0, 0x10000
	v_add_u32_e32 v2, s25, v187
	ds_read_b128 v[132:135], v2
	ds_read_b128 v[136:139], v2 offset:1024
	ds_read_b128 v[140:143], v2 offset:2048
	ds_read_b128 v[144:147], v2 offset:3072
	s_cmp_eq_u32 s22, 12
	s_cselect_b32 s47, s57, s24
	s_cselect_b32 s46, s56, s23
	s_cselect_b32 s45, s59, s21
	s_cselect_b32 s44, s58, s20
	v_lshl_add_u64 v[208:209], s[0:1], 0, v[194:195]
	s_add_i32 m0, s67, 0xc000
	ds_read_b128 v[148:151], v240
	ds_read_b128 v[152:155], v240 offset:1024
	ds_read_b128 v[156:159], v240 offset:2048
	ds_read_b128 v[160:163], v240 offset:3072
	ds_read_b128 v[164:167], v240 offset:4096
	ds_read_b128 v[168:171], v240 offset:5120
	ds_read_b128 v[172:175], v240 offset:6144
	ds_read_b128 v[204:207], v240 offset:7168
	global_load_lds_dwordx4 v[208:209], off
	v_lshl_add_u64 v[208:209], s[0:1], 0, v[202:203]
	s_add_i32 m0, s67, 0xe000
	s_nop 0
	global_load_lds_dwordx4 v[208:209], off
	s_waitcnt lgkmcnt(8)
	s_barrier
	s_waitcnt lgkmcnt(0)
	s_setprio 1
	s_waitcnt lgkmcnt(0)
	v_mfma_f32_16x16x32_bf16 v[128:131], v[132:135], v[148:151], v[128:131]
	v_mfma_f32_16x16x32_bf16 v[124:127], v[140:143], v[148:151], v[124:127]
	v_mfma_f32_16x16x32_bf16 v[120:123], v[132:135], v[156:159], v[120:123]
	v_mfma_f32_16x16x32_bf16 v[116:119], v[140:143], v[156:159], v[116:119]
	v_mfma_f32_16x16x32_bf16 v[112:115], v[132:135], v[164:167], v[112:115]
	v_mfma_f32_16x16x32_bf16 v[108:111], v[140:143], v[164:167], v[108:111]
	v_mfma_f32_16x16x32_bf16 v[104:107], v[132:135], v[172:175], v[104:107]
	v_mfma_f32_16x16x32_bf16 v[100:103], v[140:143], v[172:175], v[100:103]
	v_mfma_f32_16x16x32_bf16 v[128:131], v[136:139], v[152:155], v[128:131]
	v_mfma_f32_16x16x32_bf16 v[124:127], v[144:147], v[152:155], v[124:127]
	v_mfma_f32_16x16x32_bf16 v[120:123], v[136:139], v[160:163], v[120:123]
	v_mfma_f32_16x16x32_bf16 v[116:119], v[144:147], v[160:163], v[116:119]
	v_mfma_f32_16x16x32_bf16 v[112:115], v[136:139], v[168:171], v[112:115]
	v_mfma_f32_16x16x32_bf16 v[108:111], v[144:147], v[168:171], v[108:111]
	v_mfma_f32_16x16x32_bf16 v[104:107], v[136:139], v[204:207], v[104:107]
	v_mfma_f32_16x16x32_bf16 v[100:103], v[144:147], v[204:207], v[100:103]
	s_setprio 0
	s_barrier
	s_add_i32 s23, 0, 0x14000
	s_add_i32 s24, s25, s61
	v_add_u32_e32 v2, s23, v187
	v_lshl_add_u64 v[222:223], s[44:45], 0, v[176:177]
	s_mov_b32 m0, s24
	ds_read_b128 v[208:211], v2
	ds_read_b128 v[212:215], v2 offset:1024
	ds_read_b128 v[242:245], v2 offset:2048
	ds_read_b128 v[246:249], v2 offset:3072
	global_load_lds_dwordx4 v[222:223], off
	v_lshl_add_u64 v[250:251], s[44:45], 0, v[180:181]
	s_add_i32 m0, s24, 0x2000
	s_nop 0
	global_load_lds_dwordx4 v[250:251], off
	s_barrier
	s_waitcnt lgkmcnt(0)
	s_setprio 1
	s_waitcnt lgkmcnt(0)
	v_mfma_f32_16x16x32_bf16 v[64:67], v[208:211], v[148:151], v[64:67]
	v_mfma_f32_16x16x32_bf16 v[60:63], v[242:245], v[148:151], v[60:63]
	v_mfma_f32_16x16x32_bf16 v[56:59], v[208:211], v[156:159], v[56:59]
	v_mfma_f32_16x16x32_bf16 v[52:55], v[242:245], v[156:159], v[52:55]
	v_mfma_f32_16x16x32_bf16 v[48:51], v[208:211], v[164:167], v[48:51]
	v_mfma_f32_16x16x32_bf16 v[44:47], v[242:245], v[164:167], v[44:47]
	v_mfma_f32_16x16x32_bf16 v[40:43], v[208:211], v[172:175], v[40:43]
	v_mfma_f32_16x16x32_bf16 v[36:39], v[242:245], v[172:175], v[36:39]
	v_mfma_f32_16x16x32_bf16 v[64:67], v[212:215], v[152:155], v[64:67]
	v_mfma_f32_16x16x32_bf16 v[60:63], v[246:249], v[152:155], v[60:63]
	v_mfma_f32_16x16x32_bf16 v[56:59], v[212:215], v[160:163], v[56:59]
	v_mfma_f32_16x16x32_bf16 v[52:55], v[246:249], v[160:163], v[52:55]
	v_mfma_f32_16x16x32_bf16 v[48:51], v[212:215], v[168:171], v[48:51]
	v_mfma_f32_16x16x32_bf16 v[44:47], v[246:249], v[168:171], v[44:47]
	v_mfma_f32_16x16x32_bf16 v[40:43], v[212:215], v[204:207], v[40:43]
	v_mfma_f32_16x16x32_bf16 v[36:39], v[246:249], v[204:207], v[36:39]
	s_setprio 0
	s_mov_b32 m0, s67
	v_lshl_add_u64 v[216:217], s[46:47], 0, v[0:1]
	s_barrier
	ds_read_b128 v[148:151], v240 offset:16384
	ds_read_b128 v[152:155], v240 offset:17408
	ds_read_b128 v[156:159], v240 offset:18432
	ds_read_b128 v[160:163], v240 offset:19456
	ds_read_b128 v[164:167], v240 offset:20480
	ds_read_b128 v[168:171], v240 offset:21504
	ds_read_b128 v[172:175], v240 offset:22528
	ds_read_b128 v[204:207], v240 offset:23552
	global_load_lds_dwordx4 v[216:217], off
	v_lshl_add_u64 v[236:237], s[46:47], 0, v[178:179]
	s_mov_b32 m0, s74
	s_nop 0
	global_load_lds_dwordx4 v[236:237], off
	s_barrier
	s_waitcnt lgkmcnt(0)
	s_setprio 1
	s_waitcnt lgkmcnt(0)
	v_mfma_f32_16x16x32_bf16 v[96:99], v[132:135], v[148:151], v[96:99]
	v_mfma_f32_16x16x32_bf16 v[92:95], v[140:143], v[148:151], v[92:95]
	v_mfma_f32_16x16x32_bf16 v[88:91], v[132:135], v[156:159], v[88:91]
	v_mfma_f32_16x16x32_bf16 v[84:87], v[140:143], v[156:159], v[84:87]
	v_mfma_f32_16x16x32_bf16 v[80:83], v[132:135], v[164:167], v[80:83]
	v_mfma_f32_16x16x32_bf16 v[76:79], v[140:143], v[164:167], v[76:79]
	v_mfma_f32_16x16x32_bf16 v[72:75], v[132:135], v[172:175], v[72:75]
	v_mfma_f32_16x16x32_bf16 v[68:71], v[140:143], v[172:175], v[68:71]
	v_mfma_f32_16x16x32_bf16 v[96:99], v[136:139], v[152:155], v[96:99]
	v_mfma_f32_16x16x32_bf16 v[92:95], v[144:147], v[152:155], v[92:95]
	v_mfma_f32_16x16x32_bf16 v[88:91], v[136:139], v[160:163], v[88:91]
	v_mfma_f32_16x16x32_bf16 v[84:87], v[144:147], v[160:163], v[84:87]
	v_mfma_f32_16x16x32_bf16 v[80:83], v[136:139], v[168:171], v[80:83]
	v_mfma_f32_16x16x32_bf16 v[76:79], v[144:147], v[168:171], v[76:79]
	v_mfma_f32_16x16x32_bf16 v[72:75], v[136:139], v[204:207], v[72:75]
	v_mfma_f32_16x16x32_bf16 v[68:71], v[144:147], v[204:207], v[68:71]
	s_setprio 0
	s_barrier
	s_add_u32 s24, s44, 0x40000
	s_addc_u32 s25, s45, 0
	s_add_i32 s23, s23, s61
	v_lshl_add_u64 v[132:133], s[24:25], 0, v[176:177]
	s_mov_b32 m0, s23
	s_nop 0
	global_load_lds_dwordx4 v[132:133], off
	v_lshl_add_u64 v[132:133], s[24:25], 0, v[180:181]
	s_add_i32 m0, s23, 0x2000
	s_nop 0
	global_load_lds_dwordx4 v[132:133], off
	s_waitcnt vmcnt(6)
	s_barrier
	s_setprio 1
	v_mfma_f32_16x16x32_bf16 v[32:35], v[208:211], v[148:151], v[32:35]
	v_mfma_f32_16x16x32_bf16 v[28:31], v[242:245], v[148:151], v[28:31]
	v_mfma_f32_16x16x32_bf16 v[24:27], v[208:211], v[156:159], v[24:27]
	v_mfma_f32_16x16x32_bf16 v[20:23], v[242:245], v[156:159], v[20:23]
	v_mfma_f32_16x16x32_bf16 v[16:19], v[208:211], v[164:167], v[16:19]
	v_mfma_f32_16x16x32_bf16 v[12:15], v[242:245], v[164:167], v[12:15]
	v_mfma_f32_16x16x32_bf16 v[8:11], v[208:211], v[172:175], v[8:11]
	v_mfma_f32_16x16x32_bf16 v[4:7], v[242:245], v[172:175], v[4:7]
	v_mfma_f32_16x16x32_bf16 v[32:35], v[212:215], v[152:155], v[32:35]
	v_mfma_f32_16x16x32_bf16 v[28:31], v[246:249], v[152:155], v[28:31]
	v_mfma_f32_16x16x32_bf16 v[24:27], v[212:215], v[160:163], v[24:27]
	v_mfma_f32_16x16x32_bf16 v[20:23], v[246:249], v[160:163], v[20:23]
	v_mfma_f32_16x16x32_bf16 v[16:19], v[212:215], v[168:171], v[16:19]
	v_mfma_f32_16x16x32_bf16 v[12:15], v[246:249], v[168:171], v[12:15]
	v_mfma_f32_16x16x32_bf16 v[8:11], v[212:215], v[204:207], v[8:11]
	v_mfma_f32_16x16x32_bf16 v[4:7], v[246:249], v[204:207], v[4:7]
	s_setprio 0
	s_add_i32 s23, 0, 0x18000
	v_add_u32_e32 v2, s23, v187
	s_barrier
	ds_read_b128 v[132:135], v2
	ds_read_b128 v[136:139], v2 offset:1024
	ds_read_b128 v[140:143], v2 offset:2048
	ds_read_b128 v[144:147], v2 offset:3072
	s_add_u32 s24, s46, 0x40000
	s_addc_u32 s25, s47, 0
	s_mov_b32 m0, s75
	v_lshl_add_u64 v[208:209], s[24:25], 0, v[0:1]
	ds_read_b128 v[148:151], v240 offset:32768
	ds_read_b128 v[152:155], v240 offset:33792
	ds_read_b128 v[156:159], v240 offset:34816
	ds_read_b128 v[160:163], v240 offset:35840
	ds_read_b128 v[164:167], v240 offset:36864
	ds_read_b128 v[168:171], v240 offset:37888
	ds_read_b128 v[172:175], v240 offset:38912
	ds_read_b128 v[204:207], v240 offset:39936
	global_load_lds_dwordx4 v[208:209], off
	v_lshl_add_u64 v[208:209], s[24:25], 0, v[178:179]
	s_mov_b32 m0, s82
	s_nop 0
	global_load_lds_dwordx4 v[208:209], off
	s_waitcnt lgkmcnt(8)
	s_barrier
	s_waitcnt lgkmcnt(0)
	s_setprio 1
	s_waitcnt lgkmcnt(0)
	v_mfma_f32_16x16x32_bf16 v[128:131], v[132:135], v[148:151], v[128:131]
	v_mfma_f32_16x16x32_bf16 v[124:127], v[140:143], v[148:151], v[124:127]
	v_mfma_f32_16x16x32_bf16 v[120:123], v[132:135], v[156:159], v[120:123]
	v_mfma_f32_16x16x32_bf16 v[116:119], v[140:143], v[156:159], v[116:119]
	v_mfma_f32_16x16x32_bf16 v[112:115], v[132:135], v[164:167], v[112:115]
	v_mfma_f32_16x16x32_bf16 v[108:111], v[140:143], v[164:167], v[108:111]
	v_mfma_f32_16x16x32_bf16 v[104:107], v[132:135], v[172:175], v[104:107]
	v_mfma_f32_16x16x32_bf16 v[100:103], v[140:143], v[172:175], v[100:103]
	v_mfma_f32_16x16x32_bf16 v[128:131], v[136:139], v[152:155], v[128:131]
	v_mfma_f32_16x16x32_bf16 v[124:127], v[144:147], v[152:155], v[124:127]
	v_mfma_f32_16x16x32_bf16 v[120:123], v[136:139], v[160:163], v[120:123]
	v_mfma_f32_16x16x32_bf16 v[116:119], v[144:147], v[160:163], v[116:119]
	v_mfma_f32_16x16x32_bf16 v[112:115], v[136:139], v[168:171], v[112:115]
	v_mfma_f32_16x16x32_bf16 v[108:111], v[144:147], v[168:171], v[108:111]
	v_mfma_f32_16x16x32_bf16 v[104:107], v[136:139], v[204:207], v[104:107]
	v_mfma_f32_16x16x32_bf16 v[100:103], v[144:147], v[204:207], v[100:103]
	s_setprio 0
	s_barrier
	s_add_i32 s26, 0, 0x1c000
	s_add_i32 s23, s23, s61
	v_add_u32_e32 v2, s26, v187
	v_lshl_add_u64 v[222:223], v[222:223], 0, s[76:77]
	s_mov_b32 m0, s23
	ds_read_b128 v[208:211], v2
	ds_read_b128 v[212:215], v2 offset:1024
	ds_read_b128 v[242:245], v2 offset:2048
	ds_read_b128 v[246:249], v2 offset:3072
	global_load_lds_dwordx4 v[222:223], off
	v_lshl_add_u64 v[222:223], v[250:251], 0, s[76:77]
	s_add_i32 m0, s23, 0x2000
	s_nop 0
	global_load_lds_dwordx4 v[222:223], off
	s_barrier
	s_waitcnt lgkmcnt(0)
	s_setprio 1
	s_waitcnt lgkmcnt(0)
	v_mfma_f32_16x16x32_bf16 v[64:67], v[208:211], v[148:151], v[64:67]
	v_mfma_f32_16x16x32_bf16 v[60:63], v[242:245], v[148:151], v[60:63]
	v_mfma_f32_16x16x32_bf16 v[56:59], v[208:211], v[156:159], v[56:59]
	v_mfma_f32_16x16x32_bf16 v[52:55], v[242:245], v[156:159], v[52:55]
	v_mfma_f32_16x16x32_bf16 v[48:51], v[208:211], v[164:167], v[48:51]
	v_mfma_f32_16x16x32_bf16 v[44:47], v[242:245], v[164:167], v[44:47]
	v_mfma_f32_16x16x32_bf16 v[40:43], v[208:211], v[172:175], v[40:43]
	v_mfma_f32_16x16x32_bf16 v[36:39], v[242:245], v[172:175], v[36:39]
	v_mfma_f32_16x16x32_bf16 v[64:67], v[212:215], v[152:155], v[64:67]
	v_mfma_f32_16x16x32_bf16 v[60:63], v[246:249], v[152:155], v[60:63]
	v_mfma_f32_16x16x32_bf16 v[56:59], v[212:215], v[160:163], v[56:59]
	v_mfma_f32_16x16x32_bf16 v[52:55], v[246:249], v[160:163], v[52:55]
	v_mfma_f32_16x16x32_bf16 v[48:51], v[212:215], v[168:171], v[48:51]
	v_mfma_f32_16x16x32_bf16 v[44:47], v[246:249], v[168:171], v[44:47]
	v_mfma_f32_16x16x32_bf16 v[40:43], v[212:215], v[204:207], v[40:43]
	v_mfma_f32_16x16x32_bf16 v[36:39], v[246:249], v[204:207], v[36:39]
	s_setprio 0
	s_mov_b32 m0, s48
	v_lshl_add_u64 v[216:217], v[216:217], 0, s[76:77]
	s_barrier
	ds_read_b128 v[148:151], v240 offset:49152
	ds_read_b128 v[152:155], v240 offset:50176
	ds_read_b128 v[156:159], v240 offset:51200
	ds_read_b128 v[160:163], v240 offset:52224
	ds_read_b128 v[164:167], v240 offset:53248
	ds_read_b128 v[168:171], v240 offset:54272
	ds_read_b128 v[172:175], v240 offset:55296
	ds_read_b128 v[204:207], v240 offset:56320
	global_load_lds_dwordx4 v[216:217], off
	v_lshl_add_u64 v[216:217], v[236:237], 0, s[76:77]
	s_mov_b32 m0, s50
	s_nop 0
	global_load_lds_dwordx4 v[216:217], off
	s_barrier
	s_waitcnt lgkmcnt(0)
	s_setprio 1
	s_waitcnt lgkmcnt(0)
	v_mfma_f32_16x16x32_bf16 v[96:99], v[132:135], v[148:151], v[96:99]
	v_mfma_f32_16x16x32_bf16 v[92:95], v[140:143], v[148:151], v[92:95]
	v_mfma_f32_16x16x32_bf16 v[88:91], v[132:135], v[156:159], v[88:91]
	v_mfma_f32_16x16x32_bf16 v[84:87], v[140:143], v[156:159], v[84:87]
	v_mfma_f32_16x16x32_bf16 v[80:83], v[132:135], v[164:167], v[80:83]
	v_mfma_f32_16x16x32_bf16 v[76:79], v[140:143], v[164:167], v[76:79]
	v_mfma_f32_16x16x32_bf16 v[72:75], v[132:135], v[172:175], v[72:75]
	v_mfma_f32_16x16x32_bf16 v[68:71], v[140:143], v[172:175], v[68:71]
	v_mfma_f32_16x16x32_bf16 v[96:99], v[136:139], v[152:155], v[96:99]
	v_mfma_f32_16x16x32_bf16 v[92:95], v[144:147], v[152:155], v[92:95]
	v_mfma_f32_16x16x32_bf16 v[88:91], v[136:139], v[160:163], v[88:91]
	v_mfma_f32_16x16x32_bf16 v[84:87], v[144:147], v[160:163], v[84:87]
	v_mfma_f32_16x16x32_bf16 v[80:83], v[136:139], v[168:171], v[80:83]
	v_mfma_f32_16x16x32_bf16 v[76:79], v[144:147], v[168:171], v[76:79]
	v_mfma_f32_16x16x32_bf16 v[72:75], v[136:139], v[204:207], v[72:75]
	v_mfma_f32_16x16x32_bf16 v[68:71], v[144:147], v[204:207], v[68:71]
	s_setprio 0
	s_barrier
	s_add_u32 s24, s44, 0x40080
	s_addc_u32 s25, s45, 0
	s_add_i32 s23, s26, s61
	v_lshl_add_u64 v[132:133], s[24:25], 0, v[176:177]
	s_mov_b32 m0, s23
	s_nop 0
	global_load_lds_dwordx4 v[132:133], off
	v_lshl_add_u64 v[132:133], s[24:25], 0, v[180:181]
	s_add_i32 m0, s23, 0x2000
	s_nop 0
	global_load_lds_dwordx4 v[132:133], off
	s_waitcnt vmcnt(6)
	s_barrier
	s_setprio 1
	v_mfma_f32_16x16x32_bf16 v[32:35], v[208:211], v[148:151], v[32:35]
	v_mfma_f32_16x16x32_bf16 v[28:31], v[242:245], v[148:151], v[28:31]
	v_mfma_f32_16x16x32_bf16 v[24:27], v[208:211], v[156:159], v[24:27]
	v_mfma_f32_16x16x32_bf16 v[20:23], v[242:245], v[156:159], v[20:23]
	v_mfma_f32_16x16x32_bf16 v[16:19], v[208:211], v[164:167], v[16:19]
	v_mfma_f32_16x16x32_bf16 v[12:15], v[242:245], v[164:167], v[12:15]
	v_mfma_f32_16x16x32_bf16 v[8:11], v[208:211], v[172:175], v[8:11]
	v_mfma_f32_16x16x32_bf16 v[4:7], v[242:245], v[172:175], v[4:7]
	v_mfma_f32_16x16x32_bf16 v[32:35], v[212:215], v[152:155], v[32:35]
	v_mfma_f32_16x16x32_bf16 v[28:31], v[246:249], v[152:155], v[28:31]
	v_mfma_f32_16x16x32_bf16 v[24:27], v[212:215], v[160:163], v[24:27]
	v_mfma_f32_16x16x32_bf16 v[20:23], v[246:249], v[160:163], v[20:23]
	v_mfma_f32_16x16x32_bf16 v[16:19], v[212:215], v[168:171], v[16:19]
	v_mfma_f32_16x16x32_bf16 v[12:15], v[246:249], v[168:171], v[12:15]
	v_mfma_f32_16x16x32_bf16 v[8:11], v[212:215], v[204:207], v[8:11]
	v_mfma_f32_16x16x32_bf16 v[4:7], v[246:249], v[204:207], v[4:7]
	s_setprio 0
	s_add_i32 s22, s22, 2
	s_add_u32 s0, s0, 0x100
	s_addc_u32 s1, s1, 0
	s_add_u32 s20, s20, 0x100
	s_addc_u32 s21, s21, 0
	s_cmp_gt_u32 s22, 13
	s_barrier
	s_cbranch_scc0 .LBB0_242
	s_add_i32 s0, s66, -8
	s_cmp_lt_u32 s0, 12
	s_mov_b64 s[0:1], -1
	s_cbranch_scc1 .LBB0_266
	s_cmp_gt_i32 s66, 33
	s_cselect_b64 s[64:65], -1, 0
	s_lshl_b32 s0, s66, 8
	s_lshl_b32 s53, s60, 8
	s_add_i32 s1, s0, 0xffffee00
	s_cmp_lt_i32 s66, 26
	v_cndmask_b32_e64 v2, 0, 1, s[80:81]
	s_cselect_b32 s62, s0, s1
	s_mov_b64 s[0:1], -1
	s_and_b64 vcc, exec, s[64:65]
	v_cmp_ne_u32_e64 s[44:45], 1, v2
	s_cbranch_vccz .LBB0_248
	s_and_b64 vcc, exec, s[44:45]
	s_cbranch_vccnz .LBB0_247
	v_add_u32_e32 v132, s53, v185
	v_ashrrev_i32_e32 v133, 31, v132
	v_lshlrev_b64 v[140:141], 7, v[132:133]
	global_load_dwordx4 v[132:135], v[188:189], off offset:16
	global_load_dwordx4 v[136:139], v[188:189], off
	s_mov_b32 s3, 0xbfb8aa3b
	s_mov_b32 s2, 0x800000
	s_mov_b32 s5, 0x3f317217
	s_mov_b32 s6, 0x7f800000
	s_waitcnt vmcnt(0)
	v_add_f32_e32 v147, v126, v134
	v_add_f32_e32 v2, v128, v136
	v_max_f32_e32 v142, 0, v2
	v_mul_f32_e64 v2, |v2|, s3
	v_exp_f32_e32 v2, v2
	v_add_f32_e32 v136, v124, v132
	v_add_f32_e32 v149, v127, v135
	v_add_f32_e32 v2, 1.0, v2
	v_cmp_gt_f32_e32 vcc, s2, v2
	s_nop 1
	v_cndmask_b32_e64 v132, 0, 32, vcc
	v_ldexp_f32 v2, v2, v132
	v_log_f32_e32 v2, v2
	s_nop 0
	v_mul_f32_e32 v132, 0x3f317217, v2
	v_fma_f32 v132, v2, s5, -v132
	v_fmac_f32_e32 v132, 0x3377d1cf, v2
	v_fmac_f32_e32 v132, 0x3f317217, v2
	v_cmp_lt_f32_e64 s[0:1], |v2|, s6
	s_nop 1
	v_cndmask_b32_e64 v2, v2, v132, s[0:1]
	v_cndmask_b32_e32 v132, 0, v228, vcc
	v_sub_f32_e32 v144, v2, v132
	v_mul_f32_e64 v2, |v136|, s3
	v_exp_f32_e32 v2, v2
	v_max_f32_e32 v132, 0, v136
	v_add_f32_e32 v2, 1.0, v2
	v_cmp_gt_f32_e32 vcc, s2, v2
	s_nop 1
	v_cndmask_b32_e64 v136, 0, 32, vcc
	v_ldexp_f32 v2, v2, v136
	v_log_f32_e32 v2, v2
	s_nop 0
	v_mul_f32_e32 v136, 0x3f317217, v2
	v_fma_f32 v136, v2, s5, -v136
	v_fmac_f32_e32 v136, 0x3377d1cf, v2
	v_fmac_f32_e32 v136, 0x3f317217, v2
	v_cmp_lt_f32_e64 s[0:1], |v2|, s6
	s_nop 1
	v_cndmask_b32_e64 v2, v2, v136, s[0:1]
	v_cndmask_b32_e32 v136, 0, v228, vcc
	v_sub_f32_e32 v136, v2, v136
	v_add_f32_e32 v2, v129, v137
	v_max_f32_e32 v143, 0, v2
	v_mul_f32_e64 v2, |v2|, s3
	v_exp_f32_e32 v2, v2
	v_add_f32_e32 v137, v125, v133
	v_add_f32_e32 v2, 1.0, v2
	v_cmp_gt_f32_e32 vcc, s2, v2
	s_nop 1
	v_cndmask_b32_e64 v133, 0, 32, vcc
	v_ldexp_f32 v2, v2, v133
	v_log_f32_e32 v2, v2
	s_nop 0
	v_mul_f32_e32 v133, 0x3f317217, v2
	v_fma_f32 v133, v2, s5, -v133
	v_fmac_f32_e32 v133, 0x3377d1cf, v2
	v_fmac_f32_e32 v133, 0x3f317217, v2
	v_cmp_lt_f32_e64 s[0:1], |v2|, s6
	s_nop 1
	v_cndmask_b32_e64 v2, v2, v133, s[0:1]
	v_cndmask_b32_e32 v133, 0, v228, vcc
	v_sub_f32_e32 v145, v2, v133
	v_mul_f32_e64 v2, |v137|, s3
	v_exp_f32_e32 v2, v2
	v_max_f32_e32 v133, 0, v137
	v_pk_add_f32 v[142:143], v[142:143], v[144:145]
	v_add_f32_e32 v2, 1.0, v2
	v_cmp_gt_f32_e32 vcc, s2, v2
	s_nop 1
	v_cndmask_b32_e64 v137, 0, 32, vcc
	v_ldexp_f32 v2, v2, v137
	v_log_f32_e32 v2, v2
	s_nop 0
	v_mul_f32_e32 v137, 0x3f317217, v2
	v_fma_f32 v137, v2, s5, -v137
	v_fmac_f32_e32 v137, 0x3377d1cf, v2
	v_fmac_f32_e32 v137, 0x3f317217, v2
	v_cmp_lt_f32_e64 s[0:1], |v2|, s6
	s_nop 1
	v_cndmask_b32_e64 v2, v2, v137, s[0:1]
	v_cndmask_b32_e32 v137, 0, v228, vcc
	v_sub_f32_e32 v137, v2, v137
	v_add_f32_e32 v2, v130, v138
	v_max_f32_e32 v138, 0, v2
	v_mul_f32_e64 v2, |v2|, s3
	v_exp_f32_e32 v2, v2
	v_pk_add_f32 v[132:133], v[132:133], v[136:137]
	v_lshl_add_u64 v[136:137], v[190:191], 0, v[140:141]
	v_add_f32_e32 v2, 1.0, v2
	v_cmp_gt_f32_e32 vcc, s2, v2
	s_nop 1
	v_cndmask_b32_e64 v134, 0, 32, vcc
	v_ldexp_f32 v2, v2, v134
	v_log_f32_e32 v2, v2
	s_nop 0
	v_mul_f32_e32 v134, 0x3f317217, v2
	v_fma_f32 v134, v2, s5, -v134
	v_fmac_f32_e32 v134, 0x3377d1cf, v2
	v_fmac_f32_e32 v134, 0x3f317217, v2
	v_cmp_lt_f32_e64 s[0:1], |v2|, s6
	s_nop 1
	v_cndmask_b32_e64 v2, v2, v134, s[0:1]
	v_cndmask_b32_e32 v134, 0, v228, vcc
	v_sub_f32_e32 v146, v2, v134
	v_mul_f32_e64 v2, |v147|, s3
	v_exp_f32_e32 v2, v2
	v_max_f32_e32 v134, 0, v147
	v_add_f32_e32 v2, 1.0, v2
	v_cmp_gt_f32_e32 vcc, s2, v2
	s_nop 1
	v_cndmask_b32_e64 v147, 0, 32, vcc
	v_ldexp_f32 v2, v2, v147
	v_log_f32_e32 v2, v2
	s_nop 0
	v_mul_f32_e32 v147, 0x3f317217, v2
	v_fma_f32 v147, v2, s5, -v147
	v_fmac_f32_e32 v147, 0x3377d1cf, v2
	v_fmac_f32_e32 v147, 0x3f317217, v2
	v_cmp_lt_f32_e64 s[0:1], |v2|, s6
	s_nop 1
	v_cndmask_b32_e64 v2, v2, v147, s[0:1]
	v_cndmask_b32_e32 v147, 0, v228, vcc
	v_sub_f32_e32 v148, v2, v147
	v_add_f32_e32 v2, v131, v139
	v_max_f32_e32 v139, 0, v2
	v_mul_f32_e64 v2, |v2|, s3
	v_exp_f32_e32 v2, v2
	s_nop 0
	v_add_f32_e32 v2, 1.0, v2
	v_cmp_gt_f32_e32 vcc, s2, v2
	s_nop 1
	v_cndmask_b32_e64 v135, 0, 32, vcc
	v_ldexp_f32 v2, v2, v135
	v_log_f32_e32 v2, v2
	s_nop 0
	v_mul_f32_e32 v135, 0x3f317217, v2
	v_fma_f32 v135, v2, s5, -v135
	v_fmac_f32_e32 v135, 0x3377d1cf, v2
	v_fmac_f32_e32 v135, 0x3f317217, v2
	v_cmp_lt_f32_e64 s[0:1], |v2|, s6
	s_nop 1
	v_cndmask_b32_e64 v2, v2, v135, s[0:1]
	v_cndmask_b32_e32 v135, 0, v228, vcc
	v_sub_f32_e32 v147, v2, v135
	v_mul_f32_e64 v2, |v149|, s3
	v_exp_f32_e32 v2, v2
	v_pk_add_f32 v[144:145], v[138:139], v[146:147]
	v_max_f32_e32 v135, 0, v149
	v_add_f32_e32 v2, 1.0, v2
	v_cmp_gt_f32_e32 vcc, s2, v2
	s_nop 1
	v_cndmask_b32_e64 v138, 0, 32, vcc
	v_ldexp_f32 v2, v2, v138
	v_log_f32_e32 v2, v2
	s_nop 0
	v_mul_f32_e32 v138, 0x3f317217, v2
	v_fma_f32 v138, v2, s5, -v138
	v_fmac_f32_e32 v138, 0x3377d1cf, v2
	v_fmac_f32_e32 v138, 0x3f317217, v2
	v_cmp_lt_f32_e64 s[0:1], |v2|, s6
	s_nop 1
	v_cndmask_b32_e64 v2, v2, v138, s[0:1]
	v_cndmask_b32_e32 v138, 0, v228, vcc
	v_sub_f32_e32 v149, v2, v138
	v_pk_add_f32 v[134:135], v[134:135], v[148:149]
	global_store_dwordx4 v[136:137], v[142:145], off nt
	global_store_dwordx4 v[136:137], v[132:135], off offset:16 nt

.LBB0_248:
	s_ashr_i32 s63, s62, 31
	s_andn2_b64 vcc, exec, s[0:1]
	v_lshlrev_b32_e32 v2, 1, v182
	s_cbranch_vccnz .LBB0_250
	v_add_u32_e32 v134, s53, v185
	v_mov_b64_e32 v[132:133], s[96:97]
	v_mad_i64_i32 v[132:133], s[0:1], v134, s29, v[132:133]
	v_lshl_add_u64 v[132:133], s[62:63], 1, v[132:133]
	s_lshl_b32 s72, s49, 1
	v_lshl_add_u64 v[132:133], v[132:133], 0, s[72:73]
	v_lshl_add_u64 v[136:137], v[132:133], 0, v[2:3]
	v_cvt_pk_bf16_f32 v132, v128, v129
	v_cvt_pk_bf16_f32 v133, v130, v131
	v_cvt_pk_bf16_f32 v134, v124, v125
	v_cvt_pk_bf16_f32 v135, v126, v127
	global_store_dwordx4 v[136:137], v[132:135], off nt
	s_nop 1
	v_cvt_pk_bf16_f32 v132, v64, v65
	v_cvt_pk_bf16_f32 v133, v66, v67
	v_cvt_pk_bf16_f32 v134, v60, v61
	v_cvt_pk_bf16_f32 v135, v62, v63
	global_store_dwordx4 v[136:137], v[132:135], off offset:256 nt

.LBB0_264:
	v_add_u32_e32 v134, s53, v239
	v_mov_b64_e32 v[132:133], s[96:97]
	v_mad_i64_i32 v[132:133], s[0:1], v134, s29, v[132:133]
	v_lshl_add_u64 v[132:133], s[62:63], 1, v[132:133]
	s_lshl_b32 s72, s49, 1
	v_lshl_add_u64 v[132:133], v[132:133], 0, s[72:73]
	v_lshl_add_u64 v[136:137], v[132:133], 0, v[2:3]
	v_cvt_pk_bf16_f32 v132, v72, v73
	v_cvt_pk_bf16_f32 v133, v74, v75
	v_cvt_pk_bf16_f32 v134, v68, v69
	v_cvt_pk_bf16_f32 v135, v70, v71
	global_store_dwordx4 v[136:137], v[132:135], off nt
	s_nop 1
	v_cvt_pk_bf16_f32 v132, v8, v9
	v_cvt_pk_bf16_f32 v133, v10, v11
	v_cvt_pk_bf16_f32 v134, v4, v5
	v_cvt_pk_bf16_f32 v135, v6, v7
	global_store_dwordx4 v[136:137], v[132:135], off offset:256 nt

.LBB0_266:
	s_and_b64 vcc, exec, s[0:1]
	s_cbranch_vccz .LBB0_234
	v_lshl_add_u32 v204, s66, 8, v201
	v_mov_b32_e32 v205, v3
	v_readlane_b32 s12, v254, 42
	v_lshlrev_b64 v[132:133], 2, v[204:205]
	v_readlane_b32 s20, v254, 50
	v_readlane_b32 s21, v254, 51
	v_readlane_b32 s22, v254, 52
	v_readlane_b32 s23, v254, 53
	v_lshl_add_u64 v[206:207], s[20:21], 0, v[132:133]
	v_add_co_u32_e32 v138, vcc, s7, v206
	s_mov_b64 s[0:1], 0x9000
	s_nop 0
	v_addc_co_u32_e32 v139, vcc, 0, v207, vcc
	v_add_co_u32_e32 v214, vcc, s4, v206
	v_lshl_add_u64 v[208:209], s[22:23], 0, v[132:133]
	s_nop 0
	v_addc_co_u32_e32 v215, vcc, 0, v207, vcc
	v_add_co_u32_e32 v154, vcc, s8, v206
	v_lshl_add_u64 v[136:137], v[206:207], 0, s[10:11]
	v_lshl_add_u64 v[140:141], v[206:207], 0, s[36:37]
	v_lshl_add_u64 v[152:153], v[206:207], 0, s[0:1]
	v_addc_co_u32_e32 v155, vcc, 0, v207, vcc
	global_load_dwordx4 v[144:147], v[208:209], off offset:16
	global_load_dwordx4 v[164:167], v[208:209], off
	global_load_dwordx4 v[132:135], v[206:207], off offset:16
	global_load_dwordx4 v[148:151], v[206:207], off
	global_load_dwordx4 v[156:159], v[138:139], off
	s_nop 0
	global_load_dwordx4 v[136:139], v[136:137], off offset:16
	s_nop 0
	global_load_dwordx4 v[160:163], v[214:215], off
	s_nop 0
	global_load_dwordx4 v[140:143], v[140:141], off offset:16
	s_nop 0
	global_load_dwordx4 v[168:171], v[154:155], off
	s_nop 0
	global_load_dwordx4 v[152:155], v[152:153], off offset:16
	v_mov_b32_dpp v172, v128 row_ror:1 row_mask:0xf bank_mask:0xf
	v_mov_b32_dpp v173, v129 row_ror:1 row_mask:0xf bank_mask:0xf
	v_mov_b32_dpp v174, v128 row_ror:2 row_mask:0xf bank_mask:0xf
	v_mov_b32_dpp v172, v128 row_shr:1 row_mask:0xf bank_mask:0xf
	v_mov_b32_dpp v173, v129 row_shr:1 row_mask:0xf bank_mask:0xf
	v_mov_b32_dpp v175, v129 row_ror:2 row_mask:0xf bank_mask:0xf
	v_mov_b32_dpp v174, v128 row_shr:2 row_mask:0xf bank_mask:0xf
	v_mov_b32_dpp v210, v128 row_ror:3 row_mask:0xf bank_mask:0xf
	v_mov_b32_dpp v175, v129 row_shr:2 row_mask:0xf bank_mask:0xf
	v_mov_b32_dpp v211, v129 row_ror:3 row_mask:0xf bank_mask:0xf
	v_mov_b32_dpp v210, v128 row_shr:3 row_mask:0xf bank_mask:0xf
	s_lshl_b32 s46, s60, 8
	v_mov_b32_dpp v211, v129 row_shr:3 row_mask:0xf bank_mask:0xf
	s_add_i32 s46, s46, s31
	v_or_b32_e32 v2, s46, v183
	v_readlane_b32 s13, v254, 43
	v_readlane_b32 s14, v254, 44
	v_readlane_b32 s15, v254, 45
	v_readlane_b32 s16, v254, 46
	v_readlane_b32 s17, v254, 47
	v_readlane_b32 s18, v254, 48
	v_readlane_b32 s19, v254, 49
	v_readlane_b32 s24, v254, 54
	v_readlane_b32 s25, v254, 55
	v_readlane_b32 s26, v254, 56
	v_readlane_b32 s27, v254, 57
	s_waitcnt vmcnt(0)
	v_pk_fma_f32 v[222:223], v[128:129], v[168:169], v[164:165]
	s_nop 0
	v_pk_fma_f32 v[172:173], v[160:161], v[172:173], v[222:223]
	v_pk_fma_f32 v[212:213], v[130:131], v[170:171], v[166:167]
	v_pk_fma_f32 v[172:173], v[156:157], v[174:175], v[172:173]
	v_mov_b32_dpp v222, v130 row_ror:3 row_mask:0xf bank_mask:0xf
	v_pk_fma_f32 v[172:173], v[148:149], v[210:211], v[172:173]
	v_mov_b32_dpp v210, v130 row_ror:2 row_mask:0xf bank_mask:0xf
	v_mul_f32_e32 v174, 0xbfb8aa3b, v172
	v_mul_f32_e32 v175, 0xbfb8aa3b, v173
	v_exp_f32_e32 v174, v174
	v_exp_f32_e32 v175, v175
	v_mov_b32_dpp v211, v131 row_ror:2 row_mask:0xf bank_mask:0xf
	v_mov_b32_dpp v210, v130 row_shr:2 row_mask:0xf bank_mask:0xf
	v_add_f32_e32 v174, 1.0, v174
	v_add_f32_e32 v175, 1.0, v175
	v_rcp_f32_e32 v174, v174
	v_rcp_f32_e32 v175, v175
	v_mov_b32_dpp v211, v131 row_shr:2 row_mask:0xf bank_mask:0xf
	v_mov_b32_dpp v223, v131 row_ror:3 row_mask:0xf bank_mask:0xf
	v_mov_b32_dpp v222, v130 row_shr:3 row_mask:0xf bank_mask:0xf
	v_pk_mul_f32 v[172:173], v[172:173], v[174:175]
	v_mov_b32_dpp v174, v130 row_ror:1 row_mask:0xf bank_mask:0xf
	v_mov_b32_dpp v175, v131 row_ror:1 row_mask:0xf bank_mask:0xf
	v_mov_b32_dpp v223, v131 row_shr:3 row_mask:0xf bank_mask:0xf
	v_mov_b32_dpp v174, v130 row_shr:1 row_mask:0xf bank_mask:0xf
	v_mov_b32_dpp v175, v131 row_shr:1 row_mask:0xf bank_mask:0xf
	v_pk_fma_f32 v[174:175], v[162:163], v[174:175], v[212:213]
	v_mov_b32_dpp v212, v124 row_ror:2 row_mask:0xf bank_mask:0xf
	v_pk_fma_f32 v[174:175], v[158:159], v[210:211], v[174:175]
	v_mov_b32_dpp v213, v125 row_ror:2 row_mask:0xf bank_mask:0xf
	v_pk_fma_f32 v[174:175], v[150:151], v[222:223], v[174:175]
	v_pk_fma_f32 v[244:245], v[124:125], v[152:153], v[144:145]
	v_mul_f32_e32 v198, 0xbfb8aa3b, v174
	v_exp_f32_e32 v198, v198
	v_mov_b32_dpp v212, v124 row_shr:2 row_mask:0xf bank_mask:0xf
	v_mov_b32_dpp v222, v124 row_ror:3 row_mask:0xf bank_mask:0xf
	v_mov_b32_dpp v213, v125 row_shr:2 row_mask:0xf bank_mask:0xf
	v_add_f32_e32 v198, 1.0, v198
	v_rcp_f32_e32 v210, v198
	v_mul_f32_e32 v198, 0xbfb8aa3b, v175
	v_exp_f32_e32 v198, v198
	v_mov_b32_dpp v223, v125 row_ror:3 row_mask:0xf bank_mask:0xf
	v_mov_b32_dpp v222, v124 row_shr:3 row_mask:0xf bank_mask:0xf
	v_pk_fma_f32 v[242:243], v[126:127], v[154:155], v[146:147]
	v_add_f32_e32 v198, 1.0, v198
	v_rcp_f32_e32 v211, v198
	v_mov_b32_dpp v223, v125 row_shr:3 row_mask:0xf bank_mask:0xf
	v_cvt_pk_bf16_f32 v172, v172, v173
	v_pk_mul_f32 v[174:175], v[174:175], v[210:211]
	v_mov_b32_dpp v210, v124 row_ror:1 row_mask:0xf bank_mask:0xf
	v_mov_b32_dpp v211, v125 row_ror:1 row_mask:0xf bank_mask:0xf
	v_cvt_pk_bf16_f32 v173, v174, v175
	v_mov_b32_dpp v210, v124 row_shr:1 row_mask:0xf bank_mask:0xf
	v_mov_b32_dpp v211, v125 row_shr:1 row_mask:0xf bank_mask:0xf
	v_pk_fma_f32 v[210:211], v[140:141], v[210:211], v[244:245]
	v_mov_b32_dpp v244, v126 row_ror:3 row_mask:0xf bank_mask:0xf
	v_pk_fma_f32 v[210:211], v[136:137], v[212:213], v[210:211]
	v_mov_b32_dpp v245, v127 row_ror:3 row_mask:0xf bank_mask:0xf
	v_pk_fma_f32 v[210:211], v[132:133], v[222:223], v[210:211]
	v_mov_b32_dpp v222, v126 row_ror:2 row_mask:0xf bank_mask:0xf
	v_mul_f32_e32 v198, 0xbfb8aa3b, v210
	v_exp_f32_e32 v198, v198
	v_mov_b32_dpp v223, v127 row_ror:2 row_mask:0xf bank_mask:0xf
	v_mov_b32_dpp v222, v126 row_shr:2 row_mask:0xf bank_mask:0xf
	v_mov_b32_dpp v244, v126 row_shr:3 row_mask:0xf bank_mask:0xf
	v_add_f32_e32 v198, 1.0, v198
	v_rcp_f32_e32 v212, v198
	v_mul_f32_e32 v198, 0xbfb8aa3b, v211
	v_exp_f32_e32 v198, v198
	v_mov_b32_dpp v223, v127 row_shr:2 row_mask:0xf bank_mask:0xf
	v_mov_b32_dpp v245, v127 row_shr:3 row_mask:0xf bank_mask:0xf
	v_add_f32_e32 v198, 1.0, v198
	v_rcp_f32_e32 v213, v198
	s_nop 0
	v_pk_mul_f32 v[210:211], v[210:211], v[212:213]
	v_mov_b32_dpp v212, v126 row_ror:1 row_mask:0xf bank_mask:0xf
	v_mov_b32_dpp v213, v127 row_ror:1 row_mask:0xf bank_mask:0xf
	v_cvt_pk_bf16_f32 v174, v210, v211
	v_mov_b32_dpp v212, v126 row_shr:1 row_mask:0xf bank_mask:0xf
	v_mov_b32_dpp v213, v127 row_shr:1 row_mask:0xf bank_mask:0xf
	v_pk_fma_f32 v[212:213], v[142:143], v[212:213], v[242:243]
	v_mov_b64_e32 v[210:211], s[92:93]
	v_pk_fma_f32 v[212:213], v[138:139], v[222:223], v[212:213]
	v_mad_i64_i32 v[210:211], s[0:1], v2, s29, v[210:211]
	v_pk_fma_f32 v[212:213], v[134:135], v[244:245], v[212:213]
	s_mov_b64 s[0:1], 0x4001000
	v_mul_f32_e32 v198, 0xbfb8aa3b, v212
	v_exp_f32_e32 v198, v198
	s_nop 0
	v_add_f32_e32 v198, 1.0, v198
	v_rcp_f32_e32 v222, v198
	v_mul_f32_e32 v198, 0xbfb8aa3b, v213
	v_exp_f32_e32 v198, v198
	s_nop 0
	v_add_f32_e32 v198, 1.0, v198
	v_rcp_f32_e32 v223, v198
	s_nop 0
	v_pk_mul_f32 v[212:213], v[212:213], v[222:223]
	s_nop 0
	v_cvt_pk_bf16_f32 v175, v212, v213
	v_lshl_add_u64 v[212:213], v[210:211], 0, s[0:1]
	v_lshl_add_u64 v[210:211], v[204:205], 1, v[212:213]
	global_store_dwordx4 v[210:211], v[172:175], off nt
	s_nop 1
	v_cvt_pk_bf16_f32 v172, v128, v129
	v_cvt_pk_bf16_f32 v173, v130, v131
	v_cvt_pk_bf16_f32 v174, v124, v125
	v_cvt_pk_bf16_f32 v175, v126, v127
	s_and_saveexec_b64 s[0:1], s[38:39]
	s_cbranch_execz .LBB0_269
	v_readlane_b32 s2, v252, 54
	s_ashr_i32 s20, s46, 6
	v_readlane_b32 s3, v252, 55
	v_mad_u64_u32 v[210:211], s[20:21], s20, 6, v[186:187]
	s_nop 0
	v_mov_b64_e32 v[222:223], s[2:3]
	v_mad_i64_i32 v[210:211], s[20:21], v210, s68, v[222:223]
	v_lshl_add_u64 v[210:211], v[204:205], 1, v[210:211]
	global_store_dwordx4 v[210:211], v[172:175], off nt
.LBB0_269:
	s_or_b64 exec, exec, s[0:1]
	s_cmpk_eq_i32 s60, 0x80
	v_readlane_b32 s2, v255, 3
	s_cselect_b64 s[0:1], -1, 0
	v_readlane_b32 s3, v255, 4
	s_and_b64 s[0:1], s[2:3], s[0:1]
	s_and_b64 s[0:1], s[0:1], s[40:41]
	v_lshl_add_u64 v[210:211], v[204:205], 1, v[192:193]
	s_and_saveexec_b64 s[44:45], s[0:1]
	s_cbranch_execz .LBB0_271
	global_store_dwordx4 v[210:211], v[172:175], off nt
.LBB0_271:
	s_or_b64 exec, exec, s[44:45]
	s_nop 0
	v_mov_b32_dpp v172, v128 row_ror:1 row_mask:0xf bank_mask:0xf
	v_mov_b32_dpp v173, v129 row_ror:1 row_mask:0xf bank_mask:0xf
	v_mov_b32_dpp v174, v128 row_ror:2 row_mask:0xf bank_mask:0xf
	v_mov_b32_dpp v172, v120 row_shr:1 row_mask:0xf bank_mask:0xf
	v_mov_b32_dpp v173, v121 row_shr:1 row_mask:0xf bank_mask:0xf
	v_mov_b32_dpp v175, v129 row_ror:2 row_mask:0xf bank_mask:0xf
	v_pk_fma_f32 v[242:243], v[120:121], v[168:169], v[164:165]
	v_mov_b32_dpp v174, v120 row_shr:2 row_mask:0xf bank_mask:0xf
	v_mov_b32_dpp v128, v128 row_ror:3 row_mask:0xf bank_mask:0xf
	v_mov_b32_dpp v175, v121 row_shr:2 row_mask:0xf bank_mask:0xf
	v_mov_b32_dpp v129, v129 row_ror:3 row_mask:0xf bank_mask:0xf
	v_pk_fma_f32 v[172:173], v[160:161], v[172:173], v[242:243]
	v_mov_b32_dpp v128, v120 row_shr:3 row_mask:0xf bank_mask:0xf
	v_mov_b32_dpp v129, v121 row_shr:3 row_mask:0xf bank_mask:0xf
	v_pk_fma_f32 v[172:173], v[156:157], v[174:175], v[172:173]
	v_pk_fma_f32 v[222:223], v[122:123], v[170:171], v[166:167]
	v_pk_fma_f32 v[128:129], v[148:149], v[128:129], v[172:173]
	v_mov_b32_dpp v174, v130 row_ror:2 row_mask:0xf bank_mask:0xf
	v_mul_f32_e32 v172, 0xbfb8aa3b, v128
	v_mul_f32_e32 v173, 0xbfb8aa3b, v129
	v_exp_f32_e32 v172, v172
	v_exp_f32_e32 v173, v173
	v_mov_b32_dpp v175, v131 row_ror:2 row_mask:0xf bank_mask:0xf
	v_mov_b32_dpp v174, v122 row_shr:2 row_mask:0xf bank_mask:0xf
	v_add_f32_e32 v172, 1.0, v172
	v_add_f32_e32 v173, 1.0, v173
	v_rcp_f32_e32 v172, v172
	v_rcp_f32_e32 v173, v173
	v_mov_b32_dpp v175, v123 row_shr:2 row_mask:0xf bank_mask:0xf
	v_pk_fma_f32 v[242:243], v[116:117], v[152:153], v[144:145]
	v_or_b32_e32 v198, 16, v2
	v_pk_mul_f32 v[128:129], v[128:129], v[172:173]
	v_mov_b32_dpp v172, v130 row_ror:1 row_mask:0xf bank_mask:0xf
	v_mov_b32_dpp v173, v131 row_ror:1 row_mask:0xf bank_mask:0xf
	v_mov_b32_dpp v130, v130 row_ror:3 row_mask:0xf bank_mask:0xf
	v_mov_b32_dpp v172, v122 row_shr:1 row_mask:0xf bank_mask:0xf
	v_mov_b32_dpp v173, v123 row_shr:1 row_mask:0xf bank_mask:0xf
	v_mov_b32_dpp v131, v131 row_ror:3 row_mask:0xf bank_mask:0xf
	v_pk_fma_f32 v[172:173], v[162:163], v[172:173], v[222:223]
	v_mov_b32_dpp v130, v122 row_shr:3 row_mask:0xf bank_mask:0xf
	v_mov_b32_dpp v131, v123 row_shr:3 row_mask:0xf bank_mask:0xf
	v_pk_fma_f32 v[172:173], v[158:159], v[174:175], v[172:173]
	v_mov_b32_dpp v174, v124 row_ror:2 row_mask:0xf bank_mask:0xf
	v_pk_fma_f32 v[130:131], v[150:151], v[130:131], v[172:173]
	v_mov_b32_dpp v175, v125 row_ror:2 row_mask:0xf bank_mask:0xf
	v_mul_f32_e32 v172, 0xbfb8aa3b, v130
	v_mul_f32_e32 v173, 0xbfb8aa3b, v131
	v_exp_f32_e32 v172, v172
	v_exp_f32_e32 v173, v173
	v_mov_b32_dpp v174, v116 row_shr:2 row_mask:0xf bank_mask:0xf
	v_mov_b32_dpp v175, v117 row_shr:2 row_mask:0xf bank_mask:0xf
	v_add_f32_e32 v172, 1.0, v172
	v_add_f32_e32 v173, 1.0, v173
	v_rcp_f32_e32 v172, v172
	v_rcp_f32_e32 v173, v173
	v_pk_fma_f32 v[222:223], v[118:119], v[154:155], v[146:147]
	s_mov_b64 s[2:3], 0x4001000
	s_mov_b64 s[14:15], 0x4001000
	v_pk_mul_f32 v[130:131], v[130:131], v[172:173]
	v_mov_b32_dpp v172, v124 row_ror:1 row_mask:0xf bank_mask:0xf
	v_mov_b32_dpp v173, v125 row_ror:1 row_mask:0xf bank_mask:0xf
	v_mov_b32_dpp v124, v124 row_ror:3 row_mask:0xf bank_mask:0xf
	v_mov_b32_dpp v172, v116 row_shr:1 row_mask:0xf bank_mask:0xf
	v_mov_b32_dpp v173, v117 row_shr:1 row_mask:0xf bank_mask:0xf
	v_mov_b32_dpp v125, v125 row_ror:3 row_mask:0xf bank_mask:0xf
	v_pk_fma_f32 v[172:173], v[140:141], v[172:173], v[242:243]
	v_mov_b32_dpp v124, v116 row_shr:3 row_mask:0xf bank_mask:0xf
	v_mov_b32_dpp v125, v117 row_shr:3 row_mask:0xf bank_mask:0xf
	v_pk_fma_f32 v[172:173], v[136:137], v[174:175], v[172:173]
	v_mov_b32_dpp v174, v126 row_ror:2 row_mask:0xf bank_mask:0xf
	v_pk_fma_f32 v[124:125], v[132:133], v[124:125], v[172:173]
	v_mov_b32_dpp v175, v127 row_ror:2 row_mask:0xf bank_mask:0xf
	v_mul_f32_e32 v172, 0xbfb8aa3b, v124
	v_mul_f32_e32 v173, 0xbfb8aa3b, v125
	v_exp_f32_e32 v172, v172
	v_exp_f32_e32 v173, v173
	v_mov_b32_dpp v174, v118 row_shr:2 row_mask:0xf bank_mask:0xf
	v_mov_b32_dpp v175, v119 row_shr:2 row_mask:0xf bank_mask:0xf
	v_add_f32_e32 v172, 1.0, v172
	v_add_f32_e32 v173, 1.0, v173
	v_rcp_f32_e32 v172, v172
	v_rcp_f32_e32 v173, v173
	s_nop 0
	v_pk_mul_f32 v[124:125], v[124:125], v[172:173]
	v_mov_b32_dpp v172, v126 row_ror:1 row_mask:0xf bank_mask:0xf
	v_mov_b32_dpp v173, v127 row_ror:1 row_mask:0xf bank_mask:0xf
	v_mov_b32_dpp v126, v126 row_ror:3 row_mask:0xf bank_mask:0xf
	v_mov_b32_dpp v172, v118 row_shr:1 row_mask:0xf bank_mask:0xf
	v_mov_b32_dpp v173, v119 row_shr:1 row_mask:0xf bank_mask:0xf
	v_mov_b32_dpp v127, v127 row_ror:3 row_mask:0xf bank_mask:0xf
	v_pk_fma_f32 v[172:173], v[142:143], v[172:173], v[222:223]
	v_mov_b32_dpp v126, v118 row_shr:3 row_mask:0xf bank_mask:0xf
	v_mov_b32_dpp v127, v119 row_shr:3 row_mask:0xf bank_mask:0xf
	v_pk_fma_f32 v[172:173], v[138:139], v[174:175], v[172:173]
	v_cvt_pk_bf16_f32 v174, v124, v125
	v_pk_fma_f32 v[126:127], v[134:135], v[126:127], v[172:173]
	v_pk_fma_f32 v[222:223], v[112:113], v[168:169], v[164:165]
	v_mul_f32_e32 v172, 0xbfb8aa3b, v126
	v_mul_f32_e32 v173, 0xbfb8aa3b, v127
	v_exp_f32_e32 v172, v172
	v_exp_f32_e32 v173, v173
	v_add_f32_e32 v172, 1.0, v172
	v_add_f32_e32 v173, 1.0, v173
	v_rcp_f32_e32 v172, v172
	v_rcp_f32_e32 v173, v173
	s_nop 0
	v_pk_mul_f32 v[126:127], v[126:127], v[172:173]
	v_cvt_pk_bf16_f32 v172, v128, v129
	v_mov_b64_e32 v[128:129], s[92:93]
	v_mad_i64_i32 v[124:125], s[20:21], v198, s29, v[128:129]
	v_cvt_pk_bf16_f32 v175, v126, v127
	v_lshl_add_u64 v[124:125], v[124:125], 0, s[2:3]
	v_lshlrev_b64 v[126:127], 1, v[204:205]
	v_cvt_pk_bf16_f32 v173, v130, v131
	v_lshl_add_u64 v[130:131], v[124:125], 0, v[126:127]
	global_store_dwordx4 v[130:131], v[172:175], off nt
	s_nop 0
	v_mov_b32_dpp v130, v120 row_ror:1 row_mask:0xf bank_mask:0xf
	v_mov_b32_dpp v131, v121 row_ror:1 row_mask:0xf bank_mask:0xf
	v_mov_b32_dpp v172, v120 row_ror:2 row_mask:0xf bank_mask:0xf
	v_mov_b32_dpp v130, v112 row_shr:1 row_mask:0xf bank_mask:0xf
	v_mov_b32_dpp v131, v113 row_shr:1 row_mask:0xf bank_mask:0xf
	v_mov_b32_dpp v173, v121 row_ror:2 row_mask:0xf bank_mask:0xf
	v_mov_b32_dpp v172, v112 row_shr:2 row_mask:0xf bank_mask:0xf
	v_mov_b32_dpp v120, v120 row_ror:3 row_mask:0xf bank_mask:0xf
	v_mov_b32_dpp v173, v113 row_shr:2 row_mask:0xf bank_mask:0xf
	v_mov_b32_dpp v121, v121 row_ror:3 row_mask:0xf bank_mask:0xf
	v_pk_fma_f32 v[130:131], v[160:161], v[130:131], v[222:223]
	v_mov_b32_dpp v120, v112 row_shr:3 row_mask:0xf bank_mask:0xf
	v_mov_b32_dpp v121, v113 row_shr:3 row_mask:0xf bank_mask:0xf
	v_pk_fma_f32 v[130:131], v[156:157], v[172:173], v[130:131]
	v_pk_fma_f32 v[174:175], v[114:115], v[170:171], v[166:167]
	v_pk_fma_f32 v[120:121], v[148:149], v[120:121], v[130:131]
	v_mov_b32_dpp v172, v122 row_ror:2 row_mask:0xf bank_mask:0xf
	v_mul_f32_e32 v130, 0xbfb8aa3b, v120
	v_mul_f32_e32 v131, 0xbfb8aa3b, v121
	v_exp_f32_e32 v130, v130
	v_exp_f32_e32 v131, v131
	v_mov_b32_dpp v173, v123 row_ror:2 row_mask:0xf bank_mask:0xf
	v_mov_b32_dpp v172, v114 row_shr:2 row_mask:0xf bank_mask:0xf
	v_add_f32_e32 v130, 1.0, v130
	v_add_f32_e32 v131, 1.0, v131
	v_rcp_f32_e32 v130, v130
	v_rcp_f32_e32 v131, v131
	v_mov_b32_dpp v173, v115 row_shr:2 row_mask:0xf bank_mask:0xf
	v_pk_fma_f32 v[222:223], v[108:109], v[152:153], v[144:145]
	v_pk_mul_f32 v[120:121], v[120:121], v[130:131]
	v_mov_b32_dpp v130, v122 row_ror:1 row_mask:0xf bank_mask:0xf
	v_mov_b32_dpp v131, v123 row_ror:1 row_mask:0xf bank_mask:0xf
	v_mov_b32_dpp v122, v122 row_ror:3 row_mask:0xf bank_mask:0xf
	v_mov_b32_dpp v130, v114 row_shr:1 row_mask:0xf bank_mask:0xf
	v_mov_b32_dpp v131, v115 row_shr:1 row_mask:0xf bank_mask:0xf
	v_mov_b32_dpp v123, v123 row_ror:3 row_mask:0xf bank_mask:0xf
	v_pk_fma_f32 v[130:131], v[162:163], v[130:131], v[174:175]
	v_mov_b32_dpp v122, v114 row_shr:3 row_mask:0xf bank_mask:0xf
	v_mov_b32_dpp v123, v115 row_shr:3 row_mask:0xf bank_mask:0xf
	v_pk_fma_f32 v[130:131], v[158:159], v[172:173], v[130:131]
	v_mov_b32_dpp v172, v116 row_ror:2 row_mask:0xf bank_mask:0xf
	v_pk_fma_f32 v[122:123], v[150:151], v[122:123], v[130:131]
	v_mov_b32_dpp v173, v117 row_ror:2 row_mask:0xf bank_mask:0xf
	v_mul_f32_e32 v130, 0xbfb8aa3b, v122
	v_mul_f32_e32 v131, 0xbfb8aa3b, v123
	v_exp_f32_e32 v130, v130
	v_exp_f32_e32 v131, v131
	v_mov_b32_dpp v172, v108 row_shr:2 row_mask:0xf bank_mask:0xf
	v_mov_b32_dpp v173, v109 row_shr:2 row_mask:0xf bank_mask:0xf
	v_add_f32_e32 v130, 1.0, v130
	v_add_f32_e32 v131, 1.0, v131
	v_rcp_f32_e32 v130, v130
	v_rcp_f32_e32 v131, v131
	v_pk_fma_f32 v[174:175], v[110:111], v[154:155], v[146:147]
	v_pk_mul_f32 v[122:123], v[122:123], v[130:131]
	v_mov_b32_dpp v130, v116 row_ror:1 row_mask:0xf bank_mask:0xf
	v_mov_b32_dpp v131, v117 row_ror:1 row_mask:0xf bank_mask:0xf
	v_mov_b32_dpp v116, v116 row_ror:3 row_mask:0xf bank_mask:0xf
	v_mov_b32_dpp v130, v108 row_shr:1 row_mask:0xf bank_mask:0xf
	v_mov_b32_dpp v131, v109 row_shr:1 row_mask:0xf bank_mask:0xf
	v_mov_b32_dpp v117, v117 row_ror:3 row_mask:0xf bank_mask:0xf
	v_pk_fma_f32 v[130:131], v[140:141], v[130:131], v[222:223]
	v_mov_b32_dpp v116, v108 row_shr:3 row_mask:0xf bank_mask:0xf
	v_mov_b32_dpp v117, v109 row_shr:3 row_mask:0xf bank_mask:0xf
	v_pk_fma_f32 v[130:131], v[136:137], v[172:173], v[130:131]
	v_mov_b32_dpp v172, v118 row_ror:2 row_mask:0xf bank_mask:0xf
	v_pk_fma_f32 v[116:117], v[132:133], v[116:117], v[130:131]
	v_mov_b32_dpp v173, v119 row_ror:2 row_mask:0xf bank_mask:0xf
	v_mul_f32_e32 v130, 0xbfb8aa3b, v116
	v_mul_f32_e32 v131, 0xbfb8aa3b, v117
	v_exp_f32_e32 v130, v130
	v_exp_f32_e32 v131, v131
	v_mov_b32_dpp v172, v110 row_shr:2 row_mask:0xf bank_mask:0xf
	v_mov_b32_dpp v173, v111 row_shr:2 row_mask:0xf bank_mask:0xf
	v_add_f32_e32 v130, 1.0, v130
	v_add_f32_e32 v131, 1.0, v131
	v_rcp_f32_e32 v130, v130
	v_rcp_f32_e32 v131, v131
	s_nop 0
	v_pk_mul_f32 v[116:117], v[116:117], v[130:131]
	v_mov_b32_dpp v130, v118 row_ror:1 row_mask:0xf bank_mask:0xf
	v_mov_b32_dpp v131, v119 row_ror:1 row_mask:0xf bank_mask:0xf
	v_mov_b32_dpp v118, v118 row_ror:3 row_mask:0xf bank_mask:0xf
	v_mov_b32_dpp v130, v110 row_shr:1 row_mask:0xf bank_mask:0xf
	v_mov_b32_dpp v131, v111 row_shr:1 row_mask:0xf bank_mask:0xf
	v_mov_b32_dpp v119, v119 row_ror:3 row_mask:0xf bank_mask:0xf
	v_pk_fma_f32 v[130:131], v[142:143], v[130:131], v[174:175]
	v_mov_b32_dpp v118, v110 row_shr:3 row_mask:0xf bank_mask:0xf
	v_mov_b32_dpp v119, v111 row_shr:3 row_mask:0xf bank_mask:0xf
	v_pk_fma_f32 v[130:131], v[138:139], v[172:173], v[130:131]
	v_or_b32_e32 v172, 32, v2
	v_pk_fma_f32 v[118:119], v[134:135], v[118:119], v[130:131]
	s_nop 0
	v_mul_f32_e32 v130, 0xbfb8aa3b, v118
	v_mul_f32_e32 v131, 0xbfb8aa3b, v119
	v_exp_f32_e32 v130, v130
	v_exp_f32_e32 v131, v131
	v_add_f32_e32 v130, 1.0, v130
	v_add_f32_e32 v131, 1.0, v131
	v_rcp_f32_e32 v130, v130
	v_rcp_f32_e32 v131, v131
	s_nop 0
	v_pk_mul_f32 v[130:131], v[118:119], v[130:131]
	v_cvt_pk_bf16_f32 v118, v120, v121
	v_cvt_pk_bf16_f32 v120, v116, v117
	v_mad_i64_i32 v[116:117], s[20:21], v172, s29, v[128:129]
	v_lshl_add_u64 v[116:117], v[116:117], 0, s[2:3]
	v_cvt_pk_bf16_f32 v119, v122, v123
	v_cvt_pk_bf16_f32 v121, v130, v131
	v_lshl_add_u64 v[122:123], v[116:117], 0, v[126:127]
	global_store_dwordx4 v[122:123], v[118:121], off nt
	v_pk_fma_f32 v[130:131], v[104:105], v[168:169], v[164:165]
	v_pk_fma_f32 v[122:123], v[106:107], v[170:171], v[166:167]
	v_mov_b32_dpp v118, v112 row_ror:1 row_mask:0xf bank_mask:0xf
	v_mov_b32_dpp v119, v113 row_ror:1 row_mask:0xf bank_mask:0xf
	v_mov_b32_dpp v120, v112 row_ror:2 row_mask:0xf bank_mask:0xf
	v_mov_b32_dpp v118, v104 row_shr:1 row_mask:0xf bank_mask:0xf
	v_mov_b32_dpp v119, v105 row_shr:1 row_mask:0xf bank_mask:0xf
	v_mov_b32_dpp v121, v113 row_ror:2 row_mask:0xf bank_mask:0xf
	v_mov_b32_dpp v120, v104 row_shr:2 row_mask:0xf bank_mask:0xf
	v_mov_b32_dpp v112, v112 row_ror:3 row_mask:0xf bank_mask:0xf
	v_mov_b32_dpp v121, v105 row_shr:2 row_mask:0xf bank_mask:0xf
	v_mov_b32_dpp v113, v113 row_ror:3 row_mask:0xf bank_mask:0xf
	v_pk_fma_f32 v[118:119], v[160:161], v[118:119], v[130:131]
	v_mov_b32_dpp v112, v104 row_shr:3 row_mask:0xf bank_mask:0xf
	v_mov_b32_dpp v113, v105 row_shr:3 row_mask:0xf bank_mask:0xf
	v_pk_fma_f32 v[118:119], v[156:157], v[120:121], v[118:119]
	v_mov_b32_dpp v120, v114 row_ror:2 row_mask:0xf bank_mask:0xf
	v_pk_fma_f32 v[112:113], v[148:149], v[112:113], v[118:119]
	v_mov_b32_dpp v121, v115 row_ror:2 row_mask:0xf bank_mask:0xf
	v_mul_f32_e32 v118, 0xbfb8aa3b, v112
	v_mul_f32_e32 v119, 0xbfb8aa3b, v113
	v_exp_f32_e32 v118, v118
	v_exp_f32_e32 v119, v119
	v_mov_b32_dpp v120, v106 row_shr:2 row_mask:0xf bank_mask:0xf
	v_mov_b32_dpp v121, v107 row_shr:2 row_mask:0xf bank_mask:0xf
	v_add_f32_e32 v118, 1.0, v118
	v_add_f32_e32 v119, 1.0, v119
	v_rcp_f32_e32 v118, v118
	v_rcp_f32_e32 v119, v119
	v_pk_fma_f32 v[130:131], v[100:101], v[152:153], v[144:145]
	v_pk_mul_f32 v[112:113], v[112:113], v[118:119]
	v_mov_b32_dpp v118, v114 row_ror:1 row_mask:0xf bank_mask:0xf
	v_mov_b32_dpp v119, v115 row_ror:1 row_mask:0xf bank_mask:0xf
	v_mov_b32_dpp v114, v114 row_ror:3 row_mask:0xf bank_mask:0xf
	v_mov_b32_dpp v118, v106 row_shr:1 row_mask:0xf bank_mask:0xf
	v_mov_b32_dpp v119, v107 row_shr:1 row_mask:0xf bank_mask:0xf
	v_mov_b32_dpp v115, v115 row_ror:3 row_mask:0xf bank_mask:0xf
	v_pk_fma_f32 v[118:119], v[162:163], v[118:119], v[122:123]
	v_mov_b32_dpp v114, v106 row_shr:3 row_mask:0xf bank_mask:0xf
	v_mov_b32_dpp v115, v107 row_shr:3 row_mask:0xf bank_mask:0xf
	v_pk_fma_f32 v[118:119], v[158:159], v[120:121], v[118:119]
	v_mov_b32_dpp v120, v108 row_ror:2 row_mask:0xf bank_mask:0xf
	v_pk_fma_f32 v[114:115], v[150:151], v[114:115], v[118:119]
	v_mov_b32_dpp v121, v109 row_ror:2 row_mask:0xf bank_mask:0xf
	v_mul_f32_e32 v118, 0xbfb8aa3b, v114
	v_mul_f32_e32 v119, 0xbfb8aa3b, v115
	v_exp_f32_e32 v118, v118
	v_exp_f32_e32 v119, v119
	v_mov_b32_dpp v120, v100 row_shr:2 row_mask:0xf bank_mask:0xf
	v_mov_b32_dpp v121, v101 row_shr:2 row_mask:0xf bank_mask:0xf
	v_add_f32_e32 v118, 1.0, v118
	v_add_f32_e32 v119, 1.0, v119
	v_rcp_f32_e32 v118, v118
	v_rcp_f32_e32 v119, v119
	v_pk_fma_f32 v[122:123], v[102:103], v[154:155], v[146:147]
	v_pk_mul_f32 v[114:115], v[114:115], v[118:119]
	v_mov_b32_dpp v118, v108 row_ror:1 row_mask:0xf bank_mask:0xf
	v_mov_b32_dpp v119, v109 row_ror:1 row_mask:0xf bank_mask:0xf
	v_mov_b32_dpp v108, v108 row_ror:3 row_mask:0xf bank_mask:0xf
	v_mov_b32_dpp v118, v100 row_shr:1 row_mask:0xf bank_mask:0xf
	v_mov_b32_dpp v119, v101 row_shr:1 row_mask:0xf bank_mask:0xf
	v_mov_b32_dpp v109, v109 row_ror:3 row_mask:0xf bank_mask:0xf
	v_pk_fma_f32 v[118:119], v[140:141], v[118:119], v[130:131]
	v_mov_b32_dpp v108, v100 row_shr:3 row_mask:0xf bank_mask:0xf
	v_mov_b32_dpp v109, v101 row_shr:3 row_mask:0xf bank_mask:0xf
	v_pk_fma_f32 v[118:119], v[136:137], v[120:121], v[118:119]
	v_mov_b32_dpp v120, v110 row_ror:2 row_mask:0xf bank_mask:0xf
	v_pk_fma_f32 v[108:109], v[132:133], v[108:109], v[118:119]
	v_mov_b32_dpp v121, v111 row_ror:2 row_mask:0xf bank_mask:0xf
	v_mul_f32_e32 v118, 0xbfb8aa3b, v108
	v_mul_f32_e32 v119, 0xbfb8aa3b, v109
	v_exp_f32_e32 v118, v118
	v_exp_f32_e32 v119, v119
	v_mov_b32_dpp v120, v102 row_shr:2 row_mask:0xf bank_mask:0xf
	v_mov_b32_dpp v121, v103 row_shr:2 row_mask:0xf bank_mask:0xf
	v_add_f32_e32 v118, 1.0, v118
	v_add_f32_e32 v119, 1.0, v119
	v_rcp_f32_e32 v118, v118
	v_rcp_f32_e32 v119, v119
	s_nop 0
	v_pk_mul_f32 v[118:119], v[108:109], v[118:119]
	v_mov_b32_dpp v108, v110 row_ror:1 row_mask:0xf bank_mask:0xf
	v_mov_b32_dpp v109, v111 row_ror:1 row_mask:0xf bank_mask:0xf
	v_mov_b32_dpp v110, v110 row_ror:3 row_mask:0xf bank_mask:0xf
	v_mov_b32_dpp v108, v102 row_shr:1 row_mask:0xf bank_mask:0xf
	v_mov_b32_dpp v109, v103 row_shr:1 row_mask:0xf bank_mask:0xf
	v_mov_b32_dpp v111, v111 row_ror:3 row_mask:0xf bank_mask:0xf
	v_pk_fma_f32 v[108:109], v[142:143], v[108:109], v[122:123]
	v_mov_b32_dpp v110, v102 row_shr:3 row_mask:0xf bank_mask:0xf
	v_mov_b32_dpp v111, v103 row_shr:3 row_mask:0xf bank_mask:0xf
	v_pk_fma_f32 v[108:109], v[138:139], v[120:121], v[108:109]
	v_or_b32_e32 v122, 48, v2
	v_pk_fma_f32 v[108:109], v[134:135], v[110:111], v[108:109]
	s_nop 0
	v_mul_f32_e32 v110, 0xbfb8aa3b, v108
	v_mul_f32_e32 v111, 0xbfb8aa3b, v109
	v_exp_f32_e32 v110, v110
	v_exp_f32_e32 v111, v111
	v_add_f32_e32 v110, 1.0, v110
	v_add_f32_e32 v111, 1.0, v111
	v_rcp_f32_e32 v110, v110
	v_rcp_f32_e32 v111, v111
	s_nop 0
	v_pk_mul_f32 v[120:121], v[108:109], v[110:111]
	v_cvt_pk_bf16_f32 v108, v112, v113
	v_mad_i64_i32 v[112:113], s[20:21], v122, s29, v[128:129]
	v_lshl_add_u64 v[112:113], v[112:113], 0, s[2:3]
	v_cvt_pk_bf16_f32 v109, v114, v115
	v_cvt_pk_bf16_f32 v110, v118, v119
	v_cvt_pk_bf16_f32 v111, v120, v121
	v_lshl_add_u64 v[114:115], v[112:113], 0, v[126:127]
	global_store_dwordx4 v[114:115], v[108:111], off nt
	s_and_saveexec_b64 s[44:45], s[40:41]
	s_cbranch_execz .LBB0_273
	v_readlane_b32 s2, v252, 54
	s_ashr_i32 s20, s46, 6
	v_readlane_b32 s3, v252, 55
	v_cvt_pk_bf16_f32 v104, v104, v105
	v_cvt_pk_bf16_f32 v105, v106, v107
	v_cvt_pk_bf16_f32 v106, v100, v101
	v_cvt_pk_bf16_f32 v107, v102, v103
	v_mad_u64_u32 v[100:101], s[20:21], s20, 6, v[184:185]
	v_mov_b64_e32 v[102:103], s[2:3]
	v_mad_i64_i32 v[100:101], s[20:21], v100, s68, v[102:103]
	v_lshl_add_u64 v[100:101], v[204:205], 1, v[100:101]
	global_store_dwordx4 v[100:101], v[104:107], off nt
.LBB0_273:
	s_or_b64 exec, exec, s[44:45]
	v_mov_b32_dpp v100, v96 row_ror:1 row_mask:0xf bank_mask:0xf
	v_mov_b32_dpp v101, v97 row_ror:1 row_mask:0xf bank_mask:0xf
	v_mov_b32_dpp v102, v96 row_ror:2 row_mask:0xf bank_mask:0xf
	v_mov_b32_dpp v100, v96 row_shr:1 row_mask:0xf bank_mask:0xf
	v_mov_b32_dpp v101, v97 row_shr:1 row_mask:0xf bank_mask:0xf
	v_mov_b32_dpp v103, v97 row_ror:2 row_mask:0xf bank_mask:0xf
	v_pk_fma_f32 v[108:109], v[96:97], v[168:169], v[164:165]
	v_mov_b32_dpp v102, v96 row_shr:2 row_mask:0xf bank_mask:0xf
	v_mov_b32_dpp v104, v96 row_ror:3 row_mask:0xf bank_mask:0xf
	v_mov_b32_dpp v103, v97 row_shr:2 row_mask:0xf bank_mask:0xf
	v_mov_b32_dpp v105, v97 row_ror:3 row_mask:0xf bank_mask:0xf
	v_pk_fma_f32 v[100:101], v[160:161], v[100:101], v[108:109]
	v_mov_b32_dpp v104, v96 row_shr:3 row_mask:0xf bank_mask:0xf
	v_mov_b32_dpp v105, v97 row_shr:3 row_mask:0xf bank_mask:0xf
	v_pk_fma_f32 v[100:101], v[156:157], v[102:103], v[100:101]
	v_pk_fma_f32 v[106:107], v[98:99], v[170:171], v[166:167]
	v_pk_fma_f32 v[100:101], v[148:149], v[104:105], v[100:101]
	v_mov_b32_dpp v104, v98 row_ror:2 row_mask:0xf bank_mask:0xf
	v_mul_f32_e32 v102, 0xbfb8aa3b, v100
	v_mul_f32_e32 v103, 0xbfb8aa3b, v101
	v_exp_f32_e32 v102, v102
	v_exp_f32_e32 v103, v103
	v_mov_b32_dpp v105, v99 row_ror:2 row_mask:0xf bank_mask:0xf
	v_mov_b32_dpp v104, v98 row_shr:2 row_mask:0xf bank_mask:0xf
	v_add_f32_e32 v102, 1.0, v102
	v_add_f32_e32 v103, 1.0, v103
	v_rcp_f32_e32 v102, v102
	v_rcp_f32_e32 v103, v103
	v_mov_b32_dpp v108, v98 row_ror:3 row_mask:0xf bank_mask:0xf
	v_mov_b32_dpp v105, v99 row_shr:2 row_mask:0xf bank_mask:0xf
	v_mov_b32_dpp v109, v99 row_ror:3 row_mask:0xf bank_mask:0xf
	v_pk_mul_f32 v[100:101], v[100:101], v[102:103]
	v_mov_b32_dpp v102, v98 row_ror:1 row_mask:0xf bank_mask:0xf
	v_mov_b32_dpp v103, v99 row_ror:1 row_mask:0xf bank_mask:0xf
	v_mov_b32_dpp v108, v98 row_shr:3 row_mask:0xf bank_mask:0xf
	v_mov_b32_dpp v102, v98 row_shr:1 row_mask:0xf bank_mask:0xf
	v_mov_b32_dpp v103, v99 row_shr:1 row_mask:0xf bank_mask:0xf
	v_pk_fma_f32 v[102:103], v[162:163], v[102:103], v[106:107]
	v_mov_b32_dpp v109, v99 row_shr:3 row_mask:0xf bank_mask:0xf
	v_pk_fma_f32 v[102:103], v[158:159], v[104:105], v[102:103]
	v_mov_b32_dpp v106, v92 row_ror:2 row_mask:0xf bank_mask:0xf
	v_pk_fma_f32 v[102:103], v[150:151], v[108:109], v[102:103]
	v_mov_b32_dpp v107, v93 row_ror:2 row_mask:0xf bank_mask:0xf
	v_mul_f32_e32 v104, 0xbfb8aa3b, v102
	v_mul_f32_e32 v105, 0xbfb8aa3b, v103
	v_exp_f32_e32 v104, v104
	v_exp_f32_e32 v105, v105
	v_pk_fma_f32 v[114:115], v[92:93], v[152:153], v[144:145]
	v_mov_b32_dpp v106, v92 row_shr:2 row_mask:0xf bank_mask:0xf
	v_add_f32_e32 v104, 1.0, v104
	v_add_f32_e32 v105, 1.0, v105
	v_rcp_f32_e32 v104, v104
	v_rcp_f32_e32 v105, v105
	v_mov_b32_dpp v108, v92 row_ror:3 row_mask:0xf bank_mask:0xf
	v_mov_b32_dpp v107, v93 row_shr:2 row_mask:0xf bank_mask:0xf
	v_mov_b32_dpp v109, v93 row_ror:3 row_mask:0xf bank_mask:0xf
	v_pk_mul_f32 v[102:103], v[102:103], v[104:105]
	v_mov_b32_dpp v104, v92 row_ror:1 row_mask:0xf bank_mask:0xf
	v_mov_b32_dpp v105, v93 row_ror:1 row_mask:0xf bank_mask:0xf
	v_mov_b32_dpp v108, v92 row_shr:3 row_mask:0xf bank_mask:0xf
	v_mov_b32_dpp v104, v92 row_shr:1 row_mask:0xf bank_mask:0xf
	v_mov_b32_dpp v105, v93 row_shr:1 row_mask:0xf bank_mask:0xf
	v_pk_fma_f32 v[104:105], v[140:141], v[104:105], v[114:115]
	v_mov_b32_dpp v109, v93 row_shr:3 row_mask:0xf bank_mask:0xf
	v_pk_fma_f32 v[104:105], v[136:137], v[106:107], v[104:105]
	v_pk_fma_f32 v[110:111], v[94:95], v[154:155], v[146:147]
	v_pk_fma_f32 v[104:105], v[132:133], v[108:109], v[104:105]
	v_mov_b32_dpp v108, v94 row_ror:2 row_mask:0xf bank_mask:0xf
	v_mul_f32_e32 v106, 0xbfb8aa3b, v104
	v_mul_f32_e32 v107, 0xbfb8aa3b, v105
	v_exp_f32_e32 v106, v106
	v_exp_f32_e32 v107, v107
	v_mov_b32_dpp v109, v95 row_ror:2 row_mask:0xf bank_mask:0xf
	v_mov_b32_dpp v108, v94 row_shr:2 row_mask:0xf bank_mask:0xf
	v_add_f32_e32 v106, 1.0, v106
	v_add_f32_e32 v107, 1.0, v107
	v_rcp_f32_e32 v106, v106
	v_rcp_f32_e32 v107, v107
	v_mov_b32_dpp v114, v94 row_ror:3 row_mask:0xf bank_mask:0xf
	v_mov_b32_dpp v109, v95 row_shr:2 row_mask:0xf bank_mask:0xf
	v_mov_b32_dpp v115, v95 row_ror:3 row_mask:0xf bank_mask:0xf
	v_pk_mul_f32 v[104:105], v[104:105], v[106:107]
	v_mov_b32_dpp v106, v94 row_ror:1 row_mask:0xf bank_mask:0xf
	v_mov_b32_dpp v107, v95 row_ror:1 row_mask:0xf bank_mask:0xf
	v_mov_b32_dpp v114, v94 row_shr:3 row_mask:0xf bank_mask:0xf
	v_mov_b32_dpp v106, v94 row_shr:1 row_mask:0xf bank_mask:0xf
	v_mov_b32_dpp v107, v95 row_shr:1 row_mask:0xf bank_mask:0xf
	v_pk_fma_f32 v[106:107], v[142:143], v[106:107], v[110:111]
	v_mov_b32_dpp v115, v95 row_shr:3 row_mask:0xf bank_mask:0xf
	v_pk_fma_f32 v[106:107], v[138:139], v[108:109], v[106:107]
	v_add_u32_e32 v118, 0x80, v2
	v_pk_fma_f32 v[106:107], v[134:135], v[114:115], v[106:107]
	v_cvt_pk_bf16_f32 v100, v100, v101
	v_mul_f32_e32 v108, 0xbfb8aa3b, v106
	v_mul_f32_e32 v109, 0xbfb8aa3b, v107
	v_exp_f32_e32 v108, v108
	v_exp_f32_e32 v109, v109
	v_cvt_pk_bf16_f32 v101, v102, v103
	v_cvt_pk_bf16_f32 v102, v104, v105
	v_add_f32_e32 v108, 1.0, v108
	v_add_f32_e32 v109, 1.0, v109
	v_rcp_f32_e32 v108, v108
	v_rcp_f32_e32 v109, v109
	v_mov_b64_e32 v[104:105], s[92:93]
	v_mad_i64_i32 v[104:105], s[20:21], v118, s29, v[104:105]
	v_pk_mul_f32 v[106:107], v[106:107], v[108:109]
	v_lshl_add_u64 v[114:115], v[104:105], 0, s[14:15]
	v_cvt_pk_bf16_f32 v103, v106, v107
	v_lshl_add_u64 v[104:105], v[204:205], 1, v[114:115]
	v_ashrrev_i32_e32 v128, 6, v118
	global_store_dwordx4 v[104:105], v[100:103], off nt
	s_and_saveexec_b64 s[44:45], s[38:39]
	s_cbranch_execz .LBB0_275
	v_readlane_b32 s2, v252, 54
	v_readlane_b32 s3, v252, 55
	v_mad_u64_u32 v[104:105], s[20:21], v128, 6, v[186:187]
	s_nop 0
	v_mov_b64_e32 v[106:107], s[2:3]
	v_mad_i64_i32 v[104:105], s[20:21], v104, s68, v[106:107]
	v_cvt_pk_bf16_f32 v100, v96, v97
	v_cvt_pk_bf16_f32 v101, v98, v99
	v_cvt_pk_bf16_f32 v102, v92, v93
	v_cvt_pk_bf16_f32 v103, v94, v95
	v_lshl_add_u64 v[104:105], v[204:205], 1, v[104:105]
	global_store_dwordx4 v[104:105], v[100:103], off nt
.LBB0_275:
	s_or_b64 exec, exec, s[44:45]
	s_nop 0
	v_mov_b32_dpp v100, v96 row_ror:1 row_mask:0xf bank_mask:0xf
	v_mov_b32_dpp v101, v97 row_ror:1 row_mask:0xf bank_mask:0xf
	v_mov_b32_dpp v102, v96 row_ror:2 row_mask:0xf bank_mask:0xf
	v_mov_b32_dpp v100, v88 row_shr:1 row_mask:0xf bank_mask:0xf
	v_mov_b32_dpp v101, v89 row_shr:1 row_mask:0xf bank_mask:0xf
	v_mov_b32_dpp v103, v97 row_ror:2 row_mask:0xf bank_mask:0xf
	v_pk_fma_f32 v[106:107], v[88:89], v[168:169], v[164:165]
	v_mov_b32_dpp v102, v88 row_shr:2 row_mask:0xf bank_mask:0xf
	v_mov_b32_dpp v96, v96 row_ror:3 row_mask:0xf bank_mask:0xf
	v_mov_b32_dpp v103, v89 row_shr:2 row_mask:0xf bank_mask:0xf
	v_mov_b32_dpp v97, v97 row_ror:3 row_mask:0xf bank_mask:0xf
	v_pk_fma_f32 v[100:101], v[160:161], v[100:101], v[106:107]
	v_mov_b32_dpp v96, v88 row_shr:3 row_mask:0xf bank_mask:0xf
	v_mov_b32_dpp v97, v89 row_shr:3 row_mask:0xf bank_mask:0xf
	v_pk_fma_f32 v[100:101], v[156:157], v[102:103], v[100:101]
	v_pk_fma_f32 v[104:105], v[90:91], v[170:171], v[166:167]
	v_pk_fma_f32 v[96:97], v[148:149], v[96:97], v[100:101]
	v_mov_b32_dpp v102, v98 row_ror:2 row_mask:0xf bank_mask:0xf
	v_mul_f32_e32 v100, 0xbfb8aa3b, v96
	v_mul_f32_e32 v101, 0xbfb8aa3b, v97
	v_exp_f32_e32 v100, v100
	v_exp_f32_e32 v101, v101
	v_mov_b32_dpp v103, v99 row_ror:2 row_mask:0xf bank_mask:0xf
	v_mov_b32_dpp v102, v90 row_shr:2 row_mask:0xf bank_mask:0xf
	v_add_f32_e32 v100, 1.0, v100
	v_add_f32_e32 v101, 1.0, v101
	v_rcp_f32_e32 v100, v100
	v_rcp_f32_e32 v101, v101
	v_mov_b32_dpp v103, v91 row_shr:2 row_mask:0xf bank_mask:0xf
	v_pk_fma_f32 v[106:107], v[84:85], v[152:153], v[144:145]
	s_mov_b64 s[2:3], 0x4001000
	v_pk_mul_f32 v[96:97], v[96:97], v[100:101]
	v_mov_b32_dpp v100, v98 row_ror:1 row_mask:0xf bank_mask:0xf
	v_mov_b32_dpp v101, v99 row_ror:1 row_mask:0xf bank_mask:0xf
	v_mov_b32_dpp v98, v98 row_ror:3 row_mask:0xf bank_mask:0xf
	v_mov_b32_dpp v100, v90 row_shr:1 row_mask:0xf bank_mask:0xf
	v_mov_b32_dpp v101, v91 row_shr:1 row_mask:0xf bank_mask:0xf
	v_mov_b32_dpp v99, v99 row_ror:3 row_mask:0xf bank_mask:0xf
	v_pk_fma_f32 v[100:101], v[162:163], v[100:101], v[104:105]
	v_mov_b32_dpp v98, v90 row_shr:3 row_mask:0xf bank_mask:0xf
	v_mov_b32_dpp v99, v91 row_shr:3 row_mask:0xf bank_mask:0xf
	v_pk_fma_f32 v[100:101], v[158:159], v[102:103], v[100:101]
	v_mov_b32_dpp v102, v92 row_ror:2 row_mask:0xf bank_mask:0xf
	v_pk_fma_f32 v[98:99], v[150:151], v[98:99], v[100:101]
	v_mov_b32_dpp v103, v93 row_ror:2 row_mask:0xf bank_mask:0xf
	v_mul_f32_e32 v100, 0xbfb8aa3b, v98
	v_mul_f32_e32 v101, 0xbfb8aa3b, v99
	v_exp_f32_e32 v100, v100
	v_exp_f32_e32 v101, v101
	v_mov_b32_dpp v102, v84 row_shr:2 row_mask:0xf bank_mask:0xf
	v_mov_b32_dpp v103, v85 row_shr:2 row_mask:0xf bank_mask:0xf
	v_add_f32_e32 v100, 1.0, v100
	v_add_f32_e32 v101, 1.0, v101
	v_rcp_f32_e32 v100, v100
	v_rcp_f32_e32 v101, v101
	v_pk_fma_f32 v[104:105], v[86:87], v[154:155], v[146:147]
	v_pk_mul_f32 v[98:99], v[98:99], v[100:101]
	v_mov_b32_dpp v100, v92 row_ror:1 row_mask:0xf bank_mask:0xf
	v_mov_b32_dpp v101, v93 row_ror:1 row_mask:0xf bank_mask:0xf
	v_mov_b32_dpp v92, v92 row_ror:3 row_mask:0xf bank_mask:0xf
	v_mov_b32_dpp v100, v84 row_shr:1 row_mask:0xf bank_mask:0xf
	v_mov_b32_dpp v101, v85 row_shr:1 row_mask:0xf bank_mask:0xf
	v_mov_b32_dpp v93, v93 row_ror:3 row_mask:0xf bank_mask:0xf
	v_pk_fma_f32 v[100:101], v[140:141], v[100:101], v[106:107]
	v_mov_b32_dpp v92, v84 row_shr:3 row_mask:0xf bank_mask:0xf
	v_mov_b32_dpp v93, v85 row_shr:3 row_mask:0xf bank_mask:0xf
	v_pk_fma_f32 v[100:101], v[136:137], v[102:103], v[100:101]
	v_mov_b32_dpp v102, v94 row_ror:2 row_mask:0xf bank_mask:0xf
	v_pk_fma_f32 v[92:93], v[132:133], v[92:93], v[100:101]
	v_mov_b32_dpp v103, v95 row_ror:2 row_mask:0xf bank_mask:0xf
	v_mul_f32_e32 v100, 0xbfb8aa3b, v92
	v_mul_f32_e32 v101, 0xbfb8aa3b, v93
	v_exp_f32_e32 v100, v100
	v_exp_f32_e32 v101, v101
	v_mov_b32_dpp v102, v86 row_shr:2 row_mask:0xf bank_mask:0xf
	v_mov_b32_dpp v103, v87 row_shr:2 row_mask:0xf bank_mask:0xf
	v_add_f32_e32 v100, 1.0, v100
	v_add_f32_e32 v101, 1.0, v101
	v_rcp_f32_e32 v100, v100
	v_rcp_f32_e32 v101, v101
	s_nop 0
	v_pk_mul_f32 v[92:93], v[92:93], v[100:101]
	v_mov_b32_dpp v100, v94 row_ror:1 row_mask:0xf bank_mask:0xf
	v_mov_b32_dpp v101, v95 row_ror:1 row_mask:0xf bank_mask:0xf
	v_mov_b32_dpp v94, v94 row_ror:3 row_mask:0xf bank_mask:0xf
	v_mov_b32_dpp v100, v86 row_shr:1 row_mask:0xf bank_mask:0xf
	v_mov_b32_dpp v101, v87 row_shr:1 row_mask:0xf bank_mask:0xf
	v_mov_b32_dpp v95, v95 row_ror:3 row_mask:0xf bank_mask:0xf
	v_pk_fma_f32 v[100:101], v[142:143], v[100:101], v[104:105]
	v_mov_b32_dpp v94, v86 row_shr:3 row_mask:0xf bank_mask:0xf
	v_mov_b32_dpp v95, v87 row_shr:3 row_mask:0xf bank_mask:0xf
	v_pk_fma_f32 v[100:101], v[138:139], v[102:103], v[100:101]
	v_add_u32_e32 v102, 0x90, v2
	v_pk_fma_f32 v[94:95], v[134:135], v[94:95], v[100:101]
	s_nop 0
	v_mul_f32_e32 v100, 0xbfb8aa3b, v94
	v_mul_f32_e32 v101, 0xbfb8aa3b, v95
	v_exp_f32_e32 v100, v100
	v_exp_f32_e32 v101, v101
	v_add_f32_e32 v100, 1.0, v100
	v_add_f32_e32 v101, 1.0, v101
	v_rcp_f32_e32 v100, v100
	v_rcp_f32_e32 v101, v101
	s_nop 0
	v_pk_mul_f32 v[100:101], v[94:95], v[100:101]
	v_cvt_pk_bf16_f32 v94, v96, v97
	v_cvt_pk_bf16_f32 v96, v92, v93
	v_mov_b64_e32 v[92:93], s[92:93]
	v_cvt_pk_bf16_f32 v95, v98, v99
	v_mad_i64_i32 v[98:99], s[20:21], v102, s29, v[92:93]
	v_lshl_add_u64 v[118:119], v[98:99], 0, s[2:3]
	v_cvt_pk_bf16_f32 v97, v100, v101
	v_lshl_add_u64 v[98:99], v[118:119], 0, v[126:127]
	global_store_dwordx4 v[98:99], v[94:97], off nt
	v_pk_fma_f32 v[100:101], v[80:81], v[168:169], v[164:165]
	v_pk_fma_f32 v[98:99], v[82:83], v[170:171], v[166:167]
	v_mov_b32_dpp v94, v88 row_ror:1 row_mask:0xf bank_mask:0xf
	v_mov_b32_dpp v95, v89 row_ror:1 row_mask:0xf bank_mask:0xf
	v_mov_b32_dpp v96, v88 row_ror:2 row_mask:0xf bank_mask:0xf
	v_mov_b32_dpp v94, v80 row_shr:1 row_mask:0xf bank_mask:0xf
	v_mov_b32_dpp v95, v81 row_shr:1 row_mask:0xf bank_mask:0xf
	v_mov_b32_dpp v97, v89 row_ror:2 row_mask:0xf bank_mask:0xf
	v_mov_b32_dpp v96, v80 row_shr:2 row_mask:0xf bank_mask:0xf
	v_mov_b32_dpp v88, v88 row_ror:3 row_mask:0xf bank_mask:0xf
	v_mov_b32_dpp v97, v81 row_shr:2 row_mask:0xf bank_mask:0xf
	v_mov_b32_dpp v89, v89 row_ror:3 row_mask:0xf bank_mask:0xf
	v_pk_fma_f32 v[94:95], v[160:161], v[94:95], v[100:101]
	v_mov_b32_dpp v88, v80 row_shr:3 row_mask:0xf bank_mask:0xf
	v_mov_b32_dpp v89, v81 row_shr:3 row_mask:0xf bank_mask:0xf
	v_pk_fma_f32 v[94:95], v[156:157], v[96:97], v[94:95]
	v_mov_b32_dpp v96, v90 row_ror:2 row_mask:0xf bank_mask:0xf
	v_pk_fma_f32 v[88:89], v[148:149], v[88:89], v[94:95]
	v_mov_b32_dpp v97, v91 row_ror:2 row_mask:0xf bank_mask:0xf
	v_mul_f32_e32 v94, 0xbfb8aa3b, v88
	v_mul_f32_e32 v95, 0xbfb8aa3b, v89
	v_exp_f32_e32 v94, v94
	v_exp_f32_e32 v95, v95
	v_mov_b32_dpp v96, v82 row_shr:2 row_mask:0xf bank_mask:0xf
	v_mov_b32_dpp v97, v83 row_shr:2 row_mask:0xf bank_mask:0xf
	v_add_f32_e32 v94, 1.0, v94
	v_add_f32_e32 v95, 1.0, v95
	v_rcp_f32_e32 v94, v94
	v_rcp_f32_e32 v95, v95
	v_pk_fma_f32 v[100:101], v[76:77], v[152:153], v[144:145]
	v_pk_mul_f32 v[88:89], v[88:89], v[94:95]
	v_mov_b32_dpp v94, v90 row_ror:1 row_mask:0xf bank_mask:0xf
	v_mov_b32_dpp v95, v91 row_ror:1 row_mask:0xf bank_mask:0xf
	v_mov_b32_dpp v90, v90 row_ror:3 row_mask:0xf bank_mask:0xf
	v_mov_b32_dpp v94, v82 row_shr:1 row_mask:0xf bank_mask:0xf
	v_mov_b32_dpp v95, v83 row_shr:1 row_mask:0xf bank_mask:0xf
	v_mov_b32_dpp v91, v91 row_ror:3 row_mask:0xf bank_mask:0xf
	v_pk_fma_f32 v[94:95], v[162:163], v[94:95], v[98:99]
	v_mov_b32_dpp v90, v82 row_shr:3 row_mask:0xf bank_mask:0xf
	v_mov_b32_dpp v91, v83 row_shr:3 row_mask:0xf bank_mask:0xf
	v_pk_fma_f32 v[94:95], v[158:159], v[96:97], v[94:95]
	v_mov_b32_dpp v96, v84 row_ror:2 row_mask:0xf bank_mask:0xf
	v_pk_fma_f32 v[90:91], v[150:151], v[90:91], v[94:95]
	v_mov_b32_dpp v97, v85 row_ror:2 row_mask:0xf bank_mask:0xf
	v_mul_f32_e32 v94, 0xbfb8aa3b, v90
	v_mul_f32_e32 v95, 0xbfb8aa3b, v91
	v_exp_f32_e32 v94, v94
	v_exp_f32_e32 v95, v95
	v_mov_b32_dpp v96, v76 row_shr:2 row_mask:0xf bank_mask:0xf
	v_mov_b32_dpp v97, v77 row_shr:2 row_mask:0xf bank_mask:0xf
	v_add_f32_e32 v94, 1.0, v94
	v_add_f32_e32 v95, 1.0, v95
	v_rcp_f32_e32 v94, v94
	v_rcp_f32_e32 v95, v95
	v_pk_fma_f32 v[98:99], v[78:79], v[154:155], v[146:147]
	v_pk_mul_f32 v[90:91], v[90:91], v[94:95]
	v_mov_b32_dpp v94, v84 row_ror:1 row_mask:0xf bank_mask:0xf
	v_mov_b32_dpp v95, v85 row_ror:1 row_mask:0xf bank_mask:0xf
	v_mov_b32_dpp v84, v84 row_ror:3 row_mask:0xf bank_mask:0xf
	v_mov_b32_dpp v94, v76 row_shr:1 row_mask:0xf bank_mask:0xf
	v_mov_b32_dpp v95, v77 row_shr:1 row_mask:0xf bank_mask:0xf
	v_mov_b32_dpp v85, v85 row_ror:3 row_mask:0xf bank_mask:0xf
	v_pk_fma_f32 v[94:95], v[140:141], v[94:95], v[100:101]
	v_mov_b32_dpp v84, v76 row_shr:3 row_mask:0xf bank_mask:0xf
	v_mov_b32_dpp v85, v77 row_shr:3 row_mask:0xf bank_mask:0xf
	v_pk_fma_f32 v[94:95], v[136:137], v[96:97], v[94:95]
	v_mov_b32_dpp v96, v86 row_ror:2 row_mask:0xf bank_mask:0xf
	v_pk_fma_f32 v[84:85], v[132:133], v[84:85], v[94:95]
	v_mov_b32_dpp v97, v87 row_ror:2 row_mask:0xf bank_mask:0xf
	v_mul_f32_e32 v94, 0xbfb8aa3b, v84
	v_mul_f32_e32 v95, 0xbfb8aa3b, v85
	v_exp_f32_e32 v94, v94
	v_exp_f32_e32 v95, v95
	v_mov_b32_dpp v96, v78 row_shr:2 row_mask:0xf bank_mask:0xf
	v_mov_b32_dpp v97, v79 row_shr:2 row_mask:0xf bank_mask:0xf
	v_add_f32_e32 v94, 1.0, v94
	v_add_f32_e32 v95, 1.0, v95
	v_rcp_f32_e32 v94, v94
	v_rcp_f32_e32 v95, v95
	s_nop 0
	v_pk_mul_f32 v[94:95], v[84:85], v[94:95]
	v_mov_b32_dpp v84, v86 row_ror:1 row_mask:0xf bank_mask:0xf
	v_mov_b32_dpp v85, v87 row_ror:1 row_mask:0xf bank_mask:0xf
	v_mov_b32_dpp v86, v86 row_ror:3 row_mask:0xf bank_mask:0xf
	v_mov_b32_dpp v84, v78 row_shr:1 row_mask:0xf bank_mask:0xf
	v_mov_b32_dpp v85, v79 row_shr:1 row_mask:0xf bank_mask:0xf
	v_mov_b32_dpp v87, v87 row_ror:3 row_mask:0xf bank_mask:0xf
	v_pk_fma_f32 v[84:85], v[142:143], v[84:85], v[98:99]
	v_mov_b32_dpp v86, v78 row_shr:3 row_mask:0xf bank_mask:0xf
	v_mov_b32_dpp v87, v79 row_shr:3 row_mask:0xf bank_mask:0xf
	v_pk_fma_f32 v[84:85], v[138:139], v[96:97], v[84:85]
	v_add_u32_e32 v98, 0xa0, v2
	v_pk_fma_f32 v[84:85], v[134:135], v[86:87], v[84:85]
	v_add_u32_e32 v2, 0xb0, v2
	v_mul_f32_e32 v86, 0xbfb8aa3b, v84
	v_mul_f32_e32 v87, 0xbfb8aa3b, v85
	v_exp_f32_e32 v86, v86
	v_exp_f32_e32 v87, v87
	v_add_f32_e32 v86, 1.0, v86
	v_add_f32_e32 v87, 1.0, v87
	v_rcp_f32_e32 v86, v86
	v_rcp_f32_e32 v87, v87
	s_nop 0
	v_pk_mul_f32 v[96:97], v[84:85], v[86:87]
	v_cvt_pk_bf16_f32 v84, v88, v89
	v_mad_i64_i32 v[88:89], s[20:21], v98, s29, v[92:93]
	v_lshl_add_u64 v[120:121], v[88:89], 0, s[2:3]
	v_cvt_pk_bf16_f32 v85, v90, v91
	v_cvt_pk_bf16_f32 v86, v94, v95
	v_cvt_pk_bf16_f32 v87, v96, v97
	v_lshl_add_u64 v[88:89], v[120:121], 0, v[126:127]
	global_store_dwordx4 v[88:89], v[84:87], off nt
	v_pk_fma_f32 v[90:91], v[72:73], v[168:169], v[164:165]
	v_pk_fma_f32 v[88:89], v[74:75], v[170:171], v[166:167]
	v_mov_b32_dpp v84, v80 row_ror:1 row_mask:0xf bank_mask:0xf
	v_mov_b32_dpp v85, v81 row_ror:1 row_mask:0xf bank_mask:0xf
	v_mov_b32_dpp v86, v80 row_ror:2 row_mask:0xf bank_mask:0xf
	v_mov_b32_dpp v84, v72 row_shr:1 row_mask:0xf bank_mask:0xf
	v_mov_b32_dpp v85, v73 row_shr:1 row_mask:0xf bank_mask:0xf
	v_mov_b32_dpp v87, v81 row_ror:2 row_mask:0xf bank_mask:0xf
	v_mov_b32_dpp v86, v72 row_shr:2 row_mask:0xf bank_mask:0xf
	v_mov_b32_dpp v80, v80 row_ror:3 row_mask:0xf bank_mask:0xf
	v_mov_b32_dpp v87, v73 row_shr:2 row_mask:0xf bank_mask:0xf
	v_mov_b32_dpp v81, v81 row_ror:3 row_mask:0xf bank_mask:0xf
	v_pk_fma_f32 v[84:85], v[160:161], v[84:85], v[90:91]
	v_mov_b32_dpp v80, v72 row_shr:3 row_mask:0xf bank_mask:0xf
	v_mov_b32_dpp v81, v73 row_shr:3 row_mask:0xf bank_mask:0xf
	v_pk_fma_f32 v[84:85], v[156:157], v[86:87], v[84:85]
	v_mov_b32_dpp v86, v82 row_ror:2 row_mask:0xf bank_mask:0xf
	v_pk_fma_f32 v[80:81], v[148:149], v[80:81], v[84:85]
	v_mov_b32_dpp v87, v83 row_ror:2 row_mask:0xf bank_mask:0xf
	v_mul_f32_e32 v84, 0xbfb8aa3b, v80
	v_mul_f32_e32 v85, 0xbfb8aa3b, v81
	v_exp_f32_e32 v84, v84
	v_exp_f32_e32 v85, v85
	v_mov_b32_dpp v86, v74 row_shr:2 row_mask:0xf bank_mask:0xf
	v_mov_b32_dpp v87, v75 row_shr:2 row_mask:0xf bank_mask:0xf
	v_add_f32_e32 v84, 1.0, v84
	v_add_f32_e32 v85, 1.0, v85
	v_rcp_f32_e32 v84, v84
	v_rcp_f32_e32 v85, v85
	v_pk_fma_f32 v[90:91], v[68:69], v[152:153], v[144:145]
	v_pk_mul_f32 v[80:81], v[80:81], v[84:85]
	v_mov_b32_dpp v84, v82 row_ror:1 row_mask:0xf bank_mask:0xf
	v_mov_b32_dpp v85, v83 row_ror:1 row_mask:0xf bank_mask:0xf
	v_mov_b32_dpp v82, v82 row_ror:3 row_mask:0xf bank_mask:0xf
	v_mov_b32_dpp v84, v74 row_shr:1 row_mask:0xf bank_mask:0xf
	v_mov_b32_dpp v85, v75 row_shr:1 row_mask:0xf bank_mask:0xf
	v_mov_b32_dpp v83, v83 row_ror:3 row_mask:0xf bank_mask:0xf
	v_pk_fma_f32 v[84:85], v[162:163], v[84:85], v[88:89]
	v_mov_b32_dpp v82, v74 row_shr:3 row_mask:0xf bank_mask:0xf
	v_mov_b32_dpp v83, v75 row_shr:3 row_mask:0xf bank_mask:0xf
	v_pk_fma_f32 v[84:85], v[158:159], v[86:87], v[84:85]
	v_mov_b32_dpp v86, v76 row_ror:2 row_mask:0xf bank_mask:0xf
	v_pk_fma_f32 v[82:83], v[150:151], v[82:83], v[84:85]
	v_mov_b32_dpp v87, v77 row_ror:2 row_mask:0xf bank_mask:0xf
	v_mul_f32_e32 v84, 0xbfb8aa3b, v82
	v_mul_f32_e32 v85, 0xbfb8aa3b, v83
	v_exp_f32_e32 v84, v84
	v_exp_f32_e32 v85, v85
	v_mov_b32_dpp v86, v68 row_shr:2 row_mask:0xf bank_mask:0xf
	v_mov_b32_dpp v87, v69 row_shr:2 row_mask:0xf bank_mask:0xf
	v_add_f32_e32 v84, 1.0, v84
	v_add_f32_e32 v85, 1.0, v85
	v_rcp_f32_e32 v84, v84
	v_rcp_f32_e32 v85, v85
	v_pk_fma_f32 v[88:89], v[70:71], v[154:155], v[146:147]
	v_pk_mul_f32 v[82:83], v[82:83], v[84:85]
	v_mov_b32_dpp v84, v76 row_ror:1 row_mask:0xf bank_mask:0xf
	v_mov_b32_dpp v85, v77 row_ror:1 row_mask:0xf bank_mask:0xf
	v_mov_b32_dpp v76, v76 row_ror:3 row_mask:0xf bank_mask:0xf
	v_mov_b32_dpp v84, v68 row_shr:1 row_mask:0xf bank_mask:0xf
	v_mov_b32_dpp v85, v69 row_shr:1 row_mask:0xf bank_mask:0xf
	v_mov_b32_dpp v77, v77 row_ror:3 row_mask:0xf bank_mask:0xf
	v_pk_fma_f32 v[84:85], v[140:141], v[84:85], v[90:91]
	v_mov_b32_dpp v76, v68 row_shr:3 row_mask:0xf bank_mask:0xf
	v_mov_b32_dpp v77, v69 row_shr:3 row_mask:0xf bank_mask:0xf
	v_pk_fma_f32 v[84:85], v[136:137], v[86:87], v[84:85]
	v_mov_b32_dpp v86, v78 row_ror:2 row_mask:0xf bank_mask:0xf
	v_pk_fma_f32 v[76:77], v[132:133], v[76:77], v[84:85]
	v_mov_b32_dpp v87, v79 row_ror:2 row_mask:0xf bank_mask:0xf
	v_mul_f32_e32 v84, 0xbfb8aa3b, v76
	v_mul_f32_e32 v85, 0xbfb8aa3b, v77
	v_exp_f32_e32 v84, v84
	v_exp_f32_e32 v85, v85
	v_mov_b32_dpp v86, v70 row_shr:2 row_mask:0xf bank_mask:0xf
	v_mov_b32_dpp v87, v71 row_shr:2 row_mask:0xf bank_mask:0xf
	v_add_f32_e32 v84, 1.0, v84
	v_add_f32_e32 v85, 1.0, v85
	v_rcp_f32_e32 v84, v84
	v_rcp_f32_e32 v85, v85
	s_nop 0
	v_pk_mul_f32 v[84:85], v[76:77], v[84:85]
	v_mov_b32_dpp v76, v78 row_ror:1 row_mask:0xf bank_mask:0xf
	v_mov_b32_dpp v77, v79 row_ror:1 row_mask:0xf bank_mask:0xf
	v_mov_b32_dpp v78, v78 row_ror:3 row_mask:0xf bank_mask:0xf
	v_mov_b32_dpp v76, v70 row_shr:1 row_mask:0xf bank_mask:0xf
	v_mov_b32_dpp v77, v71 row_shr:1 row_mask:0xf bank_mask:0xf
	v_mov_b32_dpp v79, v79 row_ror:3 row_mask:0xf bank_mask:0xf
	v_pk_fma_f32 v[76:77], v[142:143], v[76:77], v[88:89]
	v_mov_b32_dpp v78, v70 row_shr:3 row_mask:0xf bank_mask:0xf
	v_mov_b32_dpp v79, v71 row_shr:3 row_mask:0xf bank_mask:0xf
	v_pk_fma_f32 v[76:77], v[138:139], v[86:87], v[76:77]
	s_nop 0
	v_pk_fma_f32 v[76:77], v[134:135], v[78:79], v[76:77]
	s_nop 0
	v_mul_f32_e32 v78, 0xbfb8aa3b, v76
	v_mul_f32_e32 v79, 0xbfb8aa3b, v77
	v_exp_f32_e32 v78, v78
	v_exp_f32_e32 v79, v79
	v_add_f32_e32 v78, 1.0, v78
	v_add_f32_e32 v79, 1.0, v79
	v_rcp_f32_e32 v78, v78
	v_rcp_f32_e32 v79, v79
	s_nop 0
	v_pk_mul_f32 v[86:87], v[76:77], v[78:79]
	v_cvt_pk_bf16_f32 v76, v80, v81
	v_mad_i64_i32 v[80:81], s[20:21], v2, s29, v[92:93]
	v_lshl_add_u64 v[122:123], v[80:81], 0, s[2:3]
	v_cvt_pk_bf16_f32 v77, v82, v83
	v_cvt_pk_bf16_f32 v78, v84, v85
	v_cvt_pk_bf16_f32 v79, v86, v87
	v_lshl_add_u64 v[80:81], v[122:123], 0, v[126:127]
	v_ashrrev_i32_e32 v126, 6, v2
	global_store_dwordx4 v[80:81], v[76:79], off nt
	s_and_saveexec_b64 s[44:45], s[40:41]
	s_cbranch_execz .LBB0_277
	v_readlane_b32 s2, v252, 54
	v_readlane_b32 s3, v252, 55
	v_cvt_pk_bf16_f32 v72, v72, v73
	v_cvt_pk_bf16_f32 v73, v74, v75
	v_cvt_pk_bf16_f32 v74, v68, v69
	v_cvt_pk_bf16_f32 v75, v70, v71
	v_mad_u64_u32 v[68:69], s[20:21], v126, 6, v[184:185]
	v_mov_b64_e32 v[70:71], s[2:3]
	v_mad_i64_i32 v[68:69], s[20:21], v68, s68, v[70:71]
	v_lshl_add_u64 v[68:69], v[204:205], 1, v[68:69]
	global_store_dwordx4 v[68:69], v[72:75], off nt
.LBB0_277:
	s_or_b64 exec, exec, s[44:45]
	s_mov_b64 s[2:3], 0x3200
	v_add_co_u32_e32 v74, vcc, 0x3000, v206
	v_lshl_add_u64 v[72:73], v[206:207], 0, s[2:3]
	s_nop 0
	v_addc_co_u32_e32 v75, vcc, 0, v207, vcc
	s_mov_b64 s[2:3], 0x6200
	v_lshl_add_u64 v[76:77], v[206:207], 0, s[2:3]
	s_mov_b64 s[2:3], 0x9200
	v_add_co_u32_e32 v90, vcc, 0x9000, v206
	v_lshl_add_u64 v[88:89], v[206:207], 0, s[2:3]
	s_nop 0
	v_addc_co_u32_e32 v91, vcc, 0, v207, vcc
	global_load_dwordx4 v[80:83], v[208:209], off offset:528
	global_load_dwordx4 v[100:103], v[208:209], off offset:512
	global_load_dwordx4 v[68:71], v[206:207], off offset:528
	global_load_dwordx4 v[84:87], v[206:207], off offset:512
	global_load_dwordx4 v[92:95], v[74:75], off offset:512
	s_nop 0
	global_load_dwordx4 v[72:75], v[72:73], off offset:16
	s_nop 0
	global_load_dwordx4 v[96:99], v[214:215], off offset:512
	s_nop 0
	global_load_dwordx4 v[76:79], v[76:77], off offset:16
	s_nop 0
	global_load_dwordx4 v[104:107], v[90:91], off offset:512
	s_nop 0
	global_load_dwordx4 v[88:91], v[88:89], off offset:16
	v_mov_b32_dpp v108, v64 row_ror:1 row_mask:0xf bank_mask:0xf
	v_mov_b32_dpp v109, v65 row_ror:1 row_mask:0xf bank_mask:0xf
	v_mov_b32_dpp v110, v64 row_ror:2 row_mask:0xf bank_mask:0xf
	v_mov_b32_dpp v108, v64 row_shr:1 row_mask:0xf bank_mask:0xf
	v_mov_b32_dpp v109, v65 row_shr:1 row_mask:0xf bank_mask:0xf
	v_mov_b32_dpp v111, v65 row_ror:2 row_mask:0xf bank_mask:0xf
	v_mov_b32_dpp v110, v64 row_shr:2 row_mask:0xf bank_mask:0xf
	v_mov_b32_dpp v130, v64 row_ror:3 row_mask:0xf bank_mask:0xf
	v_mov_b32_dpp v111, v65 row_shr:2 row_mask:0xf bank_mask:0xf
	v_mov_b32_dpp v131, v65 row_ror:3 row_mask:0xf bank_mask:0xf
	v_mov_b32_dpp v130, v64 row_shr:3 row_mask:0xf bank_mask:0xf
	v_or_b32_e32 v2, 0x80, v204
	v_mov_b32_dpp v131, v65 row_shr:3 row_mask:0xf bank_mask:0xf
	s_waitcnt vmcnt(0)
	v_pk_fma_f32 v[134:135], v[64:65], v[104:105], v[100:101]
	s_nop 0
	v_pk_fma_f32 v[108:109], v[96:97], v[108:109], v[134:135]
	v_pk_fma_f32 v[132:133], v[66:67], v[106:107], v[102:103]
	v_pk_fma_f32 v[108:109], v[92:93], v[110:111], v[108:109]
	v_mov_b32_dpp v134, v66 row_ror:3 row_mask:0xf bank_mask:0xf
	v_pk_fma_f32 v[108:109], v[84:85], v[130:131], v[108:109]
	v_mov_b32_dpp v130, v66 row_ror:2 row_mask:0xf bank_mask:0xf
	v_mul_f32_e32 v110, 0xbfb8aa3b, v108
	v_mul_f32_e32 v111, 0xbfb8aa3b, v109
	v_exp_f32_e32 v110, v110
	v_exp_f32_e32 v111, v111
	v_mov_b32_dpp v131, v67 row_ror:2 row_mask:0xf bank_mask:0xf
	v_mov_b32_dpp v130, v66 row_shr:2 row_mask:0xf bank_mask:0xf
	v_add_f32_e32 v110, 1.0, v110
	v_add_f32_e32 v111, 1.0, v111
	v_rcp_f32_e32 v110, v110
	v_rcp_f32_e32 v111, v111
	v_mov_b32_dpp v131, v67 row_shr:2 row_mask:0xf bank_mask:0xf
	v_mov_b32_dpp v135, v67 row_ror:3 row_mask:0xf bank_mask:0xf
	v_mov_b32_dpp v134, v66 row_shr:3 row_mask:0xf bank_mask:0xf
	v_pk_mul_f32 v[108:109], v[108:109], v[110:111]
	v_mov_b32_dpp v110, v66 row_ror:1 row_mask:0xf bank_mask:0xf
	v_mov_b32_dpp v111, v67 row_ror:1 row_mask:0xf bank_mask:0xf
	v_mov_b32_dpp v135, v67 row_shr:3 row_mask:0xf bank_mask:0xf
	v_mov_b32_dpp v110, v66 row_shr:1 row_mask:0xf bank_mask:0xf
	v_mov_b32_dpp v111, v67 row_shr:1 row_mask:0xf bank_mask:0xf
	v_pk_fma_f32 v[110:111], v[98:99], v[110:111], v[132:133]
	v_mov_b32_dpp v132, v60 row_ror:2 row_mask:0xf bank_mask:0xf
	v_pk_fma_f32 v[110:111], v[94:95], v[130:131], v[110:111]
	v_mov_b32_dpp v133, v61 row_ror:2 row_mask:0xf bank_mask:0xf
	v_pk_fma_f32 v[110:111], v[86:87], v[134:135], v[110:111]
	v_pk_fma_f32 v[138:139], v[60:61], v[88:89], v[80:81]
	v_mul_f32_e32 v127, 0xbfb8aa3b, v110
	v_exp_f32_e32 v127, v127
	v_mov_b32_dpp v132, v60 row_shr:2 row_mask:0xf bank_mask:0xf
	v_mov_b32_dpp v134, v60 row_ror:3 row_mask:0xf bank_mask:0xf
	v_mov_b32_dpp v133, v61 row_shr:2 row_mask:0xf bank_mask:0xf
	v_add_f32_e32 v127, 1.0, v127
	v_rcp_f32_e32 v130, v127
	v_mul_f32_e32 v127, 0xbfb8aa3b, v111
	v_exp_f32_e32 v127, v127
	v_mov_b32_dpp v135, v61 row_ror:3 row_mask:0xf bank_mask:0xf
	v_mov_b32_dpp v134, v60 row_shr:3 row_mask:0xf bank_mask:0xf
	v_pk_fma_f32 v[136:137], v[62:63], v[90:91], v[82:83]
	v_add_f32_e32 v127, 1.0, v127
	v_rcp_f32_e32 v131, v127
	v_mov_b32_dpp v135, v61 row_shr:3 row_mask:0xf bank_mask:0xf
	v_cvt_pk_bf16_f32 v108, v108, v109
	v_pk_mul_f32 v[110:111], v[110:111], v[130:131]
	v_mov_b32_dpp v130, v60 row_ror:1 row_mask:0xf bank_mask:0xf
	v_mov_b32_dpp v131, v61 row_ror:1 row_mask:0xf bank_mask:0xf
	v_cvt_pk_bf16_f32 v109, v110, v111
	v_mov_b32_dpp v130, v60 row_shr:1 row_mask:0xf bank_mask:0xf
	v_mov_b32_dpp v131, v61 row_shr:1 row_mask:0xf bank_mask:0xf
	v_pk_fma_f32 v[130:131], v[76:77], v[130:131], v[138:139]
	v_mov_b32_dpp v138, v62 row_ror:3 row_mask:0xf bank_mask:0xf
	v_pk_fma_f32 v[130:131], v[72:73], v[132:133], v[130:131]
	v_mov_b32_dpp v139, v63 row_ror:3 row_mask:0xf bank_mask:0xf
	v_pk_fma_f32 v[130:131], v[68:69], v[134:135], v[130:131]
	v_mov_b32_dpp v134, v62 row_ror:2 row_mask:0xf bank_mask:0xf
	v_mul_f32_e32 v127, 0xbfb8aa3b, v130
	v_exp_f32_e32 v127, v127
	v_mov_b32_dpp v135, v63 row_ror:2 row_mask:0xf bank_mask:0xf
	v_mov_b32_dpp v134, v62 row_shr:2 row_mask:0xf bank_mask:0xf
	v_mov_b32_dpp v138, v62 row_shr:3 row_mask:0xf bank_mask:0xf
	v_add_f32_e32 v127, 1.0, v127
	v_rcp_f32_e32 v132, v127
	v_mul_f32_e32 v127, 0xbfb8aa3b, v131
	v_exp_f32_e32 v127, v127
	v_mov_b32_dpp v135, v63 row_shr:2 row_mask:0xf bank_mask:0xf
	v_mov_b32_dpp v139, v63 row_shr:3 row_mask:0xf bank_mask:0xf
	v_add_f32_e32 v127, 1.0, v127
	v_rcp_f32_e32 v133, v127
	s_nop 0
	v_pk_mul_f32 v[130:131], v[130:131], v[132:133]
	v_mov_b32_dpp v132, v62 row_ror:1 row_mask:0xf bank_mask:0xf
	v_mov_b32_dpp v133, v63 row_ror:1 row_mask:0xf bank_mask:0xf
	v_cvt_pk_bf16_f32 v110, v130, v131
	v_mov_b32_dpp v132, v62 row_shr:1 row_mask:0xf bank_mask:0xf
	v_mov_b32_dpp v133, v63 row_shr:1 row_mask:0xf bank_mask:0xf
	v_pk_fma_f32 v[132:133], v[78:79], v[132:133], v[136:137]
	v_lshl_add_u64 v[130:131], v[2:3], 1, v[212:213]
	v_pk_fma_f32 v[132:133], v[74:75], v[134:135], v[132:133]
	s_nop 0
	v_pk_fma_f32 v[132:133], v[70:71], v[138:139], v[132:133]
	s_nop 0
	v_mul_f32_e32 v127, 0xbfb8aa3b, v132
	v_exp_f32_e32 v127, v127
	s_nop 0
	v_add_f32_e32 v127, 1.0, v127
	v_rcp_f32_e32 v134, v127
	v_mul_f32_e32 v127, 0xbfb8aa3b, v133
	v_exp_f32_e32 v127, v127
	s_nop 0
	v_add_f32_e32 v127, 1.0, v127
	v_rcp_f32_e32 v135, v127
	s_nop 0
	v_pk_mul_f32 v[132:133], v[132:133], v[134:135]
	s_nop 0
	v_cvt_pk_bf16_f32 v111, v132, v133
	global_store_dwordx4 v[130:131], v[108:111], off nt
	s_nop 1
	v_cvt_pk_bf16_f32 v108, v64, v65
	v_cvt_pk_bf16_f32 v109, v66, v67
	v_cvt_pk_bf16_f32 v110, v60, v61
	v_cvt_pk_bf16_f32 v111, v62, v63
	s_and_saveexec_b64 s[44:45], s[38:39]
	s_cbranch_execz .LBB0_279
	v_readlane_b32 s2, v252, 54
	s_ashr_i32 s20, s46, 6
	v_readlane_b32 s3, v252, 55
	v_mad_u64_u32 v[130:131], s[20:21], s20, 6, v[186:187]
	s_nop 0
	v_mov_b64_e32 v[132:133], s[2:3]
	v_mad_i64_i32 v[130:131], s[20:21], v130, s68, v[132:133]
	v_lshl_add_u64 v[130:131], v[204:205], 1, v[130:131]
	global_store_dwordx4 v[130:131], v[108:111], off offset:256 nt
.LBB0_279:
	s_or_b64 exec, exec, s[44:45]
	s_and_saveexec_b64 s[44:45], s[0:1]
	s_cbranch_execz .LBB0_281
	global_store_dwordx4 v[210:211], v[108:111], off offset:256 nt
.LBB0_281:
	s_or_b64 exec, exec, s[44:45]
	s_nop 0
	v_mov_b32_dpp v108, v64 row_ror:1 row_mask:0xf bank_mask:0xf
	v_mov_b32_dpp v109, v65 row_ror:1 row_mask:0xf bank_mask:0xf
	v_mov_b32_dpp v110, v64 row_ror:2 row_mask:0xf bank_mask:0xf
	v_mov_b32_dpp v108, v56 row_shr:1 row_mask:0xf bank_mask:0xf
	v_mov_b32_dpp v109, v57 row_shr:1 row_mask:0xf bank_mask:0xf
	v_mov_b32_dpp v111, v65 row_ror:2 row_mask:0xf bank_mask:0xf
	v_pk_fma_f32 v[132:133], v[56:57], v[104:105], v[100:101]
	v_mov_b32_dpp v110, v56 row_shr:2 row_mask:0xf bank_mask:0xf
	v_mov_b32_dpp v64, v64 row_ror:3 row_mask:0xf bank_mask:0xf
	v_mov_b32_dpp v111, v57 row_shr:2 row_mask:0xf bank_mask:0xf
	v_mov_b32_dpp v65, v65 row_ror:3 row_mask:0xf bank_mask:0xf
	v_pk_fma_f32 v[108:109], v[96:97], v[108:109], v[132:133]
	v_mov_b32_dpp v64, v56 row_shr:3 row_mask:0xf bank_mask:0xf
	v_mov_b32_dpp v65, v57 row_shr:3 row_mask:0xf bank_mask:0xf
	v_pk_fma_f32 v[108:109], v[92:93], v[110:111], v[108:109]
	v_pk_fma_f32 v[130:131], v[58:59], v[106:107], v[102:103]
	v_pk_fma_f32 v[64:65], v[84:85], v[64:65], v[108:109]
	v_mov_b32_dpp v110, v66 row_ror:2 row_mask:0xf bank_mask:0xf
	v_mul_f32_e32 v108, 0xbfb8aa3b, v64
	v_mul_f32_e32 v109, 0xbfb8aa3b, v65
	v_exp_f32_e32 v108, v108
	v_exp_f32_e32 v109, v109
	v_mov_b32_dpp v111, v67 row_ror:2 row_mask:0xf bank_mask:0xf
	v_mov_b32_dpp v110, v58 row_shr:2 row_mask:0xf bank_mask:0xf
	v_add_f32_e32 v108, 1.0, v108
	v_add_f32_e32 v109, 1.0, v109
	v_rcp_f32_e32 v108, v108
	v_rcp_f32_e32 v109, v109
	v_mov_b32_dpp v111, v59 row_shr:2 row_mask:0xf bank_mask:0xf
	v_pk_fma_f32 v[132:133], v[52:53], v[88:89], v[80:81]
	v_pk_mul_f32 v[64:65], v[64:65], v[108:109]
	v_mov_b32_dpp v108, v66 row_ror:1 row_mask:0xf bank_mask:0xf
	v_mov_b32_dpp v109, v67 row_ror:1 row_mask:0xf bank_mask:0xf
	v_mov_b32_dpp v66, v66 row_ror:3 row_mask:0xf bank_mask:0xf
	v_mov_b32_dpp v108, v58 row_shr:1 row_mask:0xf bank_mask:0xf
	v_mov_b32_dpp v109, v59 row_shr:1 row_mask:0xf bank_mask:0xf
	v_mov_b32_dpp v67, v67 row_ror:3 row_mask:0xf bank_mask:0xf
	v_pk_fma_f32 v[108:109], v[98:99], v[108:109], v[130:131]
	v_mov_b32_dpp v66, v58 row_shr:3 row_mask:0xf bank_mask:0xf
	v_mov_b32_dpp v67, v59 row_shr:3 row_mask:0xf bank_mask:0xf
	v_pk_fma_f32 v[108:109], v[94:95], v[110:111], v[108:109]
	v_mov_b32_dpp v110, v60 row_ror:2 row_mask:0xf bank_mask:0xf
	v_pk_fma_f32 v[66:67], v[86:87], v[66:67], v[108:109]
	v_mov_b32_dpp v111, v61 row_ror:2 row_mask:0xf bank_mask:0xf
	v_mul_f32_e32 v108, 0xbfb8aa3b, v66
	v_mul_f32_e32 v109, 0xbfb8aa3b, v67
	v_exp_f32_e32 v108, v108
	v_exp_f32_e32 v109, v109
	v_mov_b32_dpp v110, v52 row_shr:2 row_mask:0xf bank_mask:0xf
	v_mov_b32_dpp v111, v53 row_shr:2 row_mask:0xf bank_mask:0xf
	v_add_f32_e32 v108, 1.0, v108
	v_add_f32_e32 v109, 1.0, v109
	v_rcp_f32_e32 v108, v108
	v_rcp_f32_e32 v109, v109
	v_pk_fma_f32 v[130:131], v[54:55], v[90:91], v[82:83]
	v_pk_mul_f32 v[66:67], v[66:67], v[108:109]
	v_mov_b32_dpp v108, v60 row_ror:1 row_mask:0xf bank_mask:0xf
	v_mov_b32_dpp v109, v61 row_ror:1 row_mask:0xf bank_mask:0xf
	v_mov_b32_dpp v60, v60 row_ror:3 row_mask:0xf bank_mask:0xf
	v_mov_b32_dpp v108, v52 row_shr:1 row_mask:0xf bank_mask:0xf
	v_mov_b32_dpp v109, v53 row_shr:1 row_mask:0xf bank_mask:0xf
	v_mov_b32_dpp v61, v61 row_ror:3 row_mask:0xf bank_mask:0xf
	v_pk_fma_f32 v[108:109], v[76:77], v[108:109], v[132:133]
	v_mov_b32_dpp v60, v52 row_shr:3 row_mask:0xf bank_mask:0xf
	v_mov_b32_dpp v61, v53 row_shr:3 row_mask:0xf bank_mask:0xf
	v_pk_fma_f32 v[108:109], v[72:73], v[110:111], v[108:109]
	v_mov_b32_dpp v110, v62 row_ror:2 row_mask:0xf bank_mask:0xf
	v_pk_fma_f32 v[60:61], v[68:69], v[60:61], v[108:109]
	v_mov_b32_dpp v111, v63 row_ror:2 row_mask:0xf bank_mask:0xf
	v_mul_f32_e32 v108, 0xbfb8aa3b, v60
	v_mul_f32_e32 v109, 0xbfb8aa3b, v61
	v_exp_f32_e32 v108, v108
	v_exp_f32_e32 v109, v109
	v_mov_b32_dpp v110, v54 row_shr:2 row_mask:0xf bank_mask:0xf
	v_mov_b32_dpp v111, v55 row_shr:2 row_mask:0xf bank_mask:0xf
	v_add_f32_e32 v108, 1.0, v108
	v_add_f32_e32 v109, 1.0, v109
	v_rcp_f32_e32 v108, v108
	v_rcp_f32_e32 v109, v109
	s_nop 0
	v_pk_mul_f32 v[60:61], v[60:61], v[108:109]
	v_mov_b32_dpp v108, v62 row_ror:1 row_mask:0xf bank_mask:0xf
	v_mov_b32_dpp v109, v63 row_ror:1 row_mask:0xf bank_mask:0xf
	v_mov_b32_dpp v62, v62 row_ror:3 row_mask:0xf bank_mask:0xf
	v_mov_b32_dpp v108, v54 row_shr:1 row_mask:0xf bank_mask:0xf
	v_mov_b32_dpp v109, v55 row_shr:1 row_mask:0xf bank_mask:0xf
	v_mov_b32_dpp v63, v63 row_ror:3 row_mask:0xf bank_mask:0xf
	v_pk_fma_f32 v[108:109], v[78:79], v[108:109], v[130:131]
	v_mov_b32_dpp v62, v54 row_shr:3 row_mask:0xf bank_mask:0xf
	v_mov_b32_dpp v63, v55 row_shr:3 row_mask:0xf bank_mask:0xf
	v_pk_fma_f32 v[108:109], v[74:75], v[110:111], v[108:109]
	s_nop 0
	v_pk_fma_f32 v[62:63], v[70:71], v[62:63], v[108:109]
	s_nop 0
	v_mul_f32_e32 v108, 0xbfb8aa3b, v62
	v_mul_f32_e32 v109, 0xbfb8aa3b, v63
	v_exp_f32_e32 v108, v108
	v_exp_f32_e32 v109, v109
	v_add_f32_e32 v108, 1.0, v108
	v_add_f32_e32 v109, 1.0, v109
	v_rcp_f32_e32 v108, v108
	v_rcp_f32_e32 v109, v109
	s_nop 0
	v_pk_mul_f32 v[108:109], v[62:63], v[108:109]
	v_cvt_pk_bf16_f32 v62, v64, v65
	v_cvt_pk_bf16_f32 v64, v60, v61
	v_lshlrev_b64 v[60:61], 1, v[2:3]
	v_cvt_pk_bf16_f32 v63, v66, v67
	v_cvt_pk_bf16_f32 v65, v108, v109
	v_lshl_add_u64 v[66:67], v[124:125], 0, v[60:61]
	global_store_dwordx4 v[66:67], v[62:65], off nt
	v_pk_fma_f32 v[108:109], v[48:49], v[104:105], v[100:101]
	v_pk_fma_f32 v[66:67], v[50:51], v[106:107], v[102:103]
	v_mov_b32_dpp v62, v56 row_ror:1 row_mask:0xf bank_mask:0xf
	v_mov_b32_dpp v63, v57 row_ror:1 row_mask:0xf bank_mask:0xf
	v_mov_b32_dpp v64, v56 row_ror:2 row_mask:0xf bank_mask:0xf
	v_mov_b32_dpp v62, v48 row_shr:1 row_mask:0xf bank_mask:0xf
	v_mov_b32_dpp v63, v49 row_shr:1 row_mask:0xf bank_mask:0xf
	v_mov_b32_dpp v65, v57 row_ror:2 row_mask:0xf bank_mask:0xf
	v_mov_b32_dpp v64, v48 row_shr:2 row_mask:0xf bank_mask:0xf
	v_mov_b32_dpp v56, v56 row_ror:3 row_mask:0xf bank_mask:0xf
	v_mov_b32_dpp v65, v49 row_shr:2 row_mask:0xf bank_mask:0xf
	v_mov_b32_dpp v57, v57 row_ror:3 row_mask:0xf bank_mask:0xf
	v_pk_fma_f32 v[62:63], v[96:97], v[62:63], v[108:109]
	v_mov_b32_dpp v56, v48 row_shr:3 row_mask:0xf bank_mask:0xf
	v_mov_b32_dpp v57, v49 row_shr:3 row_mask:0xf bank_mask:0xf
	v_pk_fma_f32 v[62:63], v[92:93], v[64:65], v[62:63]
	v_mov_b32_dpp v64, v58 row_ror:2 row_mask:0xf bank_mask:0xf
	v_pk_fma_f32 v[56:57], v[84:85], v[56:57], v[62:63]
	v_mov_b32_dpp v65, v59 row_ror:2 row_mask:0xf bank_mask:0xf
	v_mul_f32_e32 v62, 0xbfb8aa3b, v56
	v_mul_f32_e32 v63, 0xbfb8aa3b, v57
	v_exp_f32_e32 v62, v62
	v_exp_f32_e32 v63, v63
	v_mov_b32_dpp v64, v50 row_shr:2 row_mask:0xf bank_mask:0xf
	v_mov_b32_dpp v65, v51 row_shr:2 row_mask:0xf bank_mask:0xf
	v_add_f32_e32 v62, 1.0, v62
	v_add_f32_e32 v63, 1.0, v63
	v_rcp_f32_e32 v62, v62
	v_rcp_f32_e32 v63, v63
	v_pk_fma_f32 v[108:109], v[44:45], v[88:89], v[80:81]
	v_pk_mul_f32 v[56:57], v[56:57], v[62:63]
	v_mov_b32_dpp v62, v58 row_ror:1 row_mask:0xf bank_mask:0xf
	v_mov_b32_dpp v63, v59 row_ror:1 row_mask:0xf bank_mask:0xf
	v_mov_b32_dpp v58, v58 row_ror:3 row_mask:0xf bank_mask:0xf
	v_mov_b32_dpp v62, v50 row_shr:1 row_mask:0xf bank_mask:0xf
	v_mov_b32_dpp v63, v51 row_shr:1 row_mask:0xf bank_mask:0xf
	v_mov_b32_dpp v59, v59 row_ror:3 row_mask:0xf bank_mask:0xf
	v_pk_fma_f32 v[62:63], v[98:99], v[62:63], v[66:67]
	v_mov_b32_dpp v58, v50 row_shr:3 row_mask:0xf bank_mask:0xf
	v_mov_b32_dpp v59, v51 row_shr:3 row_mask:0xf bank_mask:0xf
	v_pk_fma_f32 v[62:63], v[94:95], v[64:65], v[62:63]
	v_mov_b32_dpp v64, v52 row_ror:2 row_mask:0xf bank_mask:0xf
	v_pk_fma_f32 v[58:59], v[86:87], v[58:59], v[62:63]
	v_mov_b32_dpp v65, v53 row_ror:2 row_mask:0xf bank_mask:0xf
	v_mul_f32_e32 v62, 0xbfb8aa3b, v58
	v_mul_f32_e32 v63, 0xbfb8aa3b, v59
	v_exp_f32_e32 v62, v62
	v_exp_f32_e32 v63, v63
	v_mov_b32_dpp v64, v44 row_shr:2 row_mask:0xf bank_mask:0xf
	v_mov_b32_dpp v65, v45 row_shr:2 row_mask:0xf bank_mask:0xf
	v_add_f32_e32 v62, 1.0, v62
	v_add_f32_e32 v63, 1.0, v63
	v_rcp_f32_e32 v62, v62
	v_rcp_f32_e32 v63, v63
	v_pk_fma_f32 v[66:67], v[46:47], v[90:91], v[82:83]
	v_pk_mul_f32 v[58:59], v[58:59], v[62:63]
	v_mov_b32_dpp v62, v52 row_ror:1 row_mask:0xf bank_mask:0xf
	v_mov_b32_dpp v63, v53 row_ror:1 row_mask:0xf bank_mask:0xf
	v_mov_b32_dpp v52, v52 row_ror:3 row_mask:0xf bank_mask:0xf
	v_mov_b32_dpp v62, v44 row_shr:1 row_mask:0xf bank_mask:0xf
	v_mov_b32_dpp v63, v45 row_shr:1 row_mask:0xf bank_mask:0xf
	v_mov_b32_dpp v53, v53 row_ror:3 row_mask:0xf bank_mask:0xf
	v_pk_fma_f32 v[62:63], v[76:77], v[62:63], v[108:109]
	v_mov_b32_dpp v52, v44 row_shr:3 row_mask:0xf bank_mask:0xf
	v_mov_b32_dpp v53, v45 row_shr:3 row_mask:0xf bank_mask:0xf
	v_pk_fma_f32 v[62:63], v[72:73], v[64:65], v[62:63]
	v_mov_b32_dpp v64, v54 row_ror:2 row_mask:0xf bank_mask:0xf
	v_pk_fma_f32 v[52:53], v[68:69], v[52:53], v[62:63]
	v_mov_b32_dpp v65, v55 row_ror:2 row_mask:0xf bank_mask:0xf
	v_mul_f32_e32 v62, 0xbfb8aa3b, v52
	v_mul_f32_e32 v63, 0xbfb8aa3b, v53
	v_exp_f32_e32 v62, v62
	v_exp_f32_e32 v63, v63
	v_mov_b32_dpp v64, v46 row_shr:2 row_mask:0xf bank_mask:0xf
	v_mov_b32_dpp v65, v47 row_shr:2 row_mask:0xf bank_mask:0xf
	v_add_f32_e32 v62, 1.0, v62
	v_add_f32_e32 v63, 1.0, v63
	v_rcp_f32_e32 v62, v62
	v_rcp_f32_e32 v63, v63
	s_nop 0
	v_pk_mul_f32 v[62:63], v[52:53], v[62:63]
	v_mov_b32_dpp v52, v54 row_ror:1 row_mask:0xf bank_mask:0xf
	v_mov_b32_dpp v53, v55 row_ror:1 row_mask:0xf bank_mask:0xf
	v_mov_b32_dpp v54, v54 row_ror:3 row_mask:0xf bank_mask:0xf
	v_mov_b32_dpp v52, v46 row_shr:1 row_mask:0xf bank_mask:0xf
	v_mov_b32_dpp v53, v47 row_shr:1 row_mask:0xf bank_mask:0xf
	v_mov_b32_dpp v55, v55 row_ror:3 row_mask:0xf bank_mask:0xf
	v_pk_fma_f32 v[52:53], v[78:79], v[52:53], v[66:67]
	v_mov_b32_dpp v54, v46 row_shr:3 row_mask:0xf bank_mask:0xf
	v_mov_b32_dpp v55, v47 row_shr:3 row_mask:0xf bank_mask:0xf
	v_pk_fma_f32 v[52:53], v[74:75], v[64:65], v[52:53]
	s_nop 0
	v_pk_fma_f32 v[52:53], v[70:71], v[54:55], v[52:53]
	s_nop 0
	v_mul_f32_e32 v54, 0xbfb8aa3b, v52
	v_mul_f32_e32 v55, 0xbfb8aa3b, v53
	v_exp_f32_e32 v54, v54
	v_exp_f32_e32 v55, v55
	v_add_f32_e32 v54, 1.0, v54
	v_add_f32_e32 v55, 1.0, v55
	v_rcp_f32_e32 v54, v54
	v_rcp_f32_e32 v55, v55
	s_nop 0
	v_pk_mul_f32 v[64:65], v[52:53], v[54:55]
	v_cvt_pk_bf16_f32 v52, v56, v57
	v_cvt_pk_bf16_f32 v53, v58, v59
	v_cvt_pk_bf16_f32 v54, v62, v63
	v_cvt_pk_bf16_f32 v55, v64, v65
	v_lshl_add_u64 v[56:57], v[116:117], 0, v[60:61]
	global_store_dwordx4 v[56:57], v[52:55], off nt
	v_pk_fma_f32 v[58:59], v[40:41], v[104:105], v[100:101]
	v_pk_fma_f32 v[56:57], v[42:43], v[106:107], v[102:103]
	v_mov_b32_dpp v52, v48 row_ror:1 row_mask:0xf bank_mask:0xf
	v_mov_b32_dpp v53, v49 row_ror:1 row_mask:0xf bank_mask:0xf
	v_mov_b32_dpp v54, v48 row_ror:2 row_mask:0xf bank_mask:0xf
	v_mov_b32_dpp v52, v40 row_shr:1 row_mask:0xf bank_mask:0xf
	v_mov_b32_dpp v53, v41 row_shr:1 row_mask:0xf bank_mask:0xf
	v_mov_b32_dpp v55, v49 row_ror:2 row_mask:0xf bank_mask:0xf
	v_mov_b32_dpp v54, v40 row_shr:2 row_mask:0xf bank_mask:0xf
	v_mov_b32_dpp v48, v48 row_ror:3 row_mask:0xf bank_mask:0xf
	v_mov_b32_dpp v55, v41 row_shr:2 row_mask:0xf bank_mask:0xf
	v_mov_b32_dpp v49, v49 row_ror:3 row_mask:0xf bank_mask:0xf
	v_pk_fma_f32 v[52:53], v[96:97], v[52:53], v[58:59]
	v_mov_b32_dpp v48, v40 row_shr:3 row_mask:0xf bank_mask:0xf
	v_mov_b32_dpp v49, v41 row_shr:3 row_mask:0xf bank_mask:0xf
	v_pk_fma_f32 v[52:53], v[92:93], v[54:55], v[52:53]
	v_mov_b32_dpp v54, v50 row_ror:2 row_mask:0xf bank_mask:0xf
	v_pk_fma_f32 v[48:49], v[84:85], v[48:49], v[52:53]
	v_mov_b32_dpp v55, v51 row_ror:2 row_mask:0xf bank_mask:0xf
	v_mul_f32_e32 v52, 0xbfb8aa3b, v48
	v_mul_f32_e32 v53, 0xbfb8aa3b, v49
	v_exp_f32_e32 v52, v52
	v_exp_f32_e32 v53, v53
	v_mov_b32_dpp v54, v42 row_shr:2 row_mask:0xf bank_mask:0xf
	v_mov_b32_dpp v55, v43 row_shr:2 row_mask:0xf bank_mask:0xf
	v_add_f32_e32 v52, 1.0, v52
	v_add_f32_e32 v53, 1.0, v53
	v_rcp_f32_e32 v52, v52
	v_rcp_f32_e32 v53, v53
	v_pk_fma_f32 v[58:59], v[36:37], v[88:89], v[80:81]
	v_pk_mul_f32 v[48:49], v[48:49], v[52:53]
	v_mov_b32_dpp v52, v50 row_ror:1 row_mask:0xf bank_mask:0xf
	v_mov_b32_dpp v53, v51 row_ror:1 row_mask:0xf bank_mask:0xf
	v_mov_b32_dpp v50, v50 row_ror:3 row_mask:0xf bank_mask:0xf
	v_mov_b32_dpp v52, v42 row_shr:1 row_mask:0xf bank_mask:0xf
	v_mov_b32_dpp v53, v43 row_shr:1 row_mask:0xf bank_mask:0xf
	v_mov_b32_dpp v51, v51 row_ror:3 row_mask:0xf bank_mask:0xf
	v_pk_fma_f32 v[52:53], v[98:99], v[52:53], v[56:57]
	v_mov_b32_dpp v50, v42 row_shr:3 row_mask:0xf bank_mask:0xf
	v_mov_b32_dpp v51, v43 row_shr:3 row_mask:0xf bank_mask:0xf
	v_pk_fma_f32 v[52:53], v[94:95], v[54:55], v[52:53]
	v_mov_b32_dpp v54, v44 row_ror:2 row_mask:0xf bank_mask:0xf
	v_pk_fma_f32 v[50:51], v[86:87], v[50:51], v[52:53]
	v_mov_b32_dpp v55, v45 row_ror:2 row_mask:0xf bank_mask:0xf
	v_mul_f32_e32 v52, 0xbfb8aa3b, v50
	v_mul_f32_e32 v53, 0xbfb8aa3b, v51
	v_exp_f32_e32 v52, v52
	v_exp_f32_e32 v53, v53
	v_mov_b32_dpp v54, v36 row_shr:2 row_mask:0xf bank_mask:0xf
	v_mov_b32_dpp v55, v37 row_shr:2 row_mask:0xf bank_mask:0xf
	v_add_f32_e32 v52, 1.0, v52
	v_add_f32_e32 v53, 1.0, v53
	v_rcp_f32_e32 v52, v52
	v_rcp_f32_e32 v53, v53
	v_pk_fma_f32 v[56:57], v[38:39], v[90:91], v[82:83]
	v_pk_mul_f32 v[50:51], v[50:51], v[52:53]
	v_mov_b32_dpp v52, v44 row_ror:1 row_mask:0xf bank_mask:0xf
	v_mov_b32_dpp v53, v45 row_ror:1 row_mask:0xf bank_mask:0xf
	v_mov_b32_dpp v44, v44 row_ror:3 row_mask:0xf bank_mask:0xf
	v_mov_b32_dpp v52, v36 row_shr:1 row_mask:0xf bank_mask:0xf
	v_mov_b32_dpp v53, v37 row_shr:1 row_mask:0xf bank_mask:0xf
	v_mov_b32_dpp v45, v45 row_ror:3 row_mask:0xf bank_mask:0xf
	v_pk_fma_f32 v[52:53], v[76:77], v[52:53], v[58:59]
	v_mov_b32_dpp v44, v36 row_shr:3 row_mask:0xf bank_mask:0xf
	v_mov_b32_dpp v45, v37 row_shr:3 row_mask:0xf bank_mask:0xf
	v_pk_fma_f32 v[52:53], v[72:73], v[54:55], v[52:53]
	v_mov_b32_dpp v54, v46 row_ror:2 row_mask:0xf bank_mask:0xf
	v_pk_fma_f32 v[44:45], v[68:69], v[44:45], v[52:53]
	v_mov_b32_dpp v55, v47 row_ror:2 row_mask:0xf bank_mask:0xf
	v_mul_f32_e32 v52, 0xbfb8aa3b, v44
	v_mul_f32_e32 v53, 0xbfb8aa3b, v45
	v_exp_f32_e32 v52, v52
	v_exp_f32_e32 v53, v53
	v_mov_b32_dpp v54, v38 row_shr:2 row_mask:0xf bank_mask:0xf
	v_mov_b32_dpp v55, v39 row_shr:2 row_mask:0xf bank_mask:0xf
	v_add_f32_e32 v52, 1.0, v52
	v_add_f32_e32 v53, 1.0, v53
	v_rcp_f32_e32 v52, v52
	v_rcp_f32_e32 v53, v53
	s_nop 0
	v_pk_mul_f32 v[52:53], v[44:45], v[52:53]
	v_mov_b32_dpp v44, v46 row_ror:1 row_mask:0xf bank_mask:0xf
	v_mov_b32_dpp v45, v47 row_ror:1 row_mask:0xf bank_mask:0xf
	v_mov_b32_dpp v46, v46 row_ror:3 row_mask:0xf bank_mask:0xf
	v_mov_b32_dpp v44, v38 row_shr:1 row_mask:0xf bank_mask:0xf
	v_mov_b32_dpp v45, v39 row_shr:1 row_mask:0xf bank_mask:0xf
	v_mov_b32_dpp v47, v47 row_ror:3 row_mask:0xf bank_mask:0xf
	v_pk_fma_f32 v[44:45], v[78:79], v[44:45], v[56:57]
	v_mov_b32_dpp v46, v38 row_shr:3 row_mask:0xf bank_mask:0xf
	v_mov_b32_dpp v47, v39 row_shr:3 row_mask:0xf bank_mask:0xf
	v_pk_fma_f32 v[44:45], v[74:75], v[54:55], v[44:45]
	s_nop 0
	v_pk_fma_f32 v[44:45], v[70:71], v[46:47], v[44:45]
	s_nop 0
	v_mul_f32_e32 v46, 0xbfb8aa3b, v44
	v_mul_f32_e32 v47, 0xbfb8aa3b, v45
	v_exp_f32_e32 v46, v46
	v_exp_f32_e32 v47, v47
	v_add_f32_e32 v46, 1.0, v46
	v_add_f32_e32 v47, 1.0, v47
	v_rcp_f32_e32 v46, v46
	v_rcp_f32_e32 v47, v47
	s_nop 0
	v_pk_mul_f32 v[54:55], v[44:45], v[46:47]
	v_cvt_pk_bf16_f32 v44, v48, v49
	v_cvt_pk_bf16_f32 v45, v50, v51
	v_cvt_pk_bf16_f32 v46, v52, v53
	v_cvt_pk_bf16_f32 v47, v54, v55
	v_lshl_add_u64 v[48:49], v[112:113], 0, v[60:61]
	global_store_dwordx4 v[48:49], v[44:47], off nt
	s_and_saveexec_b64 s[0:1], s[40:41]
	s_cbranch_execz .LBB0_283
	v_readlane_b32 s2, v252, 54
	s_ashr_i32 s20, s46, 6
	v_readlane_b32 s3, v252, 55
	v_cvt_pk_bf16_f32 v40, v40, v41
	v_cvt_pk_bf16_f32 v41, v42, v43
	v_cvt_pk_bf16_f32 v42, v36, v37
	v_cvt_pk_bf16_f32 v43, v38, v39
	v_mad_u64_u32 v[36:37], s[20:21], s20, 6, v[184:185]
	v_mov_b64_e32 v[38:39], s[2:3]
	v_mad_i64_i32 v[36:37], s[20:21], v36, s68, v[38:39]
	v_lshl_add_u64 v[36:37], v[204:205], 1, v[36:37]
	global_store_dwordx4 v[36:37], v[40:43], off offset:256 nt
.LBB0_283:
	s_or_b64 exec, exec, s[0:1]
	v_mov_b32_dpp v36, v32 row_ror:1 row_mask:0xf bank_mask:0xf
	v_mov_b32_dpp v37, v33 row_ror:1 row_mask:0xf bank_mask:0xf
	v_mov_b32_dpp v38, v32 row_ror:2 row_mask:0xf bank_mask:0xf
	v_mov_b32_dpp v36, v32 row_shr:1 row_mask:0xf bank_mask:0xf
	v_mov_b32_dpp v37, v33 row_shr:1 row_mask:0xf bank_mask:0xf
	v_mov_b32_dpp v39, v33 row_ror:2 row_mask:0xf bank_mask:0xf
	v_pk_fma_f32 v[44:45], v[32:33], v[104:105], v[100:101]
	v_mov_b32_dpp v38, v32 row_shr:2 row_mask:0xf bank_mask:0xf
	v_mov_b32_dpp v40, v32 row_ror:3 row_mask:0xf bank_mask:0xf
	v_mov_b32_dpp v39, v33 row_shr:2 row_mask:0xf bank_mask:0xf
	v_mov_b32_dpp v41, v33 row_ror:3 row_mask:0xf bank_mask:0xf
	v_pk_fma_f32 v[36:37], v[96:97], v[36:37], v[44:45]
	v_mov_b32_dpp v40, v32 row_shr:3 row_mask:0xf bank_mask:0xf
	v_mov_b32_dpp v41, v33 row_shr:3 row_mask:0xf bank_mask:0xf
	v_pk_fma_f32 v[36:37], v[92:93], v[38:39], v[36:37]
	v_pk_fma_f32 v[42:43], v[34:35], v[106:107], v[102:103]
	v_pk_fma_f32 v[36:37], v[84:85], v[40:41], v[36:37]
	v_mov_b32_dpp v40, v34 row_ror:2 row_mask:0xf bank_mask:0xf
	v_mul_f32_e32 v38, 0xbfb8aa3b, v36
	v_mul_f32_e32 v39, 0xbfb8aa3b, v37
	v_exp_f32_e32 v38, v38
	v_exp_f32_e32 v39, v39
	v_mov_b32_dpp v41, v35 row_ror:2 row_mask:0xf bank_mask:0xf
	v_mov_b32_dpp v40, v34 row_shr:2 row_mask:0xf bank_mask:0xf
	v_add_f32_e32 v38, 1.0, v38
	v_add_f32_e32 v39, 1.0, v39
	v_rcp_f32_e32 v38, v38
	v_rcp_f32_e32 v39, v39
	v_mov_b32_dpp v44, v34 row_ror:3 row_mask:0xf bank_mask:0xf
	v_mov_b32_dpp v41, v35 row_shr:2 row_mask:0xf bank_mask:0xf
	v_mov_b32_dpp v45, v35 row_ror:3 row_mask:0xf bank_mask:0xf
	v_pk_mul_f32 v[36:37], v[36:37], v[38:39]
	v_mov_b32_dpp v38, v34 row_ror:1 row_mask:0xf bank_mask:0xf
	v_mov_b32_dpp v39, v35 row_ror:1 row_mask:0xf bank_mask:0xf
	v_mov_b32_dpp v44, v34 row_shr:3 row_mask:0xf bank_mask:0xf
	v_mov_b32_dpp v38, v34 row_shr:1 row_mask:0xf bank_mask:0xf
	v_mov_b32_dpp v39, v35 row_shr:1 row_mask:0xf bank_mask:0xf
	v_pk_fma_f32 v[38:39], v[98:99], v[38:39], v[42:43]
	v_mov_b32_dpp v45, v35 row_shr:3 row_mask:0xf bank_mask:0xf
	v_pk_fma_f32 v[38:39], v[94:95], v[40:41], v[38:39]
	v_mov_b32_dpp v42, v28 row_ror:2 row_mask:0xf bank_mask:0xf
	v_pk_fma_f32 v[38:39], v[86:87], v[44:45], v[38:39]
	v_mov_b32_dpp v43, v29 row_ror:2 row_mask:0xf bank_mask:0xf
	v_mul_f32_e32 v40, 0xbfb8aa3b, v38
	v_mul_f32_e32 v41, 0xbfb8aa3b, v39
	v_exp_f32_e32 v40, v40
	v_exp_f32_e32 v41, v41
	v_pk_fma_f32 v[48:49], v[28:29], v[88:89], v[80:81]
	v_mov_b32_dpp v42, v28 row_shr:2 row_mask:0xf bank_mask:0xf
	v_add_f32_e32 v40, 1.0, v40
	v_add_f32_e32 v41, 1.0, v41
	v_rcp_f32_e32 v40, v40
	v_rcp_f32_e32 v41, v41
	v_mov_b32_dpp v44, v28 row_ror:3 row_mask:0xf bank_mask:0xf
	v_mov_b32_dpp v43, v29 row_shr:2 row_mask:0xf bank_mask:0xf
	v_mov_b32_dpp v45, v29 row_ror:3 row_mask:0xf bank_mask:0xf
	v_pk_mul_f32 v[38:39], v[38:39], v[40:41]
	v_mov_b32_dpp v40, v28 row_ror:1 row_mask:0xf bank_mask:0xf
	v_mov_b32_dpp v41, v29 row_ror:1 row_mask:0xf bank_mask:0xf
	v_mov_b32_dpp v44, v28 row_shr:3 row_mask:0xf bank_mask:0xf
	v_mov_b32_dpp v40, v28 row_shr:1 row_mask:0xf bank_mask:0xf
	v_mov_b32_dpp v41, v29 row_shr:1 row_mask:0xf bank_mask:0xf
	v_pk_fma_f32 v[40:41], v[76:77], v[40:41], v[48:49]
	v_mov_b32_dpp v45, v29 row_shr:3 row_mask:0xf bank_mask:0xf
	v_pk_fma_f32 v[40:41], v[72:73], v[42:43], v[40:41]
	v_pk_fma_f32 v[46:47], v[30:31], v[90:91], v[82:83]
	v_pk_fma_f32 v[40:41], v[68:69], v[44:45], v[40:41]
	v_mov_b32_dpp v44, v30 row_ror:2 row_mask:0xf bank_mask:0xf
	v_mul_f32_e32 v42, 0xbfb8aa3b, v40
	v_mul_f32_e32 v43, 0xbfb8aa3b, v41
	v_exp_f32_e32 v42, v42
	v_exp_f32_e32 v43, v43
	v_mov_b32_dpp v45, v31 row_ror:2 row_mask:0xf bank_mask:0xf
	v_mov_b32_dpp v44, v30 row_shr:2 row_mask:0xf bank_mask:0xf
	v_add_f32_e32 v42, 1.0, v42
	v_add_f32_e32 v43, 1.0, v43
	v_rcp_f32_e32 v42, v42
	v_rcp_f32_e32 v43, v43
	v_mov_b32_dpp v48, v30 row_ror:3 row_mask:0xf bank_mask:0xf
	v_mov_b32_dpp v45, v31 row_shr:2 row_mask:0xf bank_mask:0xf
	v_mov_b32_dpp v49, v31 row_ror:3 row_mask:0xf bank_mask:0xf
	v_pk_mul_f32 v[40:41], v[40:41], v[42:43]
	v_mov_b32_dpp v42, v30 row_ror:1 row_mask:0xf bank_mask:0xf
	v_mov_b32_dpp v43, v31 row_ror:1 row_mask:0xf bank_mask:0xf
	v_mov_b32_dpp v48, v30 row_shr:3 row_mask:0xf bank_mask:0xf
	v_mov_b32_dpp v42, v30 row_shr:1 row_mask:0xf bank_mask:0xf
	v_mov_b32_dpp v43, v31 row_shr:1 row_mask:0xf bank_mask:0xf
	v_pk_fma_f32 v[42:43], v[78:79], v[42:43], v[46:47]
	v_mov_b32_dpp v49, v31 row_shr:3 row_mask:0xf bank_mask:0xf
	v_pk_fma_f32 v[42:43], v[74:75], v[44:45], v[42:43]
	v_cvt_pk_bf16_f32 v36, v36, v37
	v_pk_fma_f32 v[42:43], v[70:71], v[48:49], v[42:43]
	v_cvt_pk_bf16_f32 v37, v38, v39
	v_mul_f32_e32 v44, 0xbfb8aa3b, v42
	v_mul_f32_e32 v45, 0xbfb8aa3b, v43
	v_exp_f32_e32 v44, v44
	v_exp_f32_e32 v45, v45
	v_cvt_pk_bf16_f32 v38, v40, v41
	v_lshl_add_u64 v[40:41], v[2:3], 1, v[114:115]
	v_add_f32_e32 v44, 1.0, v44
	v_add_f32_e32 v45, 1.0, v45
	v_rcp_f32_e32 v44, v44
	v_rcp_f32_e32 v45, v45
	s_nop 0
	v_pk_mul_f32 v[42:43], v[42:43], v[44:45]
	s_nop 0
	v_cvt_pk_bf16_f32 v39, v42, v43
	global_store_dwordx4 v[40:41], v[36:39], off nt
	s_and_saveexec_b64 s[0:1], s[38:39]
	s_cbranch_execz .LBB0_285
	v_readlane_b32 s2, v252, 54
	v_readlane_b32 s3, v252, 55
	v_mad_u64_u32 v[40:41], s[20:21], v128, 6, v[186:187]
	s_nop 0
	v_mov_b64_e32 v[42:43], s[2:3]
	v_mad_i64_i32 v[40:41], s[20:21], v40, s68, v[42:43]
	v_cvt_pk_bf16_f32 v36, v32, v33
	v_cvt_pk_bf16_f32 v37, v34, v35
	v_cvt_pk_bf16_f32 v38, v28, v29
	v_cvt_pk_bf16_f32 v39, v30, v31
	v_lshl_add_u64 v[40:41], v[204:205], 1, v[40:41]
	global_store_dwordx4 v[40:41], v[36:39], off offset:256 nt
.LBB0_285:
	s_or_b64 exec, exec, s[0:1]
	s_nop 0
	v_mov_b32_dpp v36, v32 row_ror:1 row_mask:0xf bank_mask:0xf
	v_mov_b32_dpp v37, v33 row_ror:1 row_mask:0xf bank_mask:0xf
	v_mov_b32_dpp v38, v32 row_ror:2 row_mask:0xf bank_mask:0xf
	v_mov_b32_dpp v36, v24 row_shr:1 row_mask:0xf bank_mask:0xf
	v_mov_b32_dpp v37, v25 row_shr:1 row_mask:0xf bank_mask:0xf
	v_mov_b32_dpp v39, v33 row_ror:2 row_mask:0xf bank_mask:0xf
	v_pk_fma_f32 v[42:43], v[24:25], v[104:105], v[100:101]
	v_mov_b32_dpp v38, v24 row_shr:2 row_mask:0xf bank_mask:0xf
	v_mov_b32_dpp v32, v32 row_ror:3 row_mask:0xf bank_mask:0xf
	v_mov_b32_dpp v39, v25 row_shr:2 row_mask:0xf bank_mask:0xf
	v_mov_b32_dpp v33, v33 row_ror:3 row_mask:0xf bank_mask:0xf
	v_pk_fma_f32 v[36:37], v[96:97], v[36:37], v[42:43]
	v_mov_b32_dpp v32, v24 row_shr:3 row_mask:0xf bank_mask:0xf
	v_mov_b32_dpp v33, v25 row_shr:3 row_mask:0xf bank_mask:0xf
	v_pk_fma_f32 v[36:37], v[92:93], v[38:39], v[36:37]
	v_pk_fma_f32 v[40:41], v[26:27], v[106:107], v[102:103]
	v_pk_fma_f32 v[32:33], v[84:85], v[32:33], v[36:37]
	v_mov_b32_dpp v38, v34 row_ror:2 row_mask:0xf bank_mask:0xf
	v_mul_f32_e32 v2, 0xbfb8aa3b, v32
	v_exp_f32_e32 v2, v2
	v_mov_b32_dpp v39, v35 row_ror:2 row_mask:0xf bank_mask:0xf
	v_mov_b32_dpp v38, v26 row_shr:2 row_mask:0xf bank_mask:0xf
	v_pk_fma_f32 v[42:43], v[20:21], v[88:89], v[80:81]
	v_add_f32_e32 v2, 1.0, v2
	v_rcp_f32_e32 v36, v2
	v_mul_f32_e32 v2, 0xbfb8aa3b, v33
	v_exp_f32_e32 v2, v2
	v_mov_b32_dpp v39, v27 row_shr:2 row_mask:0xf bank_mask:0xf
	v_add_f32_e32 v2, 1.0, v2
	v_rcp_f32_e32 v37, v2
	s_nop 0
	v_pk_mul_f32 v[32:33], v[32:33], v[36:37]
	v_mov_b32_dpp v36, v34 row_ror:1 row_mask:0xf bank_mask:0xf
	v_mov_b32_dpp v37, v35 row_ror:1 row_mask:0xf bank_mask:0xf
	v_mov_b32_dpp v34, v34 row_ror:3 row_mask:0xf bank_mask:0xf
	v_mov_b32_dpp v36, v26 row_shr:1 row_mask:0xf bank_mask:0xf
	v_mov_b32_dpp v37, v27 row_shr:1 row_mask:0xf bank_mask:0xf
	v_mov_b32_dpp v35, v35 row_ror:3 row_mask:0xf bank_mask:0xf
	v_pk_fma_f32 v[36:37], v[98:99], v[36:37], v[40:41]
	v_mov_b32_dpp v34, v26 row_shr:3 row_mask:0xf bank_mask:0xf
	v_mov_b32_dpp v35, v27 row_shr:3 row_mask:0xf bank_mask:0xf
	v_pk_fma_f32 v[36:37], v[94:95], v[38:39], v[36:37]
	v_mov_b32_dpp v38, v28 row_ror:2 row_mask:0xf bank_mask:0xf
	v_pk_fma_f32 v[34:35], v[86:87], v[34:35], v[36:37]
	v_mov_b32_dpp v39, v29 row_ror:2 row_mask:0xf bank_mask:0xf
	v_mul_f32_e32 v2, 0xbfb8aa3b, v34
	v_exp_f32_e32 v2, v2
	v_mov_b32_dpp v38, v20 row_shr:2 row_mask:0xf bank_mask:0xf
	v_mov_b32_dpp v39, v21 row_shr:2 row_mask:0xf bank_mask:0xf
	v_pk_fma_f32 v[40:41], v[22:23], v[90:91], v[82:83]
	v_add_f32_e32 v2, 1.0, v2
	v_rcp_f32_e32 v36, v2
	v_mul_f32_e32 v2, 0xbfb8aa3b, v35
	v_exp_f32_e32 v2, v2
	s_nop 0
	v_add_f32_e32 v2, 1.0, v2
	v_rcp_f32_e32 v37, v2
	s_nop 0
	v_pk_mul_f32 v[34:35], v[34:35], v[36:37]
	v_mov_b32_dpp v36, v28 row_ror:1 row_mask:0xf bank_mask:0xf
	v_mov_b32_dpp v37, v29 row_ror:1 row_mask:0xf bank_mask:0xf
	v_mov_b32_dpp v28, v28 row_ror:3 row_mask:0xf bank_mask:0xf
	v_mov_b32_dpp v36, v20 row_shr:1 row_mask:0xf bank_mask:0xf
	v_mov_b32_dpp v37, v21 row_shr:1 row_mask:0xf bank_mask:0xf
	v_mov_b32_dpp v29, v29 row_ror:3 row_mask:0xf bank_mask:0xf
	v_pk_fma_f32 v[36:37], v[76:77], v[36:37], v[42:43]
	v_mov_b32_dpp v28, v20 row_shr:3 row_mask:0xf bank_mask:0xf
	v_mov_b32_dpp v29, v21 row_shr:3 row_mask:0xf bank_mask:0xf
	v_pk_fma_f32 v[36:37], v[72:73], v[38:39], v[36:37]
	v_mov_b32_dpp v38, v30 row_ror:2 row_mask:0xf bank_mask:0xf
	v_pk_fma_f32 v[28:29], v[68:69], v[28:29], v[36:37]
	v_mov_b32_dpp v39, v31 row_ror:2 row_mask:0xf bank_mask:0xf
	v_mul_f32_e32 v2, 0xbfb8aa3b, v28
	v_exp_f32_e32 v2, v2
	v_mov_b32_dpp v38, v22 row_shr:2 row_mask:0xf bank_mask:0xf
	v_mov_b32_dpp v39, v23 row_shr:2 row_mask:0xf bank_mask:0xf
	v_add_f32_e32 v2, 1.0, v2
	v_rcp_f32_e32 v36, v2
	v_mul_f32_e32 v2, 0xbfb8aa3b, v29
	v_exp_f32_e32 v2, v2
	s_nop 0
	v_add_f32_e32 v2, 1.0, v2
	v_rcp_f32_e32 v37, v2
	s_nop 0
	v_pk_mul_f32 v[36:37], v[28:29], v[36:37]
	v_mov_b32_dpp v28, v30 row_ror:1 row_mask:0xf bank_mask:0xf
	v_mov_b32_dpp v29, v31 row_ror:1 row_mask:0xf bank_mask:0xf
	v_mov_b32_dpp v30, v30 row_ror:3 row_mask:0xf bank_mask:0xf
	v_mov_b32_dpp v28, v22 row_shr:1 row_mask:0xf bank_mask:0xf
	v_mov_b32_dpp v29, v23 row_shr:1 row_mask:0xf bank_mask:0xf
	v_mov_b32_dpp v31, v31 row_ror:3 row_mask:0xf bank_mask:0xf
	v_pk_fma_f32 v[28:29], v[78:79], v[28:29], v[40:41]
	v_mov_b32_dpp v30, v22 row_shr:3 row_mask:0xf bank_mask:0xf
	v_mov_b32_dpp v31, v23 row_shr:3 row_mask:0xf bank_mask:0xf
	v_pk_fma_f32 v[28:29], v[74:75], v[38:39], v[28:29]
	s_nop 0
	v_pk_fma_f32 v[28:29], v[70:71], v[30:31], v[28:29]
	s_nop 0
	v_mul_f32_e32 v2, 0xbfb8aa3b, v28
	v_exp_f32_e32 v2, v2
	s_nop 0
	v_add_f32_e32 v2, 1.0, v2
	v_rcp_f32_e32 v30, v2
	v_mul_f32_e32 v2, 0xbfb8aa3b, v29
	v_exp_f32_e32 v2, v2
	s_nop 0
	v_add_f32_e32 v2, 1.0, v2
	v_rcp_f32_e32 v31, v2
	s_nop 0
	v_pk_mul_f32 v[38:39], v[28:29], v[30:31]
	v_cvt_pk_bf16_f32 v28, v32, v33
	v_cvt_pk_bf16_f32 v29, v34, v35
	v_cvt_pk_bf16_f32 v30, v36, v37
	v_cvt_pk_bf16_f32 v31, v38, v39
	v_lshl_add_u64 v[32:33], v[118:119], 0, v[60:61]
	global_store_dwordx4 v[32:33], v[28:31], off nt
	v_pk_fma_f32 v[34:35], v[16:17], v[104:105], v[100:101]
	v_pk_fma_f32 v[32:33], v[18:19], v[106:107], v[102:103]
	v_mov_b32_dpp v28, v24 row_ror:1 row_mask:0xf bank_mask:0xf
	v_mov_b32_dpp v29, v25 row_ror:1 row_mask:0xf bank_mask:0xf
	v_mov_b32_dpp v30, v24 row_ror:2 row_mask:0xf bank_mask:0xf
	v_mov_b32_dpp v28, v16 row_shr:1 row_mask:0xf bank_mask:0xf
	v_mov_b32_dpp v29, v17 row_shr:1 row_mask:0xf bank_mask:0xf
	v_mov_b32_dpp v31, v25 row_ror:2 row_mask:0xf bank_mask:0xf
	v_mov_b32_dpp v30, v16 row_shr:2 row_mask:0xf bank_mask:0xf
	v_mov_b32_dpp v24, v24 row_ror:3 row_mask:0xf bank_mask:0xf
	v_mov_b32_dpp v31, v17 row_shr:2 row_mask:0xf bank_mask:0xf
	v_mov_b32_dpp v25, v25 row_ror:3 row_mask:0xf bank_mask:0xf
	v_pk_fma_f32 v[28:29], v[96:97], v[28:29], v[34:35]
	v_mov_b32_dpp v24, v16 row_shr:3 row_mask:0xf bank_mask:0xf
	v_mov_b32_dpp v25, v17 row_shr:3 row_mask:0xf bank_mask:0xf
	v_pk_fma_f32 v[28:29], v[92:93], v[30:31], v[28:29]
	v_mov_b32_dpp v30, v26 row_ror:2 row_mask:0xf bank_mask:0xf
	v_pk_fma_f32 v[24:25], v[84:85], v[24:25], v[28:29]
	v_mov_b32_dpp v31, v27 row_ror:2 row_mask:0xf bank_mask:0xf
	v_mul_f32_e32 v2, 0xbfb8aa3b, v24
	v_exp_f32_e32 v2, v2
	v_mov_b32_dpp v30, v18 row_shr:2 row_mask:0xf bank_mask:0xf
	v_mov_b32_dpp v31, v19 row_shr:2 row_mask:0xf bank_mask:0xf
	v_pk_fma_f32 v[34:35], v[12:13], v[88:89], v[80:81]
	v_add_f32_e32 v2, 1.0, v2
	v_rcp_f32_e32 v28, v2
	v_mul_f32_e32 v2, 0xbfb8aa3b, v25
	v_exp_f32_e32 v2, v2
	s_nop 0
	v_add_f32_e32 v2, 1.0, v2
	v_rcp_f32_e32 v29, v2
	s_nop 0
	v_pk_mul_f32 v[24:25], v[24:25], v[28:29]
	v_mov_b32_dpp v28, v26 row_ror:1 row_mask:0xf bank_mask:0xf
	v_mov_b32_dpp v29, v27 row_ror:1 row_mask:0xf bank_mask:0xf
	v_mov_b32_dpp v26, v26 row_ror:3 row_mask:0xf bank_mask:0xf
	v_mov_b32_dpp v28, v18 row_shr:1 row_mask:0xf bank_mask:0xf
	v_mov_b32_dpp v29, v19 row_shr:1 row_mask:0xf bank_mask:0xf
	v_mov_b32_dpp v27, v27 row_ror:3 row_mask:0xf bank_mask:0xf
	v_pk_fma_f32 v[28:29], v[98:99], v[28:29], v[32:33]
	v_mov_b32_dpp v26, v18 row_shr:3 row_mask:0xf bank_mask:0xf
	v_mov_b32_dpp v27, v19 row_shr:3 row_mask:0xf bank_mask:0xf
	v_pk_fma_f32 v[28:29], v[94:95], v[30:31], v[28:29]
	v_mov_b32_dpp v30, v20 row_ror:2 row_mask:0xf bank_mask:0xf
	v_pk_fma_f32 v[26:27], v[86:87], v[26:27], v[28:29]
	v_mov_b32_dpp v31, v21 row_ror:2 row_mask:0xf bank_mask:0xf
	v_mul_f32_e32 v2, 0xbfb8aa3b, v26
	v_exp_f32_e32 v2, v2
	v_mov_b32_dpp v30, v12 row_shr:2 row_mask:0xf bank_mask:0xf
	v_mov_b32_dpp v31, v13 row_shr:2 row_mask:0xf bank_mask:0xf
	v_pk_fma_f32 v[32:33], v[14:15], v[90:91], v[82:83]
	v_add_f32_e32 v2, 1.0, v2
	v_rcp_f32_e32 v28, v2
	v_mul_f32_e32 v2, 0xbfb8aa3b, v27
	v_exp_f32_e32 v2, v2
	s_nop 0
	v_add_f32_e32 v2, 1.0, v2
	v_rcp_f32_e32 v29, v2
	s_nop 0
	v_pk_mul_f32 v[26:27], v[26:27], v[28:29]
	v_mov_b32_dpp v28, v20 row_ror:1 row_mask:0xf bank_mask:0xf
	v_mov_b32_dpp v29, v21 row_ror:1 row_mask:0xf bank_mask:0xf
	v_mov_b32_dpp v20, v20 row_ror:3 row_mask:0xf bank_mask:0xf
	v_mov_b32_dpp v28, v12 row_shr:1 row_mask:0xf bank_mask:0xf
	v_mov_b32_dpp v29, v13 row_shr:1 row_mask:0xf bank_mask:0xf
	v_mov_b32_dpp v21, v21 row_ror:3 row_mask:0xf bank_mask:0xf
	v_pk_fma_f32 v[28:29], v[76:77], v[28:29], v[34:35]
	v_mov_b32_dpp v20, v12 row_shr:3 row_mask:0xf bank_mask:0xf
	v_mov_b32_dpp v21, v13 row_shr:3 row_mask:0xf bank_mask:0xf
	v_pk_fma_f32 v[28:29], v[72:73], v[30:31], v[28:29]
	v_mov_b32_dpp v30, v22 row_ror:2 row_mask:0xf bank_mask:0xf
	v_pk_fma_f32 v[20:21], v[68:69], v[20:21], v[28:29]
	v_mov_b32_dpp v31, v23 row_ror:2 row_mask:0xf bank_mask:0xf
	v_mul_f32_e32 v2, 0xbfb8aa3b, v20
	v_exp_f32_e32 v2, v2
	v_mov_b32_dpp v30, v14 row_shr:2 row_mask:0xf bank_mask:0xf
	v_mov_b32_dpp v31, v15 row_shr:2 row_mask:0xf bank_mask:0xf
	v_add_f32_e32 v2, 1.0, v2
	v_rcp_f32_e32 v28, v2
	v_mul_f32_e32 v2, 0xbfb8aa3b, v21
	v_exp_f32_e32 v2, v2
	s_nop 0
	v_add_f32_e32 v2, 1.0, v2
	v_rcp_f32_e32 v29, v2
	s_nop 0
	v_pk_mul_f32 v[28:29], v[20:21], v[28:29]
	v_mov_b32_dpp v20, v22 row_ror:1 row_mask:0xf bank_mask:0xf
	v_mov_b32_dpp v21, v23 row_ror:1 row_mask:0xf bank_mask:0xf
	v_mov_b32_dpp v22, v22 row_ror:3 row_mask:0xf bank_mask:0xf
	v_mov_b32_dpp v20, v14 row_shr:1 row_mask:0xf bank_mask:0xf
	v_mov_b32_dpp v21, v15 row_shr:1 row_mask:0xf bank_mask:0xf
	v_mov_b32_dpp v23, v23 row_ror:3 row_mask:0xf bank_mask:0xf
	v_pk_fma_f32 v[20:21], v[78:79], v[20:21], v[32:33]
	v_mov_b32_dpp v22, v14 row_shr:3 row_mask:0xf bank_mask:0xf
	v_mov_b32_dpp v23, v15 row_shr:3 row_mask:0xf bank_mask:0xf
	v_pk_fma_f32 v[20:21], v[74:75], v[30:31], v[20:21]
	s_nop 0
	v_pk_fma_f32 v[20:21], v[70:71], v[22:23], v[20:21]
	s_nop 0
	v_mul_f32_e32 v2, 0xbfb8aa3b, v20
	v_exp_f32_e32 v2, v2
	s_nop 0
	v_add_f32_e32 v2, 1.0, v2
	v_rcp_f32_e32 v22, v2
	v_mul_f32_e32 v2, 0xbfb8aa3b, v21
	v_exp_f32_e32 v2, v2
	s_nop 0
	v_add_f32_e32 v2, 1.0, v2
	v_rcp_f32_e32 v23, v2
	s_nop 0
	v_pk_mul_f32 v[30:31], v[20:21], v[22:23]
	v_cvt_pk_bf16_f32 v20, v24, v25
	v_cvt_pk_bf16_f32 v21, v26, v27
	v_cvt_pk_bf16_f32 v22, v28, v29
	v_cvt_pk_bf16_f32 v23, v30, v31
	v_lshl_add_u64 v[24:25], v[120:121], 0, v[60:61]
	global_store_dwordx4 v[24:25], v[20:23], off nt
	v_pk_fma_f32 v[26:27], v[8:9], v[104:105], v[100:101]
	v_pk_fma_f32 v[24:25], v[10:11], v[106:107], v[102:103]
	v_mov_b32_dpp v20, v16 row_ror:1 row_mask:0xf bank_mask:0xf
	v_mov_b32_dpp v21, v17 row_ror:1 row_mask:0xf bank_mask:0xf
	v_mov_b32_dpp v22, v16 row_ror:2 row_mask:0xf bank_mask:0xf
	v_mov_b32_dpp v20, v8 row_shr:1 row_mask:0xf bank_mask:0xf
	v_mov_b32_dpp v21, v9 row_shr:1 row_mask:0xf bank_mask:0xf
	v_mov_b32_dpp v23, v17 row_ror:2 row_mask:0xf bank_mask:0xf
	v_mov_b32_dpp v22, v8 row_shr:2 row_mask:0xf bank_mask:0xf
	v_mov_b32_dpp v16, v16 row_ror:3 row_mask:0xf bank_mask:0xf
	v_mov_b32_dpp v23, v9 row_shr:2 row_mask:0xf bank_mask:0xf
	v_mov_b32_dpp v17, v17 row_ror:3 row_mask:0xf bank_mask:0xf
	v_pk_fma_f32 v[20:21], v[96:97], v[20:21], v[26:27]
	v_mov_b32_dpp v16, v8 row_shr:3 row_mask:0xf bank_mask:0xf
	v_mov_b32_dpp v17, v9 row_shr:3 row_mask:0xf bank_mask:0xf
	v_pk_fma_f32 v[20:21], v[92:93], v[22:23], v[20:21]
	v_mov_b32_dpp v22, v18 row_ror:2 row_mask:0xf bank_mask:0xf
	v_pk_fma_f32 v[16:17], v[84:85], v[16:17], v[20:21]
	v_mov_b32_dpp v23, v19 row_ror:2 row_mask:0xf bank_mask:0xf
	v_mul_f32_e32 v2, 0xbfb8aa3b, v16
	v_exp_f32_e32 v2, v2
	v_mov_b32_dpp v22, v10 row_shr:2 row_mask:0xf bank_mask:0xf
	v_mov_b32_dpp v23, v11 row_shr:2 row_mask:0xf bank_mask:0xf
	v_pk_fma_f32 v[26:27], v[4:5], v[88:89], v[80:81]
	v_add_f32_e32 v2, 1.0, v2
	v_rcp_f32_e32 v20, v2
	v_mul_f32_e32 v2, 0xbfb8aa3b, v17
	v_exp_f32_e32 v2, v2
	s_nop 0
	v_add_f32_e32 v2, 1.0, v2
	v_rcp_f32_e32 v21, v2
	s_nop 0
	v_pk_mul_f32 v[16:17], v[16:17], v[20:21]
	v_mov_b32_dpp v20, v18 row_ror:1 row_mask:0xf bank_mask:0xf
	v_mov_b32_dpp v21, v19 row_ror:1 row_mask:0xf bank_mask:0xf
	v_mov_b32_dpp v18, v18 row_ror:3 row_mask:0xf bank_mask:0xf
	v_mov_b32_dpp v20, v10 row_shr:1 row_mask:0xf bank_mask:0xf
	v_mov_b32_dpp v21, v11 row_shr:1 row_mask:0xf bank_mask:0xf
	v_mov_b32_dpp v19, v19 row_ror:3 row_mask:0xf bank_mask:0xf
	v_pk_fma_f32 v[20:21], v[98:99], v[20:21], v[24:25]
	v_mov_b32_dpp v18, v10 row_shr:3 row_mask:0xf bank_mask:0xf
	v_mov_b32_dpp v19, v11 row_shr:3 row_mask:0xf bank_mask:0xf
	v_pk_fma_f32 v[20:21], v[94:95], v[22:23], v[20:21]
	v_mov_b32_dpp v22, v12 row_ror:2 row_mask:0xf bank_mask:0xf
	v_pk_fma_f32 v[18:19], v[86:87], v[18:19], v[20:21]
	v_mov_b32_dpp v23, v13 row_ror:2 row_mask:0xf bank_mask:0xf
	v_mul_f32_e32 v2, 0xbfb8aa3b, v18
	v_exp_f32_e32 v2, v2
	v_mov_b32_dpp v22, v4 row_shr:2 row_mask:0xf bank_mask:0xf
	v_mov_b32_dpp v23, v5 row_shr:2 row_mask:0xf bank_mask:0xf
	v_pk_fma_f32 v[24:25], v[6:7], v[90:91], v[82:83]
	v_add_f32_e32 v2, 1.0, v2
	v_rcp_f32_e32 v20, v2
	v_mul_f32_e32 v2, 0xbfb8aa3b, v19
	v_exp_f32_e32 v2, v2
	s_nop 0
	v_add_f32_e32 v2, 1.0, v2
	v_rcp_f32_e32 v21, v2
	s_nop 0
	v_pk_mul_f32 v[18:19], v[18:19], v[20:21]
	v_mov_b32_dpp v20, v12 row_ror:1 row_mask:0xf bank_mask:0xf
	v_mov_b32_dpp v21, v13 row_ror:1 row_mask:0xf bank_mask:0xf
	v_mov_b32_dpp v12, v12 row_ror:3 row_mask:0xf bank_mask:0xf
	v_mov_b32_dpp v20, v4 row_shr:1 row_mask:0xf bank_mask:0xf
	v_mov_b32_dpp v21, v5 row_shr:1 row_mask:0xf bank_mask:0xf
	v_mov_b32_dpp v13, v13 row_ror:3 row_mask:0xf bank_mask:0xf
	v_pk_fma_f32 v[20:21], v[76:77], v[20:21], v[26:27]
	v_mov_b32_dpp v12, v4 row_shr:3 row_mask:0xf bank_mask:0xf
	v_mov_b32_dpp v13, v5 row_shr:3 row_mask:0xf bank_mask:0xf
	v_pk_fma_f32 v[20:21], v[72:73], v[22:23], v[20:21]
	v_mov_b32_dpp v22, v14 row_ror:2 row_mask:0xf bank_mask:0xf
	v_pk_fma_f32 v[12:13], v[68:69], v[12:13], v[20:21]
	v_mov_b32_dpp v23, v15 row_ror:2 row_mask:0xf bank_mask:0xf
	v_mul_f32_e32 v2, 0xbfb8aa3b, v12
	v_exp_f32_e32 v2, v2
	v_mov_b32_dpp v22, v6 row_shr:2 row_mask:0xf bank_mask:0xf
	v_mov_b32_dpp v23, v7 row_shr:2 row_mask:0xf bank_mask:0xf
	v_add_f32_e32 v2, 1.0, v2
	v_rcp_f32_e32 v20, v2
	v_mul_f32_e32 v2, 0xbfb8aa3b, v13
	v_exp_f32_e32 v2, v2
	s_nop 0
	v_add_f32_e32 v2, 1.0, v2
	v_rcp_f32_e32 v21, v2
	s_nop 0
	v_pk_mul_f32 v[20:21], v[12:13], v[20:21]
	v_mov_b32_dpp v12, v14 row_ror:1 row_mask:0xf bank_mask:0xf
	v_mov_b32_dpp v13, v15 row_ror:1 row_mask:0xf bank_mask:0xf
	v_mov_b32_dpp v14, v14 row_ror:3 row_mask:0xf bank_mask:0xf
	v_mov_b32_dpp v12, v6 row_shr:1 row_mask:0xf bank_mask:0xf
	v_mov_b32_dpp v13, v7 row_shr:1 row_mask:0xf bank_mask:0xf
	v_mov_b32_dpp v15, v15 row_ror:3 row_mask:0xf bank_mask:0xf
	v_pk_fma_f32 v[12:13], v[78:79], v[12:13], v[24:25]
	v_mov_b32_dpp v14, v6 row_shr:3 row_mask:0xf bank_mask:0xf
	v_mov_b32_dpp v15, v7 row_shr:3 row_mask:0xf bank_mask:0xf
	v_pk_fma_f32 v[12:13], v[74:75], v[22:23], v[12:13]
	s_nop 0
	v_pk_fma_f32 v[12:13], v[70:71], v[14:15], v[12:13]
	s_nop 0
	v_mul_f32_e32 v2, 0xbfb8aa3b, v12
	v_exp_f32_e32 v2, v2
	s_nop 0
	v_add_f32_e32 v2, 1.0, v2
	v_rcp_f32_e32 v14, v2
	v_mul_f32_e32 v2, 0xbfb8aa3b, v13
	v_exp_f32_e32 v2, v2
	s_nop 0
	v_add_f32_e32 v2, 1.0, v2
	v_rcp_f32_e32 v15, v2
	s_nop 0
	v_pk_mul_f32 v[22:23], v[12:13], v[14:15]
	v_cvt_pk_bf16_f32 v12, v16, v17
	v_cvt_pk_bf16_f32 v13, v18, v19
	v_cvt_pk_bf16_f32 v14, v20, v21
	v_cvt_pk_bf16_f32 v15, v22, v23
	v_lshl_add_u64 v[16:17], v[122:123], 0, v[60:61]
	global_store_dwordx4 v[16:17], v[12:15], off nt
	s_and_saveexec_b64 s[0:1], s[40:41]
	s_cbranch_execz .LBB0_233
	v_readlane_b32 s2, v252, 54
	v_readlane_b32 s3, v252, 55
	v_cvt_pk_bf16_f32 v8, v8, v9
	v_cvt_pk_bf16_f32 v9, v10, v11
	v_cvt_pk_bf16_f32 v10, v4, v5
	v_cvt_pk_bf16_f32 v11, v6, v7
	v_mad_u64_u32 v[4:5], s[20:21], v126, 6, v[184:185]
	v_mov_b64_e32 v[6:7], s[2:3]
	v_mad_i64_i32 v[4:5], s[20:21], v4, s68, v[6:7]
	v_lshl_add_u64 v[4:5], v[204:205], 1, v[4:5]
	global_store_dwordx4 v[4:5], v[8:11], off offset:256 nt
	s_branch .LBB0_233

.LBB0_289:
	v_add_u32_e32 v132, s53, v219
	v_ashrrev_i32_e32 v133, 31, v132
	v_lshlrev_b64 v[140:141], 7, v[132:133]
	global_load_dwordx4 v[132:135], v[188:189], off offset:16
	global_load_dwordx4 v[136:139], v[188:189], off
	s_mov_b32 s3, 0xbfb8aa3b
	s_mov_b32 s2, 0x800000
	s_mov_b32 s5, 0x3f317217
	s_mov_b32 s6, 0x7f800000
	s_waitcnt vmcnt(0)
	v_add_f32_e32 v143, v116, v132
	v_add_f32_e32 v136, v120, v136
	v_mul_f32_e64 v132, |v136|, s3
	v_exp_f32_e32 v132, v132
	v_max_f32_e32 v142, 0, v136
	v_add_f32_e32 v137, v121, v137
	v_add_f32_e32 v146, v117, v133
	v_add_f32_e32 v132, 1.0, v132
	v_cmp_gt_f32_e32 vcc, s2, v132
	v_mul_f32_e64 v133, |v137|, s3
	v_exp_f32_e32 v133, v133
	v_cndmask_b32_e64 v136, 0, 32, vcc
	v_ldexp_f32 v132, v132, v136
	v_log_f32_e32 v132, v132
	v_add_f32_e32 v133, 1.0, v133
	v_add_f32_e32 v147, v118, v134
	v_add_f32_e32 v149, v119, v135
	v_mul_f32_e32 v136, 0x3f317217, v132
	v_fma_f32 v136, v132, s5, -v136
	v_fmac_f32_e32 v136, 0x3377d1cf, v132
	v_fmac_f32_e32 v136, 0x3f317217, v132
	v_cmp_lt_f32_e64 s[0:1], |v132|, s6
	s_nop 1
	v_cndmask_b32_e64 v132, v132, v136, s[0:1]
	v_cndmask_b32_e32 v136, 0, v228, vcc
	v_sub_f32_e32 v144, v132, v136
	v_mul_f32_e64 v136, |v143|, s3
	v_exp_f32_e32 v136, v136
	v_max_f32_e32 v132, 0, v143
	v_add_f32_e32 v136, 1.0, v136
	v_cmp_gt_f32_e32 vcc, s2, v136
	s_nop 1
	v_cndmask_b32_e64 v143, 0, 32, vcc
	v_ldexp_f32 v136, v136, v143
	v_log_f32_e32 v136, v136
	s_nop 0
	v_mul_f32_e32 v143, 0x3f317217, v136
	v_fma_f32 v143, v136, s5, -v143
	v_fmac_f32_e32 v143, 0x3377d1cf, v136
	v_fmac_f32_e32 v143, 0x3f317217, v136
	v_cmp_lt_f32_e64 s[0:1], |v136|, s6
	s_nop 1
	v_cndmask_b32_e64 v136, v136, v143, s[0:1]
	v_cndmask_b32_e32 v143, 0, v228, vcc
	v_cmp_gt_f32_e32 vcc, s2, v133
	v_sub_f32_e32 v136, v136, v143
	v_max_f32_e32 v143, 0, v137
	v_cndmask_b32_e64 v137, 0, 32, vcc
	v_ldexp_f32 v133, v133, v137
	v_log_f32_e32 v133, v133
	s_nop 0
	v_mul_f32_e32 v137, 0x3f317217, v133
	v_fma_f32 v137, v133, s5, -v137
	v_fmac_f32_e32 v137, 0x3377d1cf, v133
	v_fmac_f32_e32 v137, 0x3f317217, v133
	v_cmp_lt_f32_e64 s[0:1], |v133|, s6
	s_nop 1
	v_cndmask_b32_e64 v133, v133, v137, s[0:1]
	v_cndmask_b32_e32 v137, 0, v228, vcc
	v_sub_f32_e32 v145, v133, v137
	v_mul_f32_e64 v137, |v146|, s3
	v_exp_f32_e32 v137, v137
	v_max_f32_e32 v133, 0, v146
	v_pk_add_f32 v[142:143], v[142:143], v[144:145]
	v_add_f32_e32 v137, 1.0, v137
	v_cmp_gt_f32_e32 vcc, s2, v137
	s_nop 1
	v_cndmask_b32_e64 v146, 0, 32, vcc
	v_ldexp_f32 v137, v137, v146
	v_log_f32_e32 v137, v137
	s_nop 0
	v_mul_f32_e32 v146, 0x3f317217, v137
	v_fma_f32 v146, v137, s5, -v146
	v_fmac_f32_e32 v146, 0x3377d1cf, v137
	v_fmac_f32_e32 v146, 0x3f317217, v137
	v_cmp_lt_f32_e64 s[0:1], |v137|, s6
	s_nop 1
	v_cndmask_b32_e64 v137, v137, v146, s[0:1]
	v_cndmask_b32_e32 v146, 0, v228, vcc
	v_sub_f32_e32 v137, v137, v146
	v_add_f32_e32 v146, v122, v138
	v_mul_f32_e64 v134, |v146|, s3
	v_exp_f32_e32 v134, v134
	v_max_f32_e32 v138, 0, v146
	v_pk_add_f32 v[132:133], v[132:133], v[136:137]
	v_lshl_add_u64 v[136:137], v[190:191], 0, v[140:141]
	v_add_f32_e32 v134, 1.0, v134
	v_cmp_gt_f32_e32 vcc, s2, v134
	s_nop 1
	v_cndmask_b32_e64 v146, 0, 32, vcc
	v_ldexp_f32 v134, v134, v146
	v_log_f32_e32 v134, v134
	s_nop 0
	v_mul_f32_e32 v146, 0x3f317217, v134
	v_fma_f32 v146, v134, s5, -v146
	v_fmac_f32_e32 v146, 0x3377d1cf, v134
	v_fmac_f32_e32 v146, 0x3f317217, v134
	v_cmp_lt_f32_e64 s[0:1], |v134|, s6
	s_nop 1
	v_cndmask_b32_e64 v134, v134, v146, s[0:1]
	v_cndmask_b32_e32 v146, 0, v228, vcc
	v_sub_f32_e32 v146, v134, v146
	v_max_f32_e32 v134, 0, v147
	v_mul_f32_e64 v147, |v147|, s3
	v_exp_f32_e32 v147, v147
	s_nop 0
	v_add_f32_e32 v147, 1.0, v147
	v_cmp_gt_f32_e32 vcc, s2, v147
	s_nop 1
	v_cndmask_b32_e64 v148, 0, 32, vcc
	v_ldexp_f32 v147, v147, v148
	v_log_f32_e32 v147, v147
	s_nop 0
	v_mul_f32_e32 v148, 0x3f317217, v147
	v_fma_f32 v148, v147, s5, -v148
	v_fmac_f32_e32 v148, 0x3377d1cf, v147
	v_fmac_f32_e32 v148, 0x3f317217, v147
	v_cmp_lt_f32_e64 s[0:1], |v147|, s6
	s_nop 1
	v_cndmask_b32_e64 v147, v147, v148, s[0:1]
	v_cndmask_b32_e32 v148, 0, v228, vcc
	v_sub_f32_e32 v148, v147, v148
	v_add_f32_e32 v147, v123, v139
	v_mul_f32_e64 v135, |v147|, s3
	v_exp_f32_e32 v135, v135
	v_max_f32_e32 v139, 0, v147
	v_add_f32_e32 v135, 1.0, v135
	v_cmp_gt_f32_e32 vcc, s2, v135
	s_nop 1
	v_cndmask_b32_e64 v147, 0, 32, vcc
	v_ldexp_f32 v135, v135, v147
	v_log_f32_e32 v135, v135
	s_nop 0
	v_mul_f32_e32 v147, 0x3f317217, v135
	v_fma_f32 v147, v135, s5, -v147
	v_fmac_f32_e32 v147, 0x3377d1cf, v135
	v_fmac_f32_e32 v147, 0x3f317217, v135
	v_cmp_lt_f32_e64 s[0:1], |v135|, s6
	s_nop 1
	v_cndmask_b32_e64 v135, v135, v147, s[0:1]
	v_cndmask_b32_e32 v147, 0, v228, vcc
	v_sub_f32_e32 v147, v135, v147
	v_pk_add_f32 v[144:145], v[138:139], v[146:147]
	v_mul_f32_e64 v138, |v149|, s3
	v_exp_f32_e32 v138, v138
	v_max_f32_e32 v135, 0, v149
	v_add_f32_e32 v138, 1.0, v138
	v_cmp_gt_f32_e32 vcc, s2, v138
	s_nop 1
	v_cndmask_b32_e64 v139, 0, 32, vcc
	v_ldexp_f32 v138, v138, v139
	v_log_f32_e32 v138, v138
	s_nop 0
	v_mul_f32_e32 v139, 0x3f317217, v138
	v_fma_f32 v139, v138, s5, -v139
	v_fmac_f32_e32 v139, 0x3377d1cf, v138
	v_fmac_f32_e32 v139, 0x3f317217, v138
	v_cmp_lt_f32_e64 s[0:1], |v138|, s6
	s_nop 1
	v_cndmask_b32_e64 v138, v138, v139, s[0:1]
	v_cndmask_b32_e32 v139, 0, v228, vcc
	v_sub_f32_e32 v149, v138, v139
	v_pk_add_f32 v[134:135], v[134:135], v[148:149]
	global_store_dwordx4 v[136:137], v[142:145], off nt
	global_store_dwordx4 v[136:137], v[132:135], off offset:16 nt
	s_cbranch_execnz .LBB0_252
.LBB0_290:
	s_nop 0
	v_add_u32_e32 v134, s53, v219
	v_mov_b64_e32 v[132:133], s[96:97]
	v_mad_i64_i32 v[132:133], s[0:1], v134, s29, v[132:133]
	v_lshl_add_u64 v[132:133], s[62:63], 1, v[132:133]
	s_lshl_b32 s72, s49, 1
	v_lshl_add_u64 v[132:133], v[132:133], 0, s[72:73]
	v_lshl_add_u64 v[136:137], v[132:133], 0, v[2:3]
	v_cvt_pk_bf16_f32 v132, v120, v121
	v_cvt_pk_bf16_f32 v133, v122, v123
	v_cvt_pk_bf16_f32 v134, v116, v117
	v_cvt_pk_bf16_f32 v135, v118, v119
	global_store_dwordx4 v[136:137], v[132:135], off nt
	s_nop 1
	v_cvt_pk_bf16_f32 v132, v56, v57
	v_cvt_pk_bf16_f32 v133, v58, v59
	v_cvt_pk_bf16_f32 v134, v52, v53
	v_cvt_pk_bf16_f32 v135, v54, v55
	global_store_dwordx4 v[136:137], v[132:135], off offset:256 nt
	s_and_b64 vcc, exec, s[46:47]
	s_mov_b64 s[0:1], -1
	s_cbranch_vccnz .LBB0_253

.LBB0_293:
	v_add_u32_e32 v132, s53, v221
	v_ashrrev_i32_e32 v133, 31, v132
	v_lshlrev_b64 v[140:141], 7, v[132:133]
	global_load_dwordx4 v[132:135], v[188:189], off offset:16
	global_load_dwordx4 v[136:139], v[188:189], off
	s_mov_b32 s3, 0xbfb8aa3b
	s_mov_b32 s2, 0x800000
	s_mov_b32 s5, 0x3f317217
	s_mov_b32 s6, 0x7f800000
	s_waitcnt vmcnt(0)
	v_add_f32_e32 v143, v108, v132
	v_add_f32_e32 v136, v112, v136
	v_mul_f32_e64 v132, |v136|, s3
	v_exp_f32_e32 v132, v132
	v_max_f32_e32 v142, 0, v136
	v_add_f32_e32 v137, v113, v137
	v_add_f32_e32 v146, v109, v133
	v_add_f32_e32 v132, 1.0, v132
	v_cmp_gt_f32_e32 vcc, s2, v132
	v_mul_f32_e64 v133, |v137|, s3
	v_exp_f32_e32 v133, v133
	v_cndmask_b32_e64 v136, 0, 32, vcc
	v_ldexp_f32 v132, v132, v136
	v_log_f32_e32 v132, v132
	v_add_f32_e32 v133, 1.0, v133
	v_add_f32_e32 v147, v110, v134
	v_add_f32_e32 v149, v111, v135
	v_mul_f32_e32 v136, 0x3f317217, v132
	v_fma_f32 v136, v132, s5, -v136
	v_fmac_f32_e32 v136, 0x3377d1cf, v132
	v_fmac_f32_e32 v136, 0x3f317217, v132
	v_cmp_lt_f32_e64 s[0:1], |v132|, s6
	s_nop 1
	v_cndmask_b32_e64 v132, v132, v136, s[0:1]
	v_cndmask_b32_e32 v136, 0, v228, vcc
	v_sub_f32_e32 v144, v132, v136
	v_mul_f32_e64 v136, |v143|, s3
	v_exp_f32_e32 v136, v136
	v_max_f32_e32 v132, 0, v143
	v_add_f32_e32 v136, 1.0, v136
	v_cmp_gt_f32_e32 vcc, s2, v136
	s_nop 1
	v_cndmask_b32_e64 v143, 0, 32, vcc
	v_ldexp_f32 v136, v136, v143
	v_log_f32_e32 v136, v136
	s_nop 0
	v_mul_f32_e32 v143, 0x3f317217, v136
	v_fma_f32 v143, v136, s5, -v143
	v_fmac_f32_e32 v143, 0x3377d1cf, v136
	v_fmac_f32_e32 v143, 0x3f317217, v136
	v_cmp_lt_f32_e64 s[0:1], |v136|, s6
	s_nop 1
	v_cndmask_b32_e64 v136, v136, v143, s[0:1]
	v_cndmask_b32_e32 v143, 0, v228, vcc
	v_cmp_gt_f32_e32 vcc, s2, v133
	v_sub_f32_e32 v136, v136, v143
	v_max_f32_e32 v143, 0, v137
	v_cndmask_b32_e64 v137, 0, 32, vcc
	v_ldexp_f32 v133, v133, v137
	v_log_f32_e32 v133, v133
	s_nop 0
	v_mul_f32_e32 v137, 0x3f317217, v133
	v_fma_f32 v137, v133, s5, -v137
	v_fmac_f32_e32 v137, 0x3377d1cf, v133
	v_fmac_f32_e32 v137, 0x3f317217, v133
	v_cmp_lt_f32_e64 s[0:1], |v133|, s6
	s_nop 1
	v_cndmask_b32_e64 v133, v133, v137, s[0:1]
	v_cndmask_b32_e32 v137, 0, v228, vcc
	v_sub_f32_e32 v145, v133, v137
	v_mul_f32_e64 v137, |v146|, s3
	v_exp_f32_e32 v137, v137
	v_max_f32_e32 v133, 0, v146
	v_pk_add_f32 v[142:143], v[142:143], v[144:145]
	v_add_f32_e32 v137, 1.0, v137
	v_cmp_gt_f32_e32 vcc, s2, v137
	s_nop 1
	v_cndmask_b32_e64 v146, 0, 32, vcc
	v_ldexp_f32 v137, v137, v146
	v_log_f32_e32 v137, v137
	s_nop 0
	v_mul_f32_e32 v146, 0x3f317217, v137
	v_fma_f32 v146, v137, s5, -v146
	v_fmac_f32_e32 v146, 0x3377d1cf, v137
	v_fmac_f32_e32 v146, 0x3f317217, v137
	v_cmp_lt_f32_e64 s[0:1], |v137|, s6
	s_nop 1
	v_cndmask_b32_e64 v137, v137, v146, s[0:1]
	v_cndmask_b32_e32 v146, 0, v228, vcc
	v_sub_f32_e32 v137, v137, v146
	v_add_f32_e32 v146, v114, v138
	v_mul_f32_e64 v134, |v146|, s3
	v_exp_f32_e32 v134, v134
	v_max_f32_e32 v138, 0, v146
	v_pk_add_f32 v[132:133], v[132:133], v[136:137]
	v_lshl_add_u64 v[136:137], v[190:191], 0, v[140:141]
	v_add_f32_e32 v134, 1.0, v134
	v_cmp_gt_f32_e32 vcc, s2, v134
	s_nop 1
	v_cndmask_b32_e64 v146, 0, 32, vcc
	v_ldexp_f32 v134, v134, v146
	v_log_f32_e32 v134, v134
	s_nop 0
	v_mul_f32_e32 v146, 0x3f317217, v134
	v_fma_f32 v146, v134, s5, -v146
	v_fmac_f32_e32 v146, 0x3377d1cf, v134
	v_fmac_f32_e32 v146, 0x3f317217, v134
	v_cmp_lt_f32_e64 s[0:1], |v134|, s6
	s_nop 1
	v_cndmask_b32_e64 v134, v134, v146, s[0:1]
	v_cndmask_b32_e32 v146, 0, v228, vcc
	v_sub_f32_e32 v146, v134, v146
	v_max_f32_e32 v134, 0, v147
	v_mul_f32_e64 v147, |v147|, s3
	v_exp_f32_e32 v147, v147
	s_nop 0
	v_add_f32_e32 v147, 1.0, v147
	v_cmp_gt_f32_e32 vcc, s2, v147
	s_nop 1
	v_cndmask_b32_e64 v148, 0, 32, vcc
	v_ldexp_f32 v147, v147, v148
	v_log_f32_e32 v147, v147
	s_nop 0
	v_mul_f32_e32 v148, 0x3f317217, v147
	v_fma_f32 v148, v147, s5, -v148
	v_fmac_f32_e32 v148, 0x3377d1cf, v147
	v_fmac_f32_e32 v148, 0x3f317217, v147
	v_cmp_lt_f32_e64 s[0:1], |v147|, s6
	s_nop 1
	v_cndmask_b32_e64 v147, v147, v148, s[0:1]
	v_cndmask_b32_e32 v148, 0, v228, vcc
	v_sub_f32_e32 v148, v147, v148
	v_add_f32_e32 v147, v115, v139
	v_mul_f32_e64 v135, |v147|, s3
	v_exp_f32_e32 v135, v135
	v_max_f32_e32 v139, 0, v147
	v_add_f32_e32 v135, 1.0, v135
	v_cmp_gt_f32_e32 vcc, s2, v135
	s_nop 1
	v_cndmask_b32_e64 v147, 0, 32, vcc
	v_ldexp_f32 v135, v135, v147
	v_log_f32_e32 v135, v135
	s_nop 0
	v_mul_f32_e32 v147, 0x3f317217, v135
	v_fma_f32 v147, v135, s5, -v147
	v_fmac_f32_e32 v147, 0x3377d1cf, v135
	v_fmac_f32_e32 v147, 0x3f317217, v135
	v_cmp_lt_f32_e64 s[0:1], |v135|, s6
	s_nop 1
	v_cndmask_b32_e64 v135, v135, v147, s[0:1]
	v_cndmask_b32_e32 v147, 0, v228, vcc
	v_sub_f32_e32 v147, v135, v147
	v_pk_add_f32 v[144:145], v[138:139], v[146:147]
	v_mul_f32_e64 v138, |v149|, s3
	v_exp_f32_e32 v138, v138
	v_max_f32_e32 v135, 0, v149
	v_add_f32_e32 v138, 1.0, v138
	v_cmp_gt_f32_e32 vcc, s2, v138
	s_nop 1
	v_cndmask_b32_e64 v139, 0, 32, vcc
	v_ldexp_f32 v138, v138, v139
	v_log_f32_e32 v138, v138
	s_nop 0
	v_mul_f32_e32 v139, 0x3f317217, v138
	v_fma_f32 v139, v138, s5, -v139
	v_fmac_f32_e32 v139, 0x3377d1cf, v138
	v_fmac_f32_e32 v139, 0x3f317217, v138
	v_cmp_lt_f32_e64 s[0:1], |v138|, s6
	s_nop 1
	v_cndmask_b32_e64 v138, v138, v139, s[0:1]
	v_cndmask_b32_e32 v139, 0, v228, vcc
	v_sub_f32_e32 v149, v138, v139
	v_pk_add_f32 v[134:135], v[134:135], v[148:149]
	global_store_dwordx4 v[136:137], v[142:145], off nt
	global_store_dwordx4 v[136:137], v[132:135], off offset:16 nt
	s_cbranch_execnz .LBB0_254
.LBB0_294:
	s_nop 0
	v_add_u32_e32 v134, s53, v221
	v_mov_b64_e32 v[132:133], s[96:97]
	v_mad_i64_i32 v[132:133], s[0:1], v134, s29, v[132:133]
	v_lshl_add_u64 v[132:133], s[62:63], 1, v[132:133]
	s_lshl_b32 s72, s49, 1
	v_lshl_add_u64 v[132:133], v[132:133], 0, s[72:73]
	v_lshl_add_u64 v[136:137], v[132:133], 0, v[2:3]
	v_cvt_pk_bf16_f32 v132, v112, v113
	v_cvt_pk_bf16_f32 v133, v114, v115
	v_cvt_pk_bf16_f32 v134, v108, v109
	v_cvt_pk_bf16_f32 v135, v110, v111
	global_store_dwordx4 v[136:137], v[132:135], off nt
	s_nop 1
	v_cvt_pk_bf16_f32 v132, v48, v49
	v_cvt_pk_bf16_f32 v133, v50, v51
	v_cvt_pk_bf16_f32 v134, v44, v45
	v_cvt_pk_bf16_f32 v135, v46, v47
	global_store_dwordx4 v[136:137], v[132:135], off offset:256 nt
	s_and_b64 vcc, exec, s[46:47]
	s_mov_b64 s[0:1], -1
	s_cbranch_vccnz .LBB0_255

.LBB0_297:
	v_add_u32_e32 v132, s53, v235
	v_ashrrev_i32_e32 v133, 31, v132
	v_lshlrev_b64 v[140:141], 7, v[132:133]
	global_load_dwordx4 v[132:135], v[188:189], off offset:16
	global_load_dwordx4 v[136:139], v[188:189], off
	s_mov_b32 s3, 0xbfb8aa3b
	s_mov_b32 s2, 0x800000
	s_mov_b32 s5, 0x3f317217
	s_mov_b32 s6, 0x7f800000
	s_waitcnt vmcnt(0)
	v_add_f32_e32 v143, v100, v132
	v_add_f32_e32 v136, v104, v136
	v_mul_f32_e64 v132, |v136|, s3
	v_exp_f32_e32 v132, v132
	v_max_f32_e32 v142, 0, v136
	v_add_f32_e32 v137, v105, v137
	v_add_f32_e32 v146, v101, v133
	v_add_f32_e32 v132, 1.0, v132
	v_cmp_gt_f32_e32 vcc, s2, v132
	v_mul_f32_e64 v133, |v137|, s3
	v_exp_f32_e32 v133, v133
	v_cndmask_b32_e64 v136, 0, 32, vcc
	v_ldexp_f32 v132, v132, v136
	v_log_f32_e32 v132, v132
	v_add_f32_e32 v133, 1.0, v133
	v_add_f32_e32 v147, v102, v134
	v_add_f32_e32 v149, v103, v135
	v_mul_f32_e32 v136, 0x3f317217, v132
	v_fma_f32 v136, v132, s5, -v136
	v_fmac_f32_e32 v136, 0x3377d1cf, v132
	v_fmac_f32_e32 v136, 0x3f317217, v132
	v_cmp_lt_f32_e64 s[0:1], |v132|, s6
	s_nop 1
	v_cndmask_b32_e64 v132, v132, v136, s[0:1]
	v_cndmask_b32_e32 v136, 0, v228, vcc
	v_sub_f32_e32 v144, v132, v136
	v_mul_f32_e64 v136, |v143|, s3
	v_exp_f32_e32 v136, v136
	v_max_f32_e32 v132, 0, v143
	v_add_f32_e32 v136, 1.0, v136
	v_cmp_gt_f32_e32 vcc, s2, v136
	s_nop 1
	v_cndmask_b32_e64 v143, 0, 32, vcc
	v_ldexp_f32 v136, v136, v143
	v_log_f32_e32 v136, v136
	s_nop 0
	v_mul_f32_e32 v143, 0x3f317217, v136
	v_fma_f32 v143, v136, s5, -v143
	v_fmac_f32_e32 v143, 0x3377d1cf, v136
	v_fmac_f32_e32 v143, 0x3f317217, v136
	v_cmp_lt_f32_e64 s[0:1], |v136|, s6
	s_nop 1
	v_cndmask_b32_e64 v136, v136, v143, s[0:1]
	v_cndmask_b32_e32 v143, 0, v228, vcc
	v_cmp_gt_f32_e32 vcc, s2, v133
	v_sub_f32_e32 v136, v136, v143
	v_max_f32_e32 v143, 0, v137
	v_cndmask_b32_e64 v137, 0, 32, vcc
	v_ldexp_f32 v133, v133, v137
	v_log_f32_e32 v133, v133
	s_nop 0
	v_mul_f32_e32 v137, 0x3f317217, v133
	v_fma_f32 v137, v133, s5, -v137
	v_fmac_f32_e32 v137, 0x3377d1cf, v133
	v_fmac_f32_e32 v137, 0x3f317217, v133
	v_cmp_lt_f32_e64 s[0:1], |v133|, s6
	s_nop 1
	v_cndmask_b32_e64 v133, v133, v137, s[0:1]
	v_cndmask_b32_e32 v137, 0, v228, vcc
	v_sub_f32_e32 v145, v133, v137
	v_mul_f32_e64 v137, |v146|, s3
	v_exp_f32_e32 v137, v137
	v_max_f32_e32 v133, 0, v146
	v_pk_add_f32 v[142:143], v[142:143], v[144:145]
	v_add_f32_e32 v137, 1.0, v137
	v_cmp_gt_f32_e32 vcc, s2, v137
	s_nop 1
	v_cndmask_b32_e64 v146, 0, 32, vcc
	v_ldexp_f32 v137, v137, v146
	v_log_f32_e32 v137, v137
	s_nop 0
	v_mul_f32_e32 v146, 0x3f317217, v137
	v_fma_f32 v146, v137, s5, -v146
	v_fmac_f32_e32 v146, 0x3377d1cf, v137
	v_fmac_f32_e32 v146, 0x3f317217, v137
	v_cmp_lt_f32_e64 s[0:1], |v137|, s6
	s_nop 1
	v_cndmask_b32_e64 v137, v137, v146, s[0:1]
	v_cndmask_b32_e32 v146, 0, v228, vcc
	v_sub_f32_e32 v137, v137, v146
	v_add_f32_e32 v146, v106, v138
	v_mul_f32_e64 v134, |v146|, s3
	v_exp_f32_e32 v134, v134
	v_max_f32_e32 v138, 0, v146
	v_pk_add_f32 v[132:133], v[132:133], v[136:137]
	v_lshl_add_u64 v[136:137], v[190:191], 0, v[140:141]
	v_add_f32_e32 v134, 1.0, v134
	v_cmp_gt_f32_e32 vcc, s2, v134
	s_nop 1
	v_cndmask_b32_e64 v146, 0, 32, vcc
	v_ldexp_f32 v134, v134, v146
	v_log_f32_e32 v134, v134
	s_nop 0
	v_mul_f32_e32 v146, 0x3f317217, v134
	v_fma_f32 v146, v134, s5, -v146
	v_fmac_f32_e32 v146, 0x3377d1cf, v134
	v_fmac_f32_e32 v146, 0x3f317217, v134
	v_cmp_lt_f32_e64 s[0:1], |v134|, s6
	s_nop 1
	v_cndmask_b32_e64 v134, v134, v146, s[0:1]
	v_cndmask_b32_e32 v146, 0, v228, vcc
	v_sub_f32_e32 v146, v134, v146
	v_max_f32_e32 v134, 0, v147
	v_mul_f32_e64 v147, |v147|, s3
	v_exp_f32_e32 v147, v147
	s_nop 0
	v_add_f32_e32 v147, 1.0, v147
	v_cmp_gt_f32_e32 vcc, s2, v147
	s_nop 1
	v_cndmask_b32_e64 v148, 0, 32, vcc
	v_ldexp_f32 v147, v147, v148
	v_log_f32_e32 v147, v147
	s_nop 0
	v_mul_f32_e32 v148, 0x3f317217, v147
	v_fma_f32 v148, v147, s5, -v148
	v_fmac_f32_e32 v148, 0x3377d1cf, v147
	v_fmac_f32_e32 v148, 0x3f317217, v147
	v_cmp_lt_f32_e64 s[0:1], |v147|, s6
	s_nop 1
	v_cndmask_b32_e64 v147, v147, v148, s[0:1]
	v_cndmask_b32_e32 v148, 0, v228, vcc
	v_sub_f32_e32 v148, v147, v148
	v_add_f32_e32 v147, v107, v139
	v_mul_f32_e64 v135, |v147|, s3
	v_exp_f32_e32 v135, v135
	v_max_f32_e32 v139, 0, v147
	v_add_f32_e32 v135, 1.0, v135
	v_cmp_gt_f32_e32 vcc, s2, v135
	s_nop 1
	v_cndmask_b32_e64 v147, 0, 32, vcc
	v_ldexp_f32 v135, v135, v147
	v_log_f32_e32 v135, v135
	s_nop 0
	v_mul_f32_e32 v147, 0x3f317217, v135
	v_fma_f32 v147, v135, s5, -v147
	v_fmac_f32_e32 v147, 0x3377d1cf, v135
	v_fmac_f32_e32 v147, 0x3f317217, v135
	v_cmp_lt_f32_e64 s[0:1], |v135|, s6
	s_nop 1
	v_cndmask_b32_e64 v135, v135, v147, s[0:1]
	v_cndmask_b32_e32 v147, 0, v228, vcc
	v_sub_f32_e32 v147, v135, v147
	v_pk_add_f32 v[144:145], v[138:139], v[146:147]
	v_mul_f32_e64 v138, |v149|, s3
	v_exp_f32_e32 v138, v138
	v_max_f32_e32 v135, 0, v149
	v_add_f32_e32 v138, 1.0, v138
	v_cmp_gt_f32_e32 vcc, s2, v138
	s_nop 1
	v_cndmask_b32_e64 v139, 0, 32, vcc
	v_ldexp_f32 v138, v138, v139
	v_log_f32_e32 v138, v138
	s_nop 0
	v_mul_f32_e32 v139, 0x3f317217, v138
	v_fma_f32 v139, v138, s5, -v139
	v_fmac_f32_e32 v139, 0x3377d1cf, v138
	v_fmac_f32_e32 v139, 0x3f317217, v138
	v_cmp_lt_f32_e64 s[0:1], |v138|, s6
	s_nop 1
	v_cndmask_b32_e64 v138, v138, v139, s[0:1]
	v_cndmask_b32_e32 v139, 0, v228, vcc
	v_sub_f32_e32 v149, v138, v139
	v_pk_add_f32 v[134:135], v[134:135], v[148:149]
	global_store_dwordx4 v[136:137], v[142:145], off nt
	global_store_dwordx4 v[136:137], v[132:135], off offset:16 nt
	s_cbranch_execnz .LBB0_256
.LBB0_298:
	s_nop 0
	v_add_u32_e32 v134, s53, v235
	v_mov_b64_e32 v[132:133], s[96:97]
	v_mad_i64_i32 v[132:133], s[0:1], v134, s29, v[132:133]
	v_lshl_add_u64 v[132:133], s[62:63], 1, v[132:133]
	s_lshl_b32 s72, s49, 1
	v_lshl_add_u64 v[132:133], v[132:133], 0, s[72:73]
	v_lshl_add_u64 v[136:137], v[132:133], 0, v[2:3]
	v_cvt_pk_bf16_f32 v132, v104, v105
	v_cvt_pk_bf16_f32 v133, v106, v107
	v_cvt_pk_bf16_f32 v134, v100, v101
	v_cvt_pk_bf16_f32 v135, v102, v103
	global_store_dwordx4 v[136:137], v[132:135], off nt
	s_nop 1
	v_cvt_pk_bf16_f32 v132, v40, v41
	v_cvt_pk_bf16_f32 v133, v42, v43
	v_cvt_pk_bf16_f32 v134, v36, v37
	v_cvt_pk_bf16_f32 v135, v38, v39
	global_store_dwordx4 v[136:137], v[132:135], off offset:256 nt
	s_and_b64 vcc, exec, s[46:47]
	s_mov_b64 s[0:1], -1
	s_cbranch_vccnz .LBB0_257

.LBB0_301:
	v_add_u32_e32 v132, s53, v224
	v_ashrrev_i32_e32 v133, 31, v132
	v_lshlrev_b64 v[140:141], 7, v[132:133]
	global_load_dwordx4 v[132:135], v[188:189], off offset:16
	global_load_dwordx4 v[136:139], v[188:189], off
	s_mov_b32 s3, 0xbfb8aa3b
	s_mov_b32 s2, 0x800000
	s_mov_b32 s5, 0x3f317217
	s_mov_b32 s6, 0x7f800000
	s_waitcnt vmcnt(0)
	v_add_f32_e32 v143, v92, v132
	v_add_f32_e32 v136, v96, v136
	v_mul_f32_e64 v132, |v136|, s3
	v_exp_f32_e32 v132, v132
	v_max_f32_e32 v142, 0, v136
	v_add_f32_e32 v137, v97, v137
	v_add_f32_e32 v146, v93, v133
	v_add_f32_e32 v132, 1.0, v132
	v_cmp_gt_f32_e32 vcc, s2, v132
	v_mul_f32_e64 v133, |v137|, s3
	v_exp_f32_e32 v133, v133
	v_cndmask_b32_e64 v136, 0, 32, vcc
	v_ldexp_f32 v132, v132, v136
	v_log_f32_e32 v132, v132
	v_add_f32_e32 v133, 1.0, v133
	v_add_f32_e32 v147, v94, v134
	v_add_f32_e32 v149, v95, v135
	v_mul_f32_e32 v136, 0x3f317217, v132
	v_fma_f32 v136, v132, s5, -v136
	v_fmac_f32_e32 v136, 0x3377d1cf, v132
	v_fmac_f32_e32 v136, 0x3f317217, v132
	v_cmp_lt_f32_e64 s[0:1], |v132|, s6
	s_nop 1
	v_cndmask_b32_e64 v132, v132, v136, s[0:1]
	v_cndmask_b32_e32 v136, 0, v228, vcc
	v_sub_f32_e32 v144, v132, v136
	v_mul_f32_e64 v136, |v143|, s3
	v_exp_f32_e32 v136, v136
	v_max_f32_e32 v132, 0, v143
	v_add_f32_e32 v136, 1.0, v136
	v_cmp_gt_f32_e32 vcc, s2, v136
	s_nop 1
	v_cndmask_b32_e64 v143, 0, 32, vcc
	v_ldexp_f32 v136, v136, v143
	v_log_f32_e32 v136, v136
	s_nop 0
	v_mul_f32_e32 v143, 0x3f317217, v136
	v_fma_f32 v143, v136, s5, -v143
	v_fmac_f32_e32 v143, 0x3377d1cf, v136
	v_fmac_f32_e32 v143, 0x3f317217, v136
	v_cmp_lt_f32_e64 s[0:1], |v136|, s6
	s_nop 1
	v_cndmask_b32_e64 v136, v136, v143, s[0:1]
	v_cndmask_b32_e32 v143, 0, v228, vcc
	v_cmp_gt_f32_e32 vcc, s2, v133
	v_sub_f32_e32 v136, v136, v143
	v_max_f32_e32 v143, 0, v137
	v_cndmask_b32_e64 v137, 0, 32, vcc
	v_ldexp_f32 v133, v133, v137
	v_log_f32_e32 v133, v133
	s_nop 0
	v_mul_f32_e32 v137, 0x3f317217, v133
	v_fma_f32 v137, v133, s5, -v137
	v_fmac_f32_e32 v137, 0x3377d1cf, v133
	v_fmac_f32_e32 v137, 0x3f317217, v133
	v_cmp_lt_f32_e64 s[0:1], |v133|, s6
	s_nop 1
	v_cndmask_b32_e64 v133, v133, v137, s[0:1]
	v_cndmask_b32_e32 v137, 0, v228, vcc
	v_sub_f32_e32 v145, v133, v137
	v_mul_f32_e64 v137, |v146|, s3
	v_exp_f32_e32 v137, v137
	v_max_f32_e32 v133, 0, v146
	v_pk_add_f32 v[142:143], v[142:143], v[144:145]
	v_add_f32_e32 v137, 1.0, v137
	v_cmp_gt_f32_e32 vcc, s2, v137
	s_nop 1
	v_cndmask_b32_e64 v146, 0, 32, vcc
	v_ldexp_f32 v137, v137, v146
	v_log_f32_e32 v137, v137
	s_nop 0
	v_mul_f32_e32 v146, 0x3f317217, v137
	v_fma_f32 v146, v137, s5, -v146
	v_fmac_f32_e32 v146, 0x3377d1cf, v137
	v_fmac_f32_e32 v146, 0x3f317217, v137
	v_cmp_lt_f32_e64 s[0:1], |v137|, s6
	s_nop 1
	v_cndmask_b32_e64 v137, v137, v146, s[0:1]
	v_cndmask_b32_e32 v146, 0, v228, vcc
	v_sub_f32_e32 v137, v137, v146
	v_add_f32_e32 v146, v98, v138
	v_mul_f32_e64 v134, |v146|, s3
	v_exp_f32_e32 v134, v134
	v_max_f32_e32 v138, 0, v146
	v_pk_add_f32 v[132:133], v[132:133], v[136:137]
	v_lshl_add_u64 v[136:137], v[190:191], 0, v[140:141]
	v_add_f32_e32 v134, 1.0, v134
	v_cmp_gt_f32_e32 vcc, s2, v134
	s_nop 1
	v_cndmask_b32_e64 v146, 0, 32, vcc
	v_ldexp_f32 v134, v134, v146
	v_log_f32_e32 v134, v134
	s_nop 0
	v_mul_f32_e32 v146, 0x3f317217, v134
	v_fma_f32 v146, v134, s5, -v146
	v_fmac_f32_e32 v146, 0x3377d1cf, v134
	v_fmac_f32_e32 v146, 0x3f317217, v134
	v_cmp_lt_f32_e64 s[0:1], |v134|, s6
	s_nop 1
	v_cndmask_b32_e64 v134, v134, v146, s[0:1]
	v_cndmask_b32_e32 v146, 0, v228, vcc
	v_sub_f32_e32 v146, v134, v146
	v_max_f32_e32 v134, 0, v147
	v_mul_f32_e64 v147, |v147|, s3
	v_exp_f32_e32 v147, v147
	s_nop 0
	v_add_f32_e32 v147, 1.0, v147
	v_cmp_gt_f32_e32 vcc, s2, v147
	s_nop 1
	v_cndmask_b32_e64 v148, 0, 32, vcc
	v_ldexp_f32 v147, v147, v148
	v_log_f32_e32 v147, v147
	s_nop 0
	v_mul_f32_e32 v148, 0x3f317217, v147
	v_fma_f32 v148, v147, s5, -v148
	v_fmac_f32_e32 v148, 0x3377d1cf, v147
	v_fmac_f32_e32 v148, 0x3f317217, v147
	v_cmp_lt_f32_e64 s[0:1], |v147|, s6
	s_nop 1
	v_cndmask_b32_e64 v147, v147, v148, s[0:1]
	v_cndmask_b32_e32 v148, 0, v228, vcc
	v_sub_f32_e32 v148, v147, v148
	v_add_f32_e32 v147, v99, v139
	v_mul_f32_e64 v135, |v147|, s3
	v_exp_f32_e32 v135, v135
	v_max_f32_e32 v139, 0, v147
	v_add_f32_e32 v135, 1.0, v135
	v_cmp_gt_f32_e32 vcc, s2, v135
	s_nop 1
	v_cndmask_b32_e64 v147, 0, 32, vcc
	v_ldexp_f32 v135, v135, v147
	v_log_f32_e32 v135, v135
	s_nop 0
	v_mul_f32_e32 v147, 0x3f317217, v135
	v_fma_f32 v147, v135, s5, -v147
	v_fmac_f32_e32 v147, 0x3377d1cf, v135
	v_fmac_f32_e32 v147, 0x3f317217, v135
	v_cmp_lt_f32_e64 s[0:1], |v135|, s6
	s_nop 1
	v_cndmask_b32_e64 v135, v135, v147, s[0:1]
	v_cndmask_b32_e32 v147, 0, v228, vcc
	v_sub_f32_e32 v147, v135, v147
	v_pk_add_f32 v[144:145], v[138:139], v[146:147]
	v_mul_f32_e64 v138, |v149|, s3
	v_exp_f32_e32 v138, v138
	v_max_f32_e32 v135, 0, v149
	v_add_f32_e32 v138, 1.0, v138
	v_cmp_gt_f32_e32 vcc, s2, v138
	s_nop 1
	v_cndmask_b32_e64 v139, 0, 32, vcc
	v_ldexp_f32 v138, v138, v139
	v_log_f32_e32 v138, v138
	s_nop 0
	v_mul_f32_e32 v139, 0x3f317217, v138
	v_fma_f32 v139, v138, s5, -v139
	v_fmac_f32_e32 v139, 0x3377d1cf, v138
	v_fmac_f32_e32 v139, 0x3f317217, v138
	v_cmp_lt_f32_e64 s[0:1], |v138|, s6
	s_nop 1
	v_cndmask_b32_e64 v138, v138, v139, s[0:1]
	v_cndmask_b32_e32 v139, 0, v228, vcc
	v_sub_f32_e32 v149, v138, v139
	v_pk_add_f32 v[134:135], v[134:135], v[148:149]
	global_store_dwordx4 v[136:137], v[142:145], off nt
	global_store_dwordx4 v[136:137], v[132:135], off offset:16 nt
	s_cbranch_execnz .LBB0_258
.LBB0_302:
	s_nop 0
	v_add_u32_e32 v134, s53, v224
	v_mov_b64_e32 v[132:133], s[96:97]
	v_mad_i64_i32 v[132:133], s[0:1], v134, s29, v[132:133]
	v_lshl_add_u64 v[132:133], s[62:63], 1, v[132:133]
	s_lshl_b32 s72, s49, 1
	v_lshl_add_u64 v[132:133], v[132:133], 0, s[72:73]
	v_lshl_add_u64 v[136:137], v[132:133], 0, v[2:3]
	v_cvt_pk_bf16_f32 v132, v96, v97
	v_cvt_pk_bf16_f32 v133, v98, v99
	v_cvt_pk_bf16_f32 v134, v92, v93
	v_cvt_pk_bf16_f32 v135, v94, v95
	global_store_dwordx4 v[136:137], v[132:135], off nt
	s_nop 1
	v_cvt_pk_bf16_f32 v132, v32, v33
	v_cvt_pk_bf16_f32 v133, v34, v35
	v_cvt_pk_bf16_f32 v134, v28, v29
	v_cvt_pk_bf16_f32 v135, v30, v31
	global_store_dwordx4 v[136:137], v[132:135], off offset:256 nt
	s_and_b64 vcc, exec, s[46:47]
	s_mov_b64 s[0:1], -1
	s_cbranch_vccnz .LBB0_259

.LBB0_305:
	v_add_u32_e32 v132, s53, v241
	v_ashrrev_i32_e32 v133, 31, v132
	v_lshlrev_b64 v[140:141], 7, v[132:133]
	global_load_dwordx4 v[132:135], v[188:189], off offset:16
	global_load_dwordx4 v[136:139], v[188:189], off
	s_mov_b32 s3, 0xbfb8aa3b
	s_mov_b32 s2, 0x800000
	s_mov_b32 s5, 0x3f317217
	s_mov_b32 s6, 0x7f800000
	s_waitcnt vmcnt(0)
	v_add_f32_e32 v143, v84, v132
	v_add_f32_e32 v136, v88, v136
	v_mul_f32_e64 v132, |v136|, s3
	v_exp_f32_e32 v132, v132
	v_max_f32_e32 v142, 0, v136
	v_add_f32_e32 v137, v89, v137
	v_add_f32_e32 v146, v85, v133
	v_add_f32_e32 v132, 1.0, v132
	v_cmp_gt_f32_e32 vcc, s2, v132
	v_mul_f32_e64 v133, |v137|, s3
	v_exp_f32_e32 v133, v133
	v_cndmask_b32_e64 v136, 0, 32, vcc
	v_ldexp_f32 v132, v132, v136
	v_log_f32_e32 v132, v132
	v_add_f32_e32 v133, 1.0, v133
	v_add_f32_e32 v147, v86, v134
	v_add_f32_e32 v149, v87, v135
	v_mul_f32_e32 v136, 0x3f317217, v132
	v_fma_f32 v136, v132, s5, -v136
	v_fmac_f32_e32 v136, 0x3377d1cf, v132
	v_fmac_f32_e32 v136, 0x3f317217, v132
	v_cmp_lt_f32_e64 s[0:1], |v132|, s6
	s_nop 1
	v_cndmask_b32_e64 v132, v132, v136, s[0:1]
	v_cndmask_b32_e32 v136, 0, v228, vcc
	v_sub_f32_e32 v144, v132, v136
	v_mul_f32_e64 v136, |v143|, s3
	v_exp_f32_e32 v136, v136
	v_max_f32_e32 v132, 0, v143
	v_add_f32_e32 v136, 1.0, v136
	v_cmp_gt_f32_e32 vcc, s2, v136
	s_nop 1
	v_cndmask_b32_e64 v143, 0, 32, vcc
	v_ldexp_f32 v136, v136, v143
	v_log_f32_e32 v136, v136
	s_nop 0
	v_mul_f32_e32 v143, 0x3f317217, v136
	v_fma_f32 v143, v136, s5, -v143
	v_fmac_f32_e32 v143, 0x3377d1cf, v136
	v_fmac_f32_e32 v143, 0x3f317217, v136
	v_cmp_lt_f32_e64 s[0:1], |v136|, s6
	s_nop 1
	v_cndmask_b32_e64 v136, v136, v143, s[0:1]
	v_cndmask_b32_e32 v143, 0, v228, vcc
	v_cmp_gt_f32_e32 vcc, s2, v133
	v_sub_f32_e32 v136, v136, v143
	v_max_f32_e32 v143, 0, v137
	v_cndmask_b32_e64 v137, 0, 32, vcc
	v_ldexp_f32 v133, v133, v137
	v_log_f32_e32 v133, v133
	s_nop 0
	v_mul_f32_e32 v137, 0x3f317217, v133
	v_fma_f32 v137, v133, s5, -v137
	v_fmac_f32_e32 v137, 0x3377d1cf, v133
	v_fmac_f32_e32 v137, 0x3f317217, v133
	v_cmp_lt_f32_e64 s[0:1], |v133|, s6
	s_nop 1
	v_cndmask_b32_e64 v133, v133, v137, s[0:1]
	v_cndmask_b32_e32 v137, 0, v228, vcc
	v_sub_f32_e32 v145, v133, v137
	v_mul_f32_e64 v137, |v146|, s3
	v_exp_f32_e32 v137, v137
	v_max_f32_e32 v133, 0, v146
	v_pk_add_f32 v[142:143], v[142:143], v[144:145]
	v_add_f32_e32 v137, 1.0, v137
	v_cmp_gt_f32_e32 vcc, s2, v137
	s_nop 1
	v_cndmask_b32_e64 v146, 0, 32, vcc
	v_ldexp_f32 v137, v137, v146
	v_log_f32_e32 v137, v137
	s_nop 0
	v_mul_f32_e32 v146, 0x3f317217, v137
	v_fma_f32 v146, v137, s5, -v146
	v_fmac_f32_e32 v146, 0x3377d1cf, v137
	v_fmac_f32_e32 v146, 0x3f317217, v137
	v_cmp_lt_f32_e64 s[0:1], |v137|, s6
	s_nop 1
	v_cndmask_b32_e64 v137, v137, v146, s[0:1]
	v_cndmask_b32_e32 v146, 0, v228, vcc
	v_sub_f32_e32 v137, v137, v146
	v_add_f32_e32 v146, v90, v138
	v_mul_f32_e64 v134, |v146|, s3
	v_exp_f32_e32 v134, v134
	v_max_f32_e32 v138, 0, v146
	v_pk_add_f32 v[132:133], v[132:133], v[136:137]
	v_lshl_add_u64 v[136:137], v[190:191], 0, v[140:141]
	v_add_f32_e32 v134, 1.0, v134
	v_cmp_gt_f32_e32 vcc, s2, v134
	s_nop 1
	v_cndmask_b32_e64 v146, 0, 32, vcc
	v_ldexp_f32 v134, v134, v146
	v_log_f32_e32 v134, v134
	s_nop 0
	v_mul_f32_e32 v146, 0x3f317217, v134
	v_fma_f32 v146, v134, s5, -v146
	v_fmac_f32_e32 v146, 0x3377d1cf, v134
	v_fmac_f32_e32 v146, 0x3f317217, v134
	v_cmp_lt_f32_e64 s[0:1], |v134|, s6
	s_nop 1
	v_cndmask_b32_e64 v134, v134, v146, s[0:1]
	v_cndmask_b32_e32 v146, 0, v228, vcc
	v_sub_f32_e32 v146, v134, v146
	v_max_f32_e32 v134, 0, v147
	v_mul_f32_e64 v147, |v147|, s3
	v_exp_f32_e32 v147, v147
	s_nop 0
	v_add_f32_e32 v147, 1.0, v147
	v_cmp_gt_f32_e32 vcc, s2, v147
	s_nop 1
	v_cndmask_b32_e64 v148, 0, 32, vcc
	v_ldexp_f32 v147, v147, v148
	v_log_f32_e32 v147, v147
	s_nop 0
	v_mul_f32_e32 v148, 0x3f317217, v147
	v_fma_f32 v148, v147, s5, -v148
	v_fmac_f32_e32 v148, 0x3377d1cf, v147
	v_fmac_f32_e32 v148, 0x3f317217, v147
	v_cmp_lt_f32_e64 s[0:1], |v147|, s6
	s_nop 1
	v_cndmask_b32_e64 v147, v147, v148, s[0:1]
	v_cndmask_b32_e32 v148, 0, v228, vcc
	v_sub_f32_e32 v148, v147, v148
	v_add_f32_e32 v147, v91, v139
	v_mul_f32_e64 v135, |v147|, s3
	v_exp_f32_e32 v135, v135
	v_max_f32_e32 v139, 0, v147
	v_add_f32_e32 v135, 1.0, v135
	v_cmp_gt_f32_e32 vcc, s2, v135
	s_nop 1
	v_cndmask_b32_e64 v147, 0, 32, vcc
	v_ldexp_f32 v135, v135, v147
	v_log_f32_e32 v135, v135
	s_nop 0
	v_mul_f32_e32 v147, 0x3f317217, v135
	v_fma_f32 v147, v135, s5, -v147
	v_fmac_f32_e32 v147, 0x3377d1cf, v135
	v_fmac_f32_e32 v147, 0x3f317217, v135
	v_cmp_lt_f32_e64 s[0:1], |v135|, s6
	s_nop 1
	v_cndmask_b32_e64 v135, v135, v147, s[0:1]
	v_cndmask_b32_e32 v147, 0, v228, vcc
	v_sub_f32_e32 v147, v135, v147
	v_pk_add_f32 v[144:145], v[138:139], v[146:147]
	v_mul_f32_e64 v138, |v149|, s3
	v_exp_f32_e32 v138, v138
	v_max_f32_e32 v135, 0, v149
	v_add_f32_e32 v138, 1.0, v138
	v_cmp_gt_f32_e32 vcc, s2, v138
	s_nop 1
	v_cndmask_b32_e64 v139, 0, 32, vcc
	v_ldexp_f32 v138, v138, v139
	v_log_f32_e32 v138, v138
	s_nop 0
	v_mul_f32_e32 v139, 0x3f317217, v138
	v_fma_f32 v139, v138, s5, -v139
	v_fmac_f32_e32 v139, 0x3377d1cf, v138
	v_fmac_f32_e32 v139, 0x3f317217, v138
	v_cmp_lt_f32_e64 s[0:1], |v138|, s6
	s_nop 1
	v_cndmask_b32_e64 v138, v138, v139, s[0:1]
	v_cndmask_b32_e32 v139, 0, v228, vcc
	v_sub_f32_e32 v149, v138, v139
	v_pk_add_f32 v[134:135], v[134:135], v[148:149]
	global_store_dwordx4 v[136:137], v[142:145], off nt
	global_store_dwordx4 v[136:137], v[132:135], off offset:16 nt
	s_cbranch_execnz .LBB0_260
.LBB0_306:
	s_nop 0
	v_add_u32_e32 v134, s53, v241
	v_mov_b64_e32 v[132:133], s[96:97]
	v_mad_i64_i32 v[132:133], s[0:1], v134, s29, v[132:133]
	v_lshl_add_u64 v[132:133], s[62:63], 1, v[132:133]
	s_lshl_b32 s72, s49, 1
	v_lshl_add_u64 v[132:133], v[132:133], 0, s[72:73]
	v_lshl_add_u64 v[136:137], v[132:133], 0, v[2:3]
	v_cvt_pk_bf16_f32 v132, v88, v89
	v_cvt_pk_bf16_f32 v133, v90, v91
	v_cvt_pk_bf16_f32 v134, v84, v85
	v_cvt_pk_bf16_f32 v135, v86, v87
	global_store_dwordx4 v[136:137], v[132:135], off nt
	s_nop 1
	v_cvt_pk_bf16_f32 v132, v24, v25
	v_cvt_pk_bf16_f32 v133, v26, v27
	v_cvt_pk_bf16_f32 v134, v20, v21
	v_cvt_pk_bf16_f32 v135, v22, v23
	global_store_dwordx4 v[136:137], v[132:135], off offset:256 nt
	s_and_b64 vcc, exec, s[46:47]
	s_mov_b64 s[0:1], -1
	s_cbranch_vccnz .LBB0_261

.LBB0_309:
	v_add_u32_e32 v132, s53, v238
	v_ashrrev_i32_e32 v133, 31, v132
	v_lshlrev_b64 v[140:141], 7, v[132:133]
	global_load_dwordx4 v[132:135], v[188:189], off offset:16
	global_load_dwordx4 v[136:139], v[188:189], off
	s_mov_b32 s3, 0xbfb8aa3b
	s_mov_b32 s2, 0x800000
	s_mov_b32 s5, 0x3f317217
	s_mov_b32 s6, 0x7f800000
	s_waitcnt vmcnt(0)
	v_add_f32_e32 v143, v76, v132
	v_add_f32_e32 v136, v80, v136
	v_mul_f32_e64 v132, |v136|, s3
	v_exp_f32_e32 v132, v132
	v_max_f32_e32 v142, 0, v136
	v_add_f32_e32 v137, v81, v137
	v_add_f32_e32 v146, v77, v133
	v_add_f32_e32 v132, 1.0, v132
	v_cmp_gt_f32_e32 vcc, s2, v132
	v_mul_f32_e64 v133, |v137|, s3
	v_exp_f32_e32 v133, v133
	v_cndmask_b32_e64 v136, 0, 32, vcc
	v_ldexp_f32 v132, v132, v136
	v_log_f32_e32 v132, v132
	v_add_f32_e32 v133, 1.0, v133
	v_add_f32_e32 v147, v78, v134
	v_add_f32_e32 v149, v79, v135
	v_mul_f32_e32 v136, 0x3f317217, v132
	v_fma_f32 v136, v132, s5, -v136
	v_fmac_f32_e32 v136, 0x3377d1cf, v132
	v_fmac_f32_e32 v136, 0x3f317217, v132
	v_cmp_lt_f32_e64 s[0:1], |v132|, s6
	s_nop 1
	v_cndmask_b32_e64 v132, v132, v136, s[0:1]
	v_cndmask_b32_e32 v136, 0, v228, vcc
	v_sub_f32_e32 v144, v132, v136
	v_mul_f32_e64 v136, |v143|, s3
	v_exp_f32_e32 v136, v136
	v_max_f32_e32 v132, 0, v143
	v_add_f32_e32 v136, 1.0, v136
	v_cmp_gt_f32_e32 vcc, s2, v136
	s_nop 1
	v_cndmask_b32_e64 v143, 0, 32, vcc
	v_ldexp_f32 v136, v136, v143
	v_log_f32_e32 v136, v136
	s_nop 0
	v_mul_f32_e32 v143, 0x3f317217, v136
	v_fma_f32 v143, v136, s5, -v143
	v_fmac_f32_e32 v143, 0x3377d1cf, v136
	v_fmac_f32_e32 v143, 0x3f317217, v136
	v_cmp_lt_f32_e64 s[0:1], |v136|, s6
	s_nop 1
	v_cndmask_b32_e64 v136, v136, v143, s[0:1]
	v_cndmask_b32_e32 v143, 0, v228, vcc
	v_cmp_gt_f32_e32 vcc, s2, v133
	v_sub_f32_e32 v136, v136, v143
	v_max_f32_e32 v143, 0, v137
	v_cndmask_b32_e64 v137, 0, 32, vcc
	v_ldexp_f32 v133, v133, v137
	v_log_f32_e32 v133, v133
	s_nop 0
	v_mul_f32_e32 v137, 0x3f317217, v133
	v_fma_f32 v137, v133, s5, -v137
	v_fmac_f32_e32 v137, 0x3377d1cf, v133
	v_fmac_f32_e32 v137, 0x3f317217, v133
	v_cmp_lt_f32_e64 s[0:1], |v133|, s6
	s_nop 1
	v_cndmask_b32_e64 v133, v133, v137, s[0:1]
	v_cndmask_b32_e32 v137, 0, v228, vcc
	v_sub_f32_e32 v145, v133, v137
	v_mul_f32_e64 v137, |v146|, s3
	v_exp_f32_e32 v137, v137
	v_max_f32_e32 v133, 0, v146
	v_pk_add_f32 v[142:143], v[142:143], v[144:145]
	v_add_f32_e32 v137, 1.0, v137
	v_cmp_gt_f32_e32 vcc, s2, v137
	s_nop 1
	v_cndmask_b32_e64 v146, 0, 32, vcc
	v_ldexp_f32 v137, v137, v146
	v_log_f32_e32 v137, v137
	s_nop 0
	v_mul_f32_e32 v146, 0x3f317217, v137
	v_fma_f32 v146, v137, s5, -v146
	v_fmac_f32_e32 v146, 0x3377d1cf, v137
	v_fmac_f32_e32 v146, 0x3f317217, v137
	v_cmp_lt_f32_e64 s[0:1], |v137|, s6
	s_nop 1
	v_cndmask_b32_e64 v137, v137, v146, s[0:1]
	v_cndmask_b32_e32 v146, 0, v228, vcc
	v_sub_f32_e32 v137, v137, v146
	v_add_f32_e32 v146, v82, v138
	v_mul_f32_e64 v134, |v146|, s3
	v_exp_f32_e32 v134, v134
	v_max_f32_e32 v138, 0, v146
	v_pk_add_f32 v[132:133], v[132:133], v[136:137]
	v_lshl_add_u64 v[136:137], v[190:191], 0, v[140:141]
	v_add_f32_e32 v134, 1.0, v134
	v_cmp_gt_f32_e32 vcc, s2, v134
	s_nop 1
	v_cndmask_b32_e64 v146, 0, 32, vcc
	v_ldexp_f32 v134, v134, v146
	v_log_f32_e32 v134, v134
	s_nop 0
	v_mul_f32_e32 v146, 0x3f317217, v134
	v_fma_f32 v146, v134, s5, -v146
	v_fmac_f32_e32 v146, 0x3377d1cf, v134
	v_fmac_f32_e32 v146, 0x3f317217, v134
	v_cmp_lt_f32_e64 s[0:1], |v134|, s6
	s_nop 1
	v_cndmask_b32_e64 v134, v134, v146, s[0:1]
	v_cndmask_b32_e32 v146, 0, v228, vcc
	v_sub_f32_e32 v146, v134, v146
	v_max_f32_e32 v134, 0, v147
	v_mul_f32_e64 v147, |v147|, s3
	v_exp_f32_e32 v147, v147
	s_nop 0
	v_add_f32_e32 v147, 1.0, v147
	v_cmp_gt_f32_e32 vcc, s2, v147
	s_nop 1
	v_cndmask_b32_e64 v148, 0, 32, vcc
	v_ldexp_f32 v147, v147, v148
	v_log_f32_e32 v147, v147
	s_nop 0
	v_mul_f32_e32 v148, 0x3f317217, v147
	v_fma_f32 v148, v147, s5, -v148
	v_fmac_f32_e32 v148, 0x3377d1cf, v147
	v_fmac_f32_e32 v148, 0x3f317217, v147
	v_cmp_lt_f32_e64 s[0:1], |v147|, s6
	s_nop 1
	v_cndmask_b32_e64 v147, v147, v148, s[0:1]
	v_cndmask_b32_e32 v148, 0, v228, vcc
	v_sub_f32_e32 v148, v147, v148
	v_add_f32_e32 v147, v83, v139
	v_mul_f32_e64 v135, |v147|, s3
	v_exp_f32_e32 v135, v135
	v_max_f32_e32 v139, 0, v147
	v_add_f32_e32 v135, 1.0, v135
	v_cmp_gt_f32_e32 vcc, s2, v135
	s_nop 1
	v_cndmask_b32_e64 v147, 0, 32, vcc
	v_ldexp_f32 v135, v135, v147
	v_log_f32_e32 v135, v135
	s_nop 0
	v_mul_f32_e32 v147, 0x3f317217, v135
	v_fma_f32 v147, v135, s5, -v147
	v_fmac_f32_e32 v147, 0x3377d1cf, v135
	v_fmac_f32_e32 v147, 0x3f317217, v135
	v_cmp_lt_f32_e64 s[0:1], |v135|, s6
	s_nop 1
	v_cndmask_b32_e64 v135, v135, v147, s[0:1]
	v_cndmask_b32_e32 v147, 0, v228, vcc
	v_sub_f32_e32 v147, v135, v147
	v_pk_add_f32 v[144:145], v[138:139], v[146:147]
	v_mul_f32_e64 v138, |v149|, s3
	v_exp_f32_e32 v138, v138
	v_max_f32_e32 v135, 0, v149
	v_add_f32_e32 v138, 1.0, v138
	v_cmp_gt_f32_e32 vcc, s2, v138
	s_nop 1
	v_cndmask_b32_e64 v139, 0, 32, vcc
	v_ldexp_f32 v138, v138, v139
	v_log_f32_e32 v138, v138
	s_nop 0
	v_mul_f32_e32 v139, 0x3f317217, v138
	v_fma_f32 v139, v138, s5, -v139
	v_fmac_f32_e32 v139, 0x3377d1cf, v138
	v_fmac_f32_e32 v139, 0x3f317217, v138
	v_cmp_lt_f32_e64 s[0:1], |v138|, s6
	s_nop 1
	v_cndmask_b32_e64 v138, v138, v139, s[0:1]
	v_cndmask_b32_e32 v139, 0, v228, vcc
	v_sub_f32_e32 v149, v138, v139
	v_pk_add_f32 v[134:135], v[134:135], v[148:149]
	global_store_dwordx4 v[136:137], v[142:145], off nt
	global_store_dwordx4 v[136:137], v[132:135], off offset:16 nt
	s_cbranch_execnz .LBB0_262
.LBB0_310:
	s_nop 0
	v_add_u32_e32 v134, s53, v238
	v_mov_b64_e32 v[132:133], s[96:97]
	v_mad_i64_i32 v[132:133], s[0:1], v134, s29, v[132:133]
	v_lshl_add_u64 v[132:133], s[62:63], 1, v[132:133]
	s_lshl_b32 s72, s49, 1
	v_lshl_add_u64 v[132:133], v[132:133], 0, s[72:73]
	v_lshl_add_u64 v[136:137], v[132:133], 0, v[2:3]
	v_cvt_pk_bf16_f32 v132, v80, v81
	v_cvt_pk_bf16_f32 v133, v82, v83
	v_cvt_pk_bf16_f32 v134, v76, v77
	v_cvt_pk_bf16_f32 v135, v78, v79
	global_store_dwordx4 v[136:137], v[132:135], off nt
	s_nop 1
	v_cvt_pk_bf16_f32 v132, v16, v17
	v_cvt_pk_bf16_f32 v133, v18, v19
	v_cvt_pk_bf16_f32 v134, v12, v13
	v_cvt_pk_bf16_f32 v135, v14, v15
	global_store_dwordx4 v[136:137], v[132:135], off offset:256 nt
	s_and_b64 vcc, exec, s[46:47]
	s_mov_b64 s[0:1], -1
	s_cbranch_vccnz .LBB0_263

.LBB0_313:
	v_add_u32_e32 v132, s53, v239
	v_ashrrev_i32_e32 v133, 31, v132
	v_lshlrev_b64 v[140:141], 7, v[132:133]
	global_load_dwordx4 v[132:135], v[188:189], off offset:16
	global_load_dwordx4 v[136:139], v[188:189], off
	s_mov_b32 s3, 0xbfb8aa3b
	s_mov_b32 s2, 0x800000
	s_mov_b32 s5, 0x3f317217
	s_mov_b32 s6, 0x7f800000
	s_waitcnt vmcnt(0)
	v_add_f32_e32 v143, v68, v132
	v_add_f32_e32 v136, v72, v136
	v_mul_f32_e64 v132, |v136|, s3
	v_exp_f32_e32 v132, v132
	v_max_f32_e32 v142, 0, v136
	v_add_f32_e32 v137, v73, v137
	v_add_f32_e32 v146, v69, v133
	v_add_f32_e32 v132, 1.0, v132
	v_cmp_gt_f32_e32 vcc, s2, v132
	v_mul_f32_e64 v133, |v137|, s3
	v_exp_f32_e32 v133, v133
	v_cndmask_b32_e64 v136, 0, 32, vcc
	v_ldexp_f32 v132, v132, v136
	v_log_f32_e32 v132, v132
	v_add_f32_e32 v133, 1.0, v133
	v_add_f32_e32 v147, v70, v134
	v_add_f32_e32 v149, v71, v135
	v_mul_f32_e32 v136, 0x3f317217, v132
	v_fma_f32 v136, v132, s5, -v136
	v_fmac_f32_e32 v136, 0x3377d1cf, v132
	v_fmac_f32_e32 v136, 0x3f317217, v132
	v_cmp_lt_f32_e64 s[0:1], |v132|, s6
	s_nop 1
	v_cndmask_b32_e64 v132, v132, v136, s[0:1]
	v_cndmask_b32_e32 v136, 0, v228, vcc
	v_sub_f32_e32 v144, v132, v136
	v_mul_f32_e64 v136, |v143|, s3
	v_exp_f32_e32 v136, v136
	v_max_f32_e32 v132, 0, v143
	v_add_f32_e32 v136, 1.0, v136
	v_cmp_gt_f32_e32 vcc, s2, v136
	s_nop 1
	v_cndmask_b32_e64 v143, 0, 32, vcc
	v_ldexp_f32 v136, v136, v143
	v_log_f32_e32 v136, v136
	s_nop 0
	v_mul_f32_e32 v143, 0x3f317217, v136
	v_fma_f32 v143, v136, s5, -v143
	v_fmac_f32_e32 v143, 0x3377d1cf, v136
	v_fmac_f32_e32 v143, 0x3f317217, v136
	v_cmp_lt_f32_e64 s[0:1], |v136|, s6
	s_nop 1
	v_cndmask_b32_e64 v136, v136, v143, s[0:1]
	v_cndmask_b32_e32 v143, 0, v228, vcc
	v_cmp_gt_f32_e32 vcc, s2, v133
	v_sub_f32_e32 v136, v136, v143
	v_max_f32_e32 v143, 0, v137
	v_cndmask_b32_e64 v137, 0, 32, vcc
	v_ldexp_f32 v133, v133, v137
	v_log_f32_e32 v133, v133
	s_nop 0
	v_mul_f32_e32 v137, 0x3f317217, v133
	v_fma_f32 v137, v133, s5, -v137
	v_fmac_f32_e32 v137, 0x3377d1cf, v133
	v_fmac_f32_e32 v137, 0x3f317217, v133
	v_cmp_lt_f32_e64 s[0:1], |v133|, s6
	s_nop 1
	v_cndmask_b32_e64 v133, v133, v137, s[0:1]
	v_cndmask_b32_e32 v137, 0, v228, vcc
	v_sub_f32_e32 v145, v133, v137
	v_mul_f32_e64 v137, |v146|, s3
	v_exp_f32_e32 v137, v137
	v_max_f32_e32 v133, 0, v146
	v_pk_add_f32 v[142:143], v[142:143], v[144:145]
	v_add_f32_e32 v137, 1.0, v137
	v_cmp_gt_f32_e32 vcc, s2, v137
	s_nop 1
	v_cndmask_b32_e64 v146, 0, 32, vcc
	v_ldexp_f32 v137, v137, v146
	v_log_f32_e32 v137, v137
	s_nop 0
	v_mul_f32_e32 v146, 0x3f317217, v137
	v_fma_f32 v146, v137, s5, -v146
	v_fmac_f32_e32 v146, 0x3377d1cf, v137
	v_fmac_f32_e32 v146, 0x3f317217, v137
	v_cmp_lt_f32_e64 s[0:1], |v137|, s6
	s_nop 1
	v_cndmask_b32_e64 v137, v137, v146, s[0:1]
	v_cndmask_b32_e32 v146, 0, v228, vcc
	v_sub_f32_e32 v137, v137, v146
	v_add_f32_e32 v146, v74, v138
	v_mul_f32_e64 v134, |v146|, s3
	v_exp_f32_e32 v134, v134
	v_max_f32_e32 v138, 0, v146
	v_pk_add_f32 v[132:133], v[132:133], v[136:137]
	v_lshl_add_u64 v[136:137], v[190:191], 0, v[140:141]
	v_add_f32_e32 v134, 1.0, v134
	v_cmp_gt_f32_e32 vcc, s2, v134
	s_nop 1
	v_cndmask_b32_e64 v146, 0, 32, vcc
	v_ldexp_f32 v134, v134, v146
	v_log_f32_e32 v134, v134
	s_nop 0
	v_mul_f32_e32 v146, 0x3f317217, v134
	v_fma_f32 v146, v134, s5, -v146
	v_fmac_f32_e32 v146, 0x3377d1cf, v134
	v_fmac_f32_e32 v146, 0x3f317217, v134
	v_cmp_lt_f32_e64 s[0:1], |v134|, s6
	s_nop 1
	v_cndmask_b32_e64 v134, v134, v146, s[0:1]
	v_cndmask_b32_e32 v146, 0, v228, vcc
	v_sub_f32_e32 v146, v134, v146
	v_max_f32_e32 v134, 0, v147
	v_mul_f32_e64 v147, |v147|, s3
	v_exp_f32_e32 v147, v147
	s_nop 0
	v_add_f32_e32 v147, 1.0, v147
	v_cmp_gt_f32_e32 vcc, s2, v147
	s_nop 1
	v_cndmask_b32_e64 v148, 0, 32, vcc
	v_ldexp_f32 v147, v147, v148
	v_log_f32_e32 v147, v147
	s_nop 0
	v_mul_f32_e32 v148, 0x3f317217, v147
	v_fma_f32 v148, v147, s5, -v148
	v_fmac_f32_e32 v148, 0x3377d1cf, v147
	v_fmac_f32_e32 v148, 0x3f317217, v147
	v_cmp_lt_f32_e64 s[0:1], |v147|, s6
	s_nop 1
	v_cndmask_b32_e64 v147, v147, v148, s[0:1]
	v_cndmask_b32_e32 v148, 0, v228, vcc
	v_sub_f32_e32 v148, v147, v148
	v_add_f32_e32 v147, v75, v139
	v_mul_f32_e64 v135, |v147|, s3
	v_exp_f32_e32 v135, v135
	v_max_f32_e32 v139, 0, v147
	v_add_f32_e32 v135, 1.0, v135
	v_cmp_gt_f32_e32 vcc, s2, v135
	s_nop 1
	v_cndmask_b32_e64 v147, 0, 32, vcc
	v_ldexp_f32 v135, v135, v147
	v_log_f32_e32 v135, v135
	s_nop 0
	v_mul_f32_e32 v147, 0x3f317217, v135
	v_fma_f32 v147, v135, s5, -v147
	v_fmac_f32_e32 v147, 0x3377d1cf, v135
	v_fmac_f32_e32 v147, 0x3f317217, v135
	v_cmp_lt_f32_e64 s[0:1], |v135|, s6
	s_nop 1
	v_cndmask_b32_e64 v135, v135, v147, s[0:1]
	v_cndmask_b32_e32 v147, 0, v228, vcc
	v_sub_f32_e32 v147, v135, v147
	v_pk_add_f32 v[144:145], v[138:139], v[146:147]
	v_mul_f32_e64 v138, |v149|, s3
	v_exp_f32_e32 v138, v138
	v_max_f32_e32 v135, 0, v149
	v_add_f32_e32 v138, 1.0, v138
	v_cmp_gt_f32_e32 vcc, s2, v138
	s_nop 1
	v_cndmask_b32_e64 v139, 0, 32, vcc
	v_ldexp_f32 v138, v138, v139
	v_log_f32_e32 v138, v138
	s_nop 0
	v_mul_f32_e32 v139, 0x3f317217, v138
	v_fma_f32 v139, v138, s5, -v139
	v_fmac_f32_e32 v139, 0x3377d1cf, v138
	v_fmac_f32_e32 v139, 0x3f317217, v138
	v_cmp_lt_f32_e64 s[0:1], |v138|, s6
	s_nop 1
	v_cndmask_b32_e64 v138, v138, v139, s[0:1]
	v_cndmask_b32_e32 v139, 0, v228, vcc
	v_sub_f32_e32 v149, v138, v139
	v_pk_add_f32 v[134:135], v[134:135], v[148:149]
	global_store_dwordx4 v[136:137], v[142:145], off nt
	global_store_dwordx4 v[136:137], v[132:135], off offset:16 nt
	s_cbranch_execz .LBB0_264
	s_branch .LBB0_265
